# mixer phase: workgroup classes start at different queues and visit them cyclically (7/12/19 split)
# baseline (speedup 1.0000x reference)
; #define LAS __attribute__((address_space(3)))
; __device__ __forceinline__ ArgsP launder(ArgsP p) { asm volatile("" : "+s"(p)); return p; }
; __device__ __forceinline__ unsigned xb_add(unsigned* p, unsigned v) { return __hip_atomic_fetch_add(p, v, __ATOMIC_RELAXED, __HIP_MEMORY_SCOPE_AGENT); }
; __device__ __forceinline__ unsigned xb_xcc_id() { return (unsigned)__builtin_amdgcn_s_getreg((3 << 11) | 20) & 0xFu; }
; __device__ __forceinline__ XcdBarrier xcd_barrier_post(unsigned* bar, volatile LAS unsigned* st) {
;     XcdBarrier b; b.bar = bar; b.x = xb_xcc_id(); b.st = st;
;     if (threadIdx.x == 0) (void)xb_add(&bar[XB_XCNT(b.x)], 1u);
;     return b;
; }
; template <int PHM, int MIXM>
; __global__ void __launch_bounds__(512, 2) mega(Args Aval) {
;     const ArgsP kp = (ArgsP)__builtin_amdgcn_kernarg_segment_ptr();
;     ArgsP A = launder(kp);
;     extern __shared__ __attribute__((aligned(16))) unsigned char lds[];
;     LAS unsigned char* ldsl = (LAS unsigned char*)lds;
;     const int G = gridDim.x, bx = blockIdx.x;
;     ...
;     unsigned char* ws = A->ws;
;     float* XF = A->out; bf16_t* XB = (bf16_t*)(ws + WS_XB);
;     const int lo = A->ph_lo, hi = A->ph_hi;
;     cg::grid_group grid = cg::this_grid();
;     __shared__ int s_item;
;     __shared__ unsigned s_bar[2];
;     if (threadIdx.x < 2) s_bar[threadIdx.x] = 0u;
;     __syncthreads();
;     XcdBarrier xbar; xbar.bar = (unsigned*)(ws + WS_CTL) + 2048; xbar.x = 0; xbar.st = nullptr;
;     if (hi - lo > 1) xbar = xcd_barrier_post((unsigned*)(ws + WS_CTL) + 2048, (volatile LAS unsigned*)s_bar);
_Z4megaILi65535ELi15EEv4Args:
	s_mov_b64 s[18:19], s[0:1]
	s_mov_b32 s74, s2
	v_writelane_b32 v255, s2, 41
	s_load_dwordx2 s[76:77], s[0:1], 0x158
	s_load_dwordx4 s[28:31], s[18:19], 0x140
	s_load_dwordx2 s[2:3], s[18:19], 0x150
	s_add_u32 s4, s0, 0x158
	v_and_b32_e32 v238, 0x3ff, v0
	v_cmp_gt_u32_e32 vcc, 2, v238
	s_waitcnt lgkmcnt(0)
	v_writelane_b32 v252, s2, 0
	s_nop 1
	v_writelane_b32 v252, s3, 1
	v_writelane_b32 v252, s0, 2
	s_addc_u32 s5, s1, 0
	s_nop 0
	v_writelane_b32 v252, s1, 3
	s_and_saveexec_b64 s[0:1], vcc
	v_lshlrev_b32_e32 v1, 2, v238
	v_mov_b32_e32 v2, 0
	ds_write_b32 v1, v2
	s_or_b64 exec, exec, s[0:1]
	v_readlane_b32 s0, v252, 2
	v_readlane_b32 s1, v252, 3
	s_load_dword s33, s[0:1], 0x160
	s_waitcnt lgkmcnt(0)
	s_barrier
	s_load_dwordx2 s[2:3], s[18:19], 0x150
	s_add_u32 s0, s30, 0x2000
	s_addc_u32 s1, s31, 0
	v_cmp_eq_u32_e32 vcc, 0, v238
	s_waitcnt lgkmcnt(0)
	s_sub_i32 s2, s3, s2
	s_mov_b32 s3, 0
	v_writelane_b32 v252, s3, 4
	s_cmp_lt_i32 s2, 2
	s_cbranch_scc1 .LBB0_7
	s_getreg_b32 s2, hwreg(HW_REG_XCC_ID, 0, 4)
	s_and_b32 s68, s2, 15
	s_and_saveexec_b64 s[2:3], vcc
	s_cbranch_execz .LBB0_6
	s_mov_b64 s[6:7], exec
	v_mbcnt_lo_u32_b32 v1, s6, 0
	v_mbcnt_hi_u32_b32 v1, s7, v1
	v_cmp_eq_u32_e32 vcc, 0, v1
	s_and_b64 s[8:9], exec, vcc
	s_mov_b64 exec, s[8:9]
	s_cbranch_execz .LBB0_6
	s_lshl_b32 s8, s68, 8
	s_bcnt1_i32_b64 s6, s[6:7]
	v_mov_b32_e32 v1, s8
	v_mov_b32_e32 v2, s6
	global_atomic_add v1, v2, s[0:1] offset:1024

; #define FRESH() int tid = threadIdx.x; asm volatile("" : "+v"(tid)); const int lane = tid & 63, wave = __builtin_amdgcn_readfirstlane(tid >> 6), gw = bx * 8 + wave, ngw = G * 8; (void)lane; (void)gw; (void)ngw
; #define QLOOP2(qi_, r2_, n_, ...) for (;;) { if (tid == 0) s_item = (int)atomicAdd(ctr + 64 * (qi_) + 32 * (r2_), 1u); __syncthreads(); const int item = s_item; __syncthreads(); if (item >= (n_)) break; __VA_ARGS__ }
; template <int PHM, int MIXM>
; __global__ void __launch_bounds__(512, 2) mega(Args Aval) {
;     ...
;         if ((PHM & 128) && IN(pb + 6)) {
;             FRESH();
;           for (int rep = 0; rep < ((PROBE_DUP & 1) ? 2 : 1); ++rep) {
;             unsigned* ctr = (unsigned*)(ws + WS_CTL) + 256 * l + 16 * rep;
;     ...
;             for (int r2 = 0; r2 < ((PROBE_DUP & 16) ? 2 : 1); ++r2) if (MIXM & 1) QLOOP2(0, r2, 256, { const int L = 15 - (item >> 4), r = item & 15; flash_unit<0>(A, l, r >> 2, r & 3, L, lds); })
;             for (int r2 = 0; r2 < ((PROBE_DUP & 32) ? 2 : 1); ++r2) if (MIXM & 2) QLOOP2(1, r2, 256, { const int L = 15 - (item >> 4), r = item & 15; flash_unit<2>(A, l, r >> 2, r & 3, L, lds); })
;             for (int r2 = 0; r2 < ((PROBE_DUP & 64) ? 2 : 1); ++r2) if (MIXM & 8) QLOOP2(2, r2, 256, { s5_unit(A, l, item, lds, wave, lane); })
;             for (int r2 = 0; r2 < ((PROBE_DUP & 128) ? 2 : 1); ++r2) if (MIXM & 4) QLOOP2(3, r2, 512, { const int L = 31 - (item >> 4), r = item & 15; flash_unit<1>(A, l, r >> 2, r & 3, L, lds); })
.LBB0_727:
	s_andn2_b64 vcc, exec, s[2:3]
	s_cbranch_vccnz .LBB0_884
	s_lshl_b32 s18, s92, 8
	v_readlane_b32 s4, v252, 5
	s_lshl_b64 s[2:3], s[18:19], 2
	v_readlane_b32 s6, v252, 7
	v_readlane_b32 s7, v252, 8
	s_add_u32 s2, s6, s2
	s_addc_u32 s3, s7, s3
	v_writelane_b32 v255, s2, 25
	v_mov_b32_e32 v0, v238
	v_readlane_b32 s5, v252, 6
	v_writelane_b32 v255, s3, 26
	s_mov_b32 s2, s92
	v_writelane_b32 v255, s2, 27
	v_cmp_eq_u32_e64 s[30:31], 0, v0
	s_nop 0
	v_writelane_b32 v255, s3, 28
	v_writelane_b32 v255, s26, 29
	s_nop 1
	v_writelane_b32 v255, s27, 30
	v_writelane_b32 v255, s30, 31
	s_nop 1
	v_writelane_b32 v255, s31, 32
	v_readlane_b32 s100, v255, 41
	s_mov_b32 s101, 4
	s_lshr_b32 s100, s100, 3
	s_cmp_lt_u32 s100, 7
	s_cbranch_scc1 .LBB0_731
	s_cmp_lt_u32 s100, 12
	s_cbranch_scc1 .LBB0_761
	s_cmp_lt_u32 s100, 19
	s_cbranch_scc1 .LBB0_784
	s_branch .LBB0_794
.Lq_x_mla:
	s_sub_u32 s101, s101, 1
	s_cmp_eq_u32 s101, 0
	s_cbranch_scc1 .LBB0_834
	s_branch .LBB0_761

; #define S5_LDS_FENCE() do { __builtin_amdgcn_wave_barrier(); asm volatile("s_waitcnt lgkmcnt(0)" ::: "memory"); } while (0)
; template <bool WRITEH>
; __device__ __forceinline__ void s5_block(const S5Coef& C, const bf16x8 (&bm)[8], u32x4 uw, float* Hs, int lane, float& hr, float& hi) {
;     const bf16x8 ua = __builtin_bit_cast(bf16x8, uw);
; #pragma unroll
;     for (int nb = 0; nb < 8; ++nb) { const f32x4 d = __builtin_amdgcn_mfma_f32_16x16x32_bf16(ua, bm[nb], (f32x4){0.f, 0.f, 0.f, 0.f}, 0, 0, 0);
; #pragma unroll
;         for (int i = 0; i < 4; ++i) Hs[(4 * (lane >> 4) + i) * 132 + 16 * nb + (lane & 15)] = d[i]; }
;     S5_LDS_FENCE();
; __device__ __forceinline__ void s5_unit(ArgsP A, int l, int unit, unsigned char* lds, int wave_, int lane_) {
;     ...
;     for (int gi = 0; gi < 4; ++gi) {
;         const int g = 4 * wave + gi;
;         S5Coef C; bf16x8 bm[8]; s5_fetch(A, l, g, lane, C, bm);
;         bf16x8 chl[8];
;         { const bf16x8* ct = (const bf16x8*)(A->ws + WS_S5T + (size_t)(l * 32 + g) * S5T_BYTES + 9216);
; #pragma unroll
;           for (int q = 0; q < 8; ++q) chl[q] = ct[q * 64 + lane]; }
;         const f32x2_t hin = ((const f32x2_t*)(A->ws + WS_S5H))[(size_t)((b * 64 + c) * 32 + g) * 64 + lane]; float hr = hin.x, hi = hin.y;
;         u32x4 uw[4];
; #pragma unroll
;         for (int blk = 0; blk < 4; ++blk) uw[blk] = s5_load_ua(PROJ, rowbase + 16 * blk, g, lane);
;         const float dv = A->in[20][l * 512 + 16 * g + (lane & 15)];
; #pragma unroll
;         for (int blk = 0; blk < 4; ++blk) {
;             unsigned short uraw[4];
; #pragma unroll
;             for (int i = 0; i < 4; ++i) uraw[i] = PROJ[(size_t)(rowbase + 16 * blk + 4 * (lane >> 4) + i) * INWP + C_S5 + 16 * g + (lane & 15)];
;             s5_block<true>(C, bm, uw[blk], Hs, lane, hr, hi);
.LBB0_792:
	s_waitcnt lgkmcnt(0)
	v_lshl_add_u64 v[4:5], s[2:3], 0, v[98:99]
	v_add_co_u32_e32 v0, vcc, 0x2e7b0000, v4
	v_lshl_add_u64 v[66:67], s[2:3], 0, v[96:97]
	s_nop 0
	v_addc_co_u32_e32 v1, vcc, 0, v5, vcc
	global_load_dwordx4 v[32:35], v[0:1], off
	global_load_dwordx4 v[62:65], v[0:1], off offset:1024
	global_load_dwordx4 v[58:61], v[0:1], off offset:2048
	global_load_dwordx4 v[54:57], v[0:1], off offset:3072
	v_add_co_u32_e32 v0, vcc, 0x2e7b1000, v4
	v_ashrrev_i32_e32 v79, 31, v78
	s_nop 0
	v_addc_co_u32_e32 v1, vcc, 0, v5, vcc
	global_load_dwordx4 v[50:53], v[0:1], off
	global_load_dwordx4 v[46:49], v[0:1], off offset:1024
	global_load_dwordx4 v[42:45], v[0:1], off offset:2048
	global_load_dwordx4 v[38:41], v[0:1], off offset:3072
	v_add_co_u32_e32 v0, vcc, 0x2e7b2000, v4
	v_add_u32_e32 v115, 32, v112
	s_nop 0
	v_addc_co_u32_e32 v1, vcc, 0, v5, vcc
	global_load_dwordx4 v[34:37], v[0:1], off
	global_load_dwordx4 v[24:27], v[0:1], off offset:1024
	global_load_dwordx4 v[28:31], v[0:1], off offset:2048
	global_load_dwordx4 v[16:19], v[0:1], off offset:3072
	v_add_co_u32_e32 v0, vcc, 0x2e7b3000, v4
	v_add_u32_e32 v126, 0xd0, v112
	s_nop 0
	v_addc_co_u32_e32 v1, vcc, 0, v5, vcc
	v_add_co_u32_e32 v4, vcc, 0x2e7b4000, v4
	global_load_dwordx4 v[20:23], v[0:1], off
	global_load_dwordx4 v[8:11], v[0:1], off offset:1024
	global_load_dwordx4 v[12:15], v[0:1], off offset:2048
	s_nop 0
	global_load_dwordx4 v[0:3], v[0:1], off offset:3072
	v_addc_co_u32_e32 v5, vcc, 0, v5, vcc
	global_load_dwordx4 v[4:7], v[4:5], off
	s_load_dwordx2 s[6:7], s[26:27], 0xa0
	global_load_dwordx2 v[100:101], v[66:67], off
	v_lshl_add_u64 v[66:67], s[2:3], 0, v[94:95]
	global_load_dwordx4 v[116:119], v[66:67], off
	v_lshl_add_u64 v[66:67], s[2:3], 0, v[92:93]
	s_waitcnt lgkmcnt(0)
	v_lshl_add_u64 v[102:103], v[78:79], 2, s[6:7]
	global_load_dword v79, v[102:103], off
	v_lshl_add_u64 v[102:103], s[2:3], 0, v[86:87]
	v_add_co_u32_e32 v124, vcc, s12, v102
	global_load_dwordx4 v[74:77], v[66:67], off
	s_nop 0
	v_addc_co_u32_e32 v125, vcc, 0, v103, vcc
	global_load_ushort v162, v[124:125], off
	v_add_co_u32_e32 v124, vcc, s13, v102
	v_lshl_add_u64 v[66:67], s[2:3], 0, v[90:91]
	s_nop 0
	v_addc_co_u32_e32 v125, vcc, 0, v103, vcc
	global_load_ushort v131, v[124:125], off offset:512
	v_add_co_u32_e32 v124, vcc, s33, v102
	global_load_dwordx4 v[70:73], v[66:67], off
	s_nop 0
	v_addc_co_u32_e32 v125, vcc, 0, v103, vcc
	v_add_co_u32_e32 v102, vcc, s28, v102
	v_lshl_add_u64 v[66:67], s[2:3], 0, v[88:89]
	s_nop 0
	v_addc_co_u32_e32 v103, vcc, 0, v103, vcc
	global_load_dwordx4 v[66:69], v[66:67], off
	v_add_u32_e32 v127, 0xe0, v112
	global_load_ushort v130, v[124:125], off offset:1024
	global_load_ushort v129, v[102:103], off offset:1536
	v_add_u32_e32 v124, 0xb0, v112
	v_add_u32_e32 v125, 0xc0, v112
	v_add_u32_e32 v128, 0xf0, v112
	s_mov_b64 s[6:7], 0x4400
	v_add_u32_e32 v78, 16, v78
	v_lshl_add_u64 v[86:87], v[86:87], 0, 32
	v_lshl_add_u64 v[88:89], v[88:89], 0, 32
	v_lshl_add_u64 v[90:91], v[90:91], 0, 32
	v_lshl_add_u64 v[92:93], v[92:93], 0, 32
	v_lshl_add_u64 v[94:95], v[94:95], 0, 32
	v_lshl_add_u64 v[96:97], v[96:97], 0, s[14:15]
	v_lshl_add_u64 v[98:99], v[98:99], 0, s[6:7]
	s_waitcnt vmcnt(8)
	v_mfma_f32_16x16x32_bf16 v[120:123], v[116:119], v[62:65], 0
	s_nop 7
	ds_write_b32 v106, v120
	ds_write_b32 v106, v121 offset:528
	ds_write_b32 v106, v122 offset:1056
	ds_write_b32 v107, v123
	v_mfma_f32_16x16x32_bf16 v[120:123], v[116:119], v[58:61], 0
	s_nop 7
	ds_write_b32 v106, v120 offset:64
	ds_write_b32 v106, v121 offset:592
	ds_write_b32 v106, v122 offset:1120
	ds_write_b32 v107, v123 offset:64
	v_mfma_f32_16x16x32_bf16 v[120:123], v[116:119], v[54:57], 0
	s_nop 7
	ds_write_b32 v106, v120 offset:128
	ds_write_b32 v106, v121 offset:656
	ds_write_b32 v106, v122 offset:1184
	ds_write_b32 v107, v123 offset:128
	v_mfma_f32_16x16x32_bf16 v[120:123], v[116:119], v[50:53], 0
	s_nop 7
	ds_write2_b32 v108, v120, v121 offset1:132
	ds_write_b32 v108, v122 offset:1056
	ds_write_b32 v109, v123
	v_mfma_f32_16x16x32_bf16 v[120:123], v[116:119], v[46:49], 0
	s_nop 7
	ds_write_b32 v106, v120 offset:256
	ds_write_b32 v106, v121 offset:784
	ds_write_b32 v106, v122 offset:1312
	ds_write_b32 v107, v123 offset:256
	v_mfma_f32_16x16x32_bf16 v[120:123], v[116:119], v[42:45], 0
	s_nop 7
	ds_write_b32 v106, v120 offset:320
	ds_write_b32 v106, v121 offset:848
	ds_write_b32 v106, v122 offset:1376
	ds_write_b32 v107, v123 offset:320
	v_mfma_f32_16x16x32_bf16 v[120:123], v[116:119], v[38:41], 0
	s_nop 7
	ds_write_b32 v106, v120 offset:384
	ds_write_b32 v106, v121 offset:912
	ds_write_b32 v106, v122 offset:1440
	ds_write_b32 v107, v123 offset:384
	v_mfma_f32_16x16x32_bf16 v[116:119], v[116:119], v[34:37], 0
	s_nop 7
	ds_write2_b32 v110, v116, v117 offset1:132
	ds_write_b32 v110, v118 offset:1056
	ds_write_b32 v111, v119
	s_waitcnt lgkmcnt(0)
	ds_read2st64_b32 v[102:103], v112 offset1:1
	ds_read2_b32 v[132:133], v112 offset0:132 offset1:196
	v_mul_f32_e32 v163, v33, v101
	v_mul_f32_e32 v101, v32, v101
	v_fmac_f32_e32 v101, v33, v100
	v_fma_f32 v163, v32, v100, -v163
	s_waitcnt lgkmcnt(1)
	v_add_f32_e32 v100, v101, v103
	ds_read2st64_b32 v[134:135], v115 offset0:4 offset1:5
	v_add_f32_e32 v102, v163, v102
	v_mul_f32_e32 v103, v32, v100
	v_mul_f32_e32 v101, v33, v100
	v_fmac_f32_e32 v103, v33, v102
	v_fma_f32 v101, v32, v102, -v101
	s_waitcnt lgkmcnt(1)
	v_add_f32_e32 v103, v133, v103
	v_add_f32_e32 v101, v132, v101
	v_mul_f32_e32 v132, v33, v103
	v_add_u32_e32 v116, 48, v112
	v_fma_f32 v132, v32, v101, -v132
	ds_read2st64_b32 v[136:137], v116 offset0:6 offset1:7
	s_waitcnt lgkmcnt(1)
; __device__ __forceinline__ unsigned cvt_pk(float lo, float hi) { f32x2_t v = {lo, hi}; bf16x2_t b = __builtin_convertvector(v, bf16x2_t); return __builtin_bit_cast(unsigned, b); }
; __device__ __forceinline__ float bflo(unsigned w) { return __uint_as_float(w << 16); }
; __device__ __forceinline__ float bfhi(unsigned w) { return __uint_as_float(w & 0xffff0000u); }
; #define S5_LDS_FENCE() do { __builtin_amdgcn_wave_barrier(); asm volatile("s_waitcnt lgkmcnt(0)" ::: "memory"); } while (0)
; template <bool WRITEH>
; __device__ __forceinline__ void s5_block(const S5Coef& C, const bf16x8 (&bm)[8], u32x4 uw, float* Hs, int lane, float& hr, float& hi) {
;     ...
;     for (int tl = 0; tl < 16; ++tl) { bur[tl] = Hs[tl * 132 + lane]; bui[tl] = Hs[tl * 132 + 64 + lane]; }
; #pragma unroll
;     for (int tl = 0; tl < 16; ++tl) { const float nr = C.ar * hr - C.ai * hi + bur[tl], ni = C.ar * hi + C.ai * hr + bui[tl]; hr = nr; hi = ni; bur[tl] = hr; bui[tl] = hi; }
;     if (WRITEH) {
; #pragma unroll
;         for (int tl = 0; tl < 16; ++tl) { Hs[tl * 132 + lane] = bur[tl]; Hs[tl * 132 + 64 + lane] = bui[tl]; }
;     }
;     S5_LDS_FENCE();
; }
; __device__ __forceinline__ void s5_unit(ArgsP A, int l, int unit, unsigned char* lds, int wave_, int lane_) {
;     ...
;             for (int ks = 0; ks < 4; ++ks) { const float* hp = Hs + (lane & 15) * 132 + 32 * ks + 8 * (lane >> 4); const f32x4 h0 = *(const f32x4*)hp, h1 = *(const f32x4*)(hp + 4);
;                 u32x4 wh; wh.x = cvt_pk(h0[0], h0[1]); wh.y = cvt_pk(h0[2], h0[3]); wh.z = cvt_pk(h1[0], h1[1]); wh.w = cvt_pk(h1[2], h1[3]);
;                 u32x4 wl; wl.x = cvt_pk(h0[0] - bflo(wh.x), h0[1] - bfhi(wh.x)); wl.y = cvt_pk(h0[2] - bflo(wh.y), h0[3] - bfhi(wh.y)); wl.z = cvt_pk(h1[0] - bflo(wh.z), h1[1] - bfhi(wh.z)); wl.w = cvt_pk(h1[2] - bflo(wh.w), h1[3] - bfhi(wh.w));
;                 const bf16x8 hh_ = __builtin_bit_cast(bf16x8, wh), hl_ = __builtin_bit_cast(bf16x8, wl);
;                 y = __builtin_amdgcn_mfma_f32_16x16x32_bf16(hh_, chl[2 * ks], y, 0, 0, 0); y2 = __builtin_amdgcn_mfma_f32_16x16x32_bf16(hh_, chl[2 * ks + 1], y2, 0, 0, 0);
;                 y2 = __builtin_amdgcn_mfma_f32_16x16x32_bf16(hl_, chl[2 * ks], y2, 0, 0, 0); }
	v_add_f32_e32 v134, v134, v132
	v_mul_f32_e32 v132, v32, v103
	v_fmac_f32_e32 v132, v33, v101
	v_add_f32_e32 v135, v135, v132
	v_mul_f32_e32 v132, v33, v135
	v_add_u32_e32 v117, 64, v112
	v_fma_f32 v132, v32, v134, -v132
	ds_read2st64_b32 v[138:139], v117 offset0:8 offset1:9
	s_waitcnt lgkmcnt(1)
	v_add_f32_e32 v136, v136, v132
	v_mul_f32_e32 v132, v32, v135
	v_fmac_f32_e32 v132, v33, v134
	v_add_f32_e32 v137, v137, v132
	v_mul_f32_e32 v132, v33, v137
	v_add_u32_e32 v118, 0x50, v112
	v_fma_f32 v132, v32, v136, -v132
	ds_read2st64_b32 v[140:141], v118 offset0:10 offset1:11
	s_waitcnt lgkmcnt(1)
	v_add_f32_e32 v138, v138, v132
	v_mul_f32_e32 v132, v32, v137
	v_fmac_f32_e32 v132, v33, v136
	v_add_f32_e32 v139, v139, v132
	v_mul_f32_e32 v132, v33, v139
	v_add_u32_e32 v119, 0x60, v112
	v_fma_f32 v132, v32, v138, -v132
	ds_read2st64_b32 v[142:143], v119 offset0:12 offset1:13
	s_waitcnt lgkmcnt(1)
	v_add_f32_e32 v140, v140, v132
	v_mul_f32_e32 v132, v32, v139
	v_fmac_f32_e32 v132, v33, v138
	v_add_f32_e32 v141, v141, v132
	v_mul_f32_e32 v132, v33, v141
	v_add_u32_e32 v120, 0x70, v112
	v_fma_f32 v132, v32, v140, -v132
	ds_read2st64_b32 v[144:145], v120 offset0:14 offset1:15
	s_waitcnt lgkmcnt(1)
	v_add_f32_e32 v142, v142, v132
	v_mul_f32_e32 v132, v32, v141
	v_fmac_f32_e32 v132, v33, v140
	v_add_f32_e32 v143, v143, v132
	v_mul_f32_e32 v132, v33, v143
	v_add_u32_e32 v121, 0x80, v112
	v_fma_f32 v132, v32, v142, -v132
	ds_read2st64_b32 v[146:147], v121 offset0:16 offset1:17
	s_waitcnt lgkmcnt(1)
	v_add_f32_e32 v144, v144, v132
	v_mul_f32_e32 v132, v32, v143
	v_fmac_f32_e32 v132, v33, v142
	v_add_f32_e32 v145, v145, v132
	v_mul_f32_e32 v132, v33, v145
	v_add_u32_e32 v122, 0x90, v112
	v_fma_f32 v132, v32, v144, -v132
	ds_read2st64_b32 v[148:149], v122 offset0:18 offset1:19
	s_waitcnt lgkmcnt(1)
	v_add_f32_e32 v146, v146, v132
	v_mul_f32_e32 v132, v32, v145
	v_fmac_f32_e32 v132, v33, v144
	v_add_f32_e32 v147, v147, v132
	v_mul_f32_e32 v132, v33, v147
	v_add_u32_e32 v123, 0xa0, v112
	v_fma_f32 v132, v32, v146, -v132
	ds_read2st64_b32 v[150:151], v123 offset0:20 offset1:21
	s_waitcnt lgkmcnt(1)
	v_add_f32_e32 v148, v148, v132
	v_mul_f32_e32 v132, v32, v147
	v_fmac_f32_e32 v132, v33, v146
	v_add_f32_e32 v149, v149, v132
	v_mul_f32_e32 v132, v33, v149
	v_fma_f32 v132, v32, v148, -v132
	ds_read2st64_b32 v[152:153], v124 offset0:22 offset1:23
	s_waitcnt lgkmcnt(1)
	v_add_f32_e32 v150, v150, v132
	v_mul_f32_e32 v132, v32, v149
	v_fmac_f32_e32 v132, v33, v148
	v_add_f32_e32 v151, v151, v132
	v_mul_f32_e32 v132, v33, v151
	v_fma_f32 v132, v32, v150, -v132
	ds_read2st64_b32 v[154:155], v125 offset0:24 offset1:25
	s_waitcnt lgkmcnt(1)
	v_add_f32_e32 v152, v152, v132
	v_mul_f32_e32 v132, v32, v151
	v_fmac_f32_e32 v132, v33, v150
	v_add_f32_e32 v153, v153, v132
	v_mul_f32_e32 v132, v33, v153
	v_fma_f32 v132, v32, v152, -v132
	ds_read2st64_b32 v[156:157], v126 offset0:26 offset1:27
	s_waitcnt lgkmcnt(1)
	v_add_f32_e32 v154, v154, v132
	v_mul_f32_e32 v132, v32, v153
	v_fmac_f32_e32 v132, v33, v152
	v_add_f32_e32 v155, v155, v132
	v_mul_f32_e32 v132, v33, v155
	v_fma_f32 v132, v32, v154, -v132
	ds_read2st64_b32 v[158:159], v127 offset0:28 offset1:29
	s_waitcnt lgkmcnt(1)
	v_add_f32_e32 v156, v156, v132
	v_mul_f32_e32 v132, v32, v155
	v_fmac_f32_e32 v132, v33, v154
	v_add_f32_e32 v157, v157, v132
	v_mul_f32_e32 v132, v33, v157
	v_fma_f32 v132, v32, v156, -v132
	ds_read2st64_b32 v[160:161], v128 offset0:30 offset1:31
	s_waitcnt lgkmcnt(1)
	v_add_f32_e32 v158, v158, v132
	v_mul_f32_e32 v132, v32, v157
	v_fmac_f32_e32 v132, v33, v156
	v_add_f32_e32 v159, v159, v132
	v_mul_f32_e32 v132, v33, v159
	v_mul_f32_e32 v133, v32, v159
	v_fma_f32 v132, v32, v158, -v132
	v_fmac_f32_e32 v133, v33, v158
	s_waitcnt lgkmcnt(0)
	v_add_f32_e32 v132, v160, v132
	v_add_f32_e32 v133, v161, v133
	ds_write2st64_b32 v112, v102, v100 offset1:1
	ds_write2_b32 v112, v101, v103 offset0:132 offset1:196
	ds_write2st64_b32 v115, v134, v135 offset0:4 offset1:5
	ds_write2st64_b32 v116, v136, v137 offset0:6 offset1:7
	ds_write2st64_b32 v117, v138, v139 offset0:8 offset1:9
	ds_write2st64_b32 v118, v140, v141 offset0:10 offset1:11
	ds_write2st64_b32 v119, v142, v143 offset0:12 offset1:13
	ds_write2st64_b32 v120, v144, v145 offset0:14 offset1:15
	ds_write2st64_b32 v121, v146, v147 offset0:16 offset1:17
	ds_write2st64_b32 v122, v148, v149 offset0:18 offset1:19
	ds_write2st64_b32 v123, v150, v151 offset0:20 offset1:21
	ds_write2st64_b32 v124, v152, v153 offset0:22 offset1:23
	ds_write2st64_b32 v125, v154, v155 offset0:24 offset1:25
	ds_write2st64_b32 v126, v156, v157 offset0:26 offset1:27
	ds_write2st64_b32 v127, v158, v159 offset0:28 offset1:29
	ds_write2st64_b32 v128, v132, v133 offset0:30 offset1:31
	s_waitcnt lgkmcnt(0)
	ds_read_b128 v[100:103], v113
	ds_read_b128 v[134:137], v113 offset:16
	s_waitcnt vmcnt(4)
	v_lshlrev_b32_e32 v131, 16, v131
	v_mul_f32_e32 v160, v33, v133
	v_fma_f32 v160, v32, v132, -v160
	s_waitcnt lgkmcnt(1)
	v_cvt_pk_bf16_f32 v138, v100, v101
	v_cvt_pk_bf16_f32 v139, v102, v103
	v_lshlrev_b32_e32 v142, 16, v138
	v_and_b32_e32 v143, 0xffff0000, v138
	v_pk_add_f32 v[100:101], v[100:101], v[142:143] neg_lo:[0,1] neg_hi:[0,1]
	v_lshlrev_b32_e32 v142, 16, v139
	v_and_b32_e32 v143, 0xffff0000, v139
	s_waitcnt lgkmcnt(0)
; __device__ __forceinline__ unsigned cvt_pk(float lo, float hi) { f32x2_t v = {lo, hi}; bf16x2_t b = __builtin_convertvector(v, bf16x2_t); return __builtin_bit_cast(unsigned, b); }
; __device__ __forceinline__ float bf2f(unsigned short h) { return __uint_as_float(((unsigned)h) << 16); }
; __device__ __forceinline__ float bflo(unsigned w) { return __uint_as_float(w << 16); }
; __device__ __forceinline__ float bfhi(unsigned w) { return __uint_as_float(w & 0xffff0000u); }
; __device__ __forceinline__ unsigned short f2bf(float f) { return (unsigned short)(cvt_pk(f, 0.f) & 0xffffu); }
; __device__ __forceinline__ void s5_unit(ArgsP A, int l, int unit, unsigned char* lds, int wave_, int lane_) {
;     ...
;             for (int ks = 0; ks < 4; ++ks) { const float* hp = Hs + (lane & 15) * 132 + 32 * ks + 8 * (lane >> 4); const f32x4 h0 = *(const f32x4*)hp, h1 = *(const f32x4*)(hp + 4);
;                 u32x4 wh; wh.x = cvt_pk(h0[0], h0[1]); wh.y = cvt_pk(h0[2], h0[3]); wh.z = cvt_pk(h1[0], h1[1]); wh.w = cvt_pk(h1[2], h1[3]);
;                 u32x4 wl; wl.x = cvt_pk(h0[0] - bflo(wh.x), h0[1] - bfhi(wh.x)); wl.y = cvt_pk(h0[2] - bflo(wh.y), h0[3] - bfhi(wh.y)); wl.z = cvt_pk(h1[0] - bflo(wh.z), h1[1] - bfhi(wh.z)); wl.w = cvt_pk(h1[2] - bflo(wh.w), h1[3] - bfhi(wh.w));
;                 const bf16x8 hh_ = __builtin_bit_cast(bf16x8, wh), hl_ = __builtin_bit_cast(bf16x8, wl);
;                 y = __builtin_amdgcn_mfma_f32_16x16x32_bf16(hh_, chl[2 * ks], y, 0, 0, 0); y2 = __builtin_amdgcn_mfma_f32_16x16x32_bf16(hh_, chl[2 * ks + 1], y2, 0, 0, 0);
;                 y2 = __builtin_amdgcn_mfma_f32_16x16x32_bf16(hl_, chl[2 * ks], y2, 0, 0, 0); }
;             y = y + y2;
; #pragma unroll
;             for (int i = 0; i < 4; ++i) { const int t = 16 * blk + 4 * (lane >> 4) + i; const int col = 16 * g + (lane & 15);
;                 const float uval = bf2f(uraw[i]); const float v = gelu_tanh(y[i] + dv * uval); ys[t * YS_STRIDE + col] = f2bf(v); }
	v_cvt_pk_bf16_f32 v140, v134, v135
	v_cvt_pk_bf16_f32 v141, v136, v137
	v_pk_add_f32 v[102:103], v[102:103], v[142:143] neg_lo:[0,1] neg_hi:[0,1]
	v_cvt_pk_bf16_f32 v100, v100, v101
	v_cvt_pk_bf16_f32 v101, v102, v103
	v_lshlrev_b32_e32 v102, 16, v140
	v_and_b32_e32 v103, 0xffff0000, v140
	v_pk_add_f32 v[102:103], v[134:135], v[102:103] neg_lo:[0,1] neg_hi:[0,1]
	v_lshlrev_b32_e32 v134, 16, v141
	v_and_b32_e32 v135, 0xffff0000, v141
	v_pk_add_f32 v[134:135], v[136:137], v[134:135] neg_lo:[0,1] neg_hi:[0,1]
	v_cvt_pk_bf16_f32 v102, v102, v103
	v_cvt_pk_bf16_f32 v103, v134, v135
	v_mfma_f32_16x16x32_bf16 v[134:137], v[138:141], v[24:27], 0
	v_mfma_f32_16x16x32_bf16 v[138:141], v[138:141], v[28:31], 0
	v_mfma_f32_16x16x32_bf16 v[100:103], v[100:103], v[24:27], v[138:141]
	s_nop 6
	ds_read_b128 v[138:141], v113 offset:128
	ds_read_b128 v[142:145], v113 offset:144
	s_waitcnt lgkmcnt(1)
	v_cvt_pk_bf16_f32 v146, v138, v139
	v_cvt_pk_bf16_f32 v147, v140, v141
	v_lshlrev_b32_e32 v150, 16, v146
	v_and_b32_e32 v151, 0xffff0000, v146
	v_pk_add_f32 v[138:139], v[138:139], v[150:151] neg_lo:[0,1] neg_hi:[0,1]
	v_lshlrev_b32_e32 v150, 16, v147
	v_and_b32_e32 v151, 0xffff0000, v147
	s_waitcnt lgkmcnt(0)
	v_cvt_pk_bf16_f32 v148, v142, v143
	v_cvt_pk_bf16_f32 v149, v144, v145
	v_pk_add_f32 v[140:141], v[140:141], v[150:151] neg_lo:[0,1] neg_hi:[0,1]
	v_cvt_pk_bf16_f32 v138, v138, v139
	v_cvt_pk_bf16_f32 v139, v140, v141
	v_lshlrev_b32_e32 v140, 16, v148
	v_and_b32_e32 v141, 0xffff0000, v148
	v_pk_add_f32 v[140:141], v[142:143], v[140:141] neg_lo:[0,1] neg_hi:[0,1]
	v_lshlrev_b32_e32 v142, 16, v149
	v_and_b32_e32 v143, 0xffff0000, v149
	v_pk_add_f32 v[142:143], v[144:145], v[142:143] neg_lo:[0,1] neg_hi:[0,1]
	v_cvt_pk_bf16_f32 v140, v140, v141
	v_cvt_pk_bf16_f32 v141, v142, v143
	v_mfma_f32_16x16x32_bf16 v[100:103], v[146:149], v[20:23], v[100:103]
	s_nop 0
	v_mfma_f32_16x16x32_bf16 v[100:103], v[138:141], v[16:19], v[100:103]
	ds_read_b128 v[138:141], v113 offset:256
	ds_read_b128 v[142:145], v113 offset:272
	v_mfma_f32_16x16x32_bf16 v[134:137], v[146:149], v[16:19], v[134:137]
	s_waitcnt lgkmcnt(1)
	v_cvt_pk_bf16_f32 v146, v138, v139
	v_cvt_pk_bf16_f32 v147, v140, v141
	v_lshlrev_b32_e32 v150, 16, v146
	v_and_b32_e32 v151, 0xffff0000, v146
	v_pk_add_f32 v[138:139], v[138:139], v[150:151] neg_lo:[0,1] neg_hi:[0,1]
	v_lshlrev_b32_e32 v150, 16, v147
	v_and_b32_e32 v151, 0xffff0000, v147
	s_waitcnt lgkmcnt(0)
	v_cvt_pk_bf16_f32 v148, v142, v143
	v_cvt_pk_bf16_f32 v149, v144, v145
	v_pk_add_f32 v[140:141], v[140:141], v[150:151] neg_lo:[0,1] neg_hi:[0,1]
	v_cvt_pk_bf16_f32 v138, v138, v139
	v_cvt_pk_bf16_f32 v139, v140, v141
	v_lshlrev_b32_e32 v140, 16, v148
	v_and_b32_e32 v141, 0xffff0000, v148
	v_pk_add_f32 v[140:141], v[142:143], v[140:141] neg_lo:[0,1] neg_hi:[0,1]
	v_lshlrev_b32_e32 v142, 16, v149
	v_and_b32_e32 v143, 0xffff0000, v149
	v_pk_add_f32 v[142:143], v[144:145], v[142:143] neg_lo:[0,1] neg_hi:[0,1]
	v_cvt_pk_bf16_f32 v140, v140, v141
	v_cvt_pk_bf16_f32 v141, v142, v143
	v_mfma_f32_16x16x32_bf16 v[100:103], v[146:149], v[12:15], v[100:103]
	s_nop 0
	v_mfma_f32_16x16x32_bf16 v[100:103], v[138:141], v[8:11], v[100:103]
	ds_read_b128 v[138:141], v113 offset:384
	ds_read_b128 v[142:145], v113 offset:400
	v_mfma_f32_16x16x32_bf16 v[134:137], v[146:149], v[8:11], v[134:137]
	s_waitcnt lgkmcnt(1)
	v_cvt_pk_bf16_f32 v146, v138, v139
	v_cvt_pk_bf16_f32 v147, v140, v141
	v_lshlrev_b32_e32 v150, 16, v146
	v_and_b32_e32 v151, 0xffff0000, v146
	v_pk_add_f32 v[138:139], v[138:139], v[150:151] neg_lo:[0,1] neg_hi:[0,1]
	v_lshlrev_b32_e32 v150, 16, v147
	v_and_b32_e32 v151, 0xffff0000, v147
	s_waitcnt lgkmcnt(0)
	v_cvt_pk_bf16_f32 v148, v142, v143
	v_cvt_pk_bf16_f32 v149, v144, v145
	v_pk_add_f32 v[140:141], v[140:141], v[150:151] neg_lo:[0,1] neg_hi:[0,1]
	v_cvt_pk_bf16_f32 v138, v138, v139
	v_cvt_pk_bf16_f32 v139, v140, v141
	v_lshlrev_b32_e32 v140, 16, v148
	v_and_b32_e32 v141, 0xffff0000, v148
	v_pk_add_f32 v[140:141], v[142:143], v[140:141] neg_lo:[0,1] neg_hi:[0,1]
	v_lshlrev_b32_e32 v142, 16, v149
	v_and_b32_e32 v143, 0xffff0000, v149
	v_pk_add_f32 v[142:143], v[144:145], v[142:143] neg_lo:[0,1] neg_hi:[0,1]
	v_cvt_pk_bf16_f32 v140, v140, v141
	v_cvt_pk_bf16_f32 v141, v142, v143
	v_mfma_f32_16x16x32_bf16 v[100:103], v[146:149], v[4:7], v[100:103]
	v_mfma_f32_16x16x32_bf16 v[134:137], v[146:149], v[0:3], v[134:137]
	v_mfma_f32_16x16x32_bf16 v[138:141], v[138:141], v[0:3], v[100:103]
	s_nop 7
	v_pk_add_f32 v[102:103], v[134:135], v[138:139]
	v_lshlrev_b32_e32 v134, 16, v162
	v_fma_f32 v102, v79, v134, v102
	v_fmac_f32_e32 v103, v79, v131
	v_mul_f32_e32 v134, 0x3d372713, v102
	v_mul_f32_e32 v131, 0x3d372713, v103
	v_mul_f32_e32 v134, v102, v134
	v_mul_f32_e32 v131, v103, v131
	v_fma_f32 v134, v102, v134, v102
	v_fma_f32 v131, v103, v131, v103
	v_mul_f32_e32 v134, 0x3f4c422a, v134
	v_mul_f32_e32 v131, 0x3f4c422a, v131
	v_add_f32_e32 v134, v134, v134
	v_add_f32_e32 v131, v131, v131
	v_mul_f32_e32 v134, 0x3fb8aa3b, v134
	v_mul_f32_e32 v131, 0x3fb8aa3b, v131
	v_exp_f32_e32 v134, v134
	v_exp_f32_e32 v131, v131
	v_mul_f32_e32 v102, 0.5, v102
	v_mul_f32_e32 v103, 0.5, v103
	v_add_f32_e32 v134, 1.0, v134
	v_add_f32_e32 v131, 1.0, v131
	v_rcp_f32_e32 v134, v134
	v_rcp_f32_e32 v131, v131
	v_pk_add_f32 v[100:101], v[136:137], v[140:141]
	v_fma_f32 v134, v134, -2.0, 1.0
	v_fma_f32 v131, v131, -2.0, 1.0
	v_add_f32_e32 v134, 1.0, v134
	v_add_f32_e32 v131, 1.0, v131
	v_mul_f32_e32 v102, v102, v134
	v_mul_f32_e32 v103, v103, v131
	v_cvt_pk_bf16_f32 v134, v102, s0
	v_add_u32_e32 v102, s5, v114
	v_cvt_pk_bf16_f32 v103, v103, s0
	ds_write_b16 v102, v103 offset:1040
	s_waitcnt vmcnt(1)
; template <bool WRITEH>
; __device__ __forceinline__ void s5_block(const S5Coef& C, const bf16x8 (&bm)[8], u32x4 uw, float* Hs, int lane, float& hr, float& hi) {
;     const bf16x8 ua = __builtin_bit_cast(bf16x8, uw);
; #pragma unroll
;     for (int nb = 0; nb < 8; ++nb) { const f32x4 d = __builtin_amdgcn_mfma_f32_16x16x32_bf16(ua, bm[nb], (f32x4){0.f, 0.f, 0.f, 0.f}, 0, 0, 0);
; #pragma unroll
;         for (int i = 0; i < 4; ++i) Hs[(4 * (lane >> 4) + i) * 132 + 16 * nb + (lane & 15)] = d[i]; }
;     S5_LDS_FENCE();
;     float bur[16], bui[16];
; #pragma unroll
;     for (int tl = 0; tl < 16; ++tl) { bur[tl] = Hs[tl * 132 + lane]; bui[tl] = Hs[tl * 132 + 64 + lane]; }
; #pragma unroll
;     for (int tl = 0; tl < 16; ++tl) { const float nr = C.ar * hr - C.ai * hi + bur[tl], ni = C.ar * hi + C.ai * hr + bui[tl]; hr = nr; hi = ni; bur[tl] = hr; bui[tl] = hi; }
; __device__ __forceinline__ void s5_unit(ArgsP A, int l, int unit, unsigned char* lds, int wave_, int lane_) {
;     ...
;         for (int blk = 0; blk < 4; ++blk) {
;             unsigned short uraw[4];
; #pragma unroll
;             for (int i = 0; i < 4; ++i) uraw[i] = PROJ[(size_t)(rowbase + 16 * blk + 4 * (lane >> 4) + i) * INWP + C_S5 + 16 * g + (lane & 15)];
;             s5_block<true>(C, bm, uw[blk], Hs, lane, hr, hi);
;             f32x4 y = (f32x4){0.f, 0.f, 0.f, 0.f}, y2 = (f32x4){0.f, 0.f, 0.f, 0.f};
; #pragma unroll
;             for (int ks = 0; ks < 4; ++ks) { const float* hp = Hs + (lane & 15) * 132 + 32 * ks + 8 * (lane >> 4); const f32x4 h0 = *(const f32x4*)hp, h1 = *(const f32x4*)(hp + 4);
;                 u32x4 wh; wh.x = cvt_pk(h0[0], h0[1]); wh.y = cvt_pk(h0[2], h0[3]); wh.z = cvt_pk(h1[0], h1[1]); wh.w = cvt_pk(h1[2], h1[3]);
;                 u32x4 wl; wl.x = cvt_pk(h0[0] - bflo(wh.x), h0[1] - bfhi(wh.x)); wl.y = cvt_pk(h0[2] - bflo(wh.y), h0[3] - bfhi(wh.y)); wl.z = cvt_pk(h1[0] - bflo(wh.z), h1[1] - bfhi(wh.z)); wl.w = cvt_pk(h1[2] - bflo(wh.w), h1[3] - bfhi(wh.w));
;                 const bf16x8 hh_ = __builtin_bit_cast(bf16x8, wh), hl_ = __builtin_bit_cast(bf16x8, wl);
;                 y = __builtin_amdgcn_mfma_f32_16x16x32_bf16(hh_, chl[2 * ks], y, 0, 0, 0); y2 = __builtin_amdgcn_mfma_f32_16x16x32_bf16(hh_, chl[2 * ks + 1], y2, 0, 0, 0);
;                 y2 = __builtin_amdgcn_mfma_f32_16x16x32_bf16(hl_, chl[2 * ks], y2, 0, 0, 0); }
;             y = y + y2;
; #pragma unroll
	v_lshlrev_b32_e32 v103, 16, v130
	v_fma_f32 v100, v79, v103, v100
	v_mul_f32_e32 v103, 0x3d372713, v100
	v_mul_f32_e32 v103, v100, v103
	v_fma_f32 v103, v100, v103, v100
	v_mul_f32_e32 v103, 0x3f4c422a, v103
	v_add_f32_e32 v103, v103, v103
	v_mul_f32_e32 v103, 0x3fb8aa3b, v103
	v_exp_f32_e32 v103, v103
	v_mul_f32_e32 v100, 0.5, v100
	ds_write_b16 v102, v134
	v_mfma_f32_16x16x32_bf16 v[134:137], v[74:77], v[62:65], 0
	v_add_f32_e32 v103, 1.0, v103
	v_rcp_f32_e32 v103, v103
	s_add_i32 s5, s5, 32
	s_cmpk_lg_i32 s5, 0x80
	v_fma_f32 v103, v103, -2.0, 1.0
	v_add_f32_e32 v103, 1.0, v103
	v_mul_f32_e32 v100, v100, v103
	v_cvt_pk_bf16_f32 v100, v100, s0
	ds_write_b16 v102, v100 offset:2080
	s_waitcnt vmcnt(0)
	v_lshlrev_b32_e32 v100, 16, v129
	v_fmac_f32_e32 v101, v79, v100
	v_mul_f32_e32 v100, 0x3d372713, v101
	v_mul_f32_e32 v100, v101, v100
	v_fma_f32 v100, v101, v100, v101
	v_mul_f32_e32 v100, 0x3f4c422a, v100
	v_add_f32_e32 v100, v100, v100
	v_mul_f32_e32 v100, 0x3fb8aa3b, v100
	v_exp_f32_e32 v100, v100
	v_mul_f32_e32 v101, 0.5, v101
	v_add_f32_e32 v100, 1.0, v100
	v_rcp_f32_e32 v100, v100
	s_nop 0
	v_fma_f32 v100, v100, -2.0, 1.0
	v_add_f32_e32 v100, 1.0, v100
	v_mul_f32_e32 v100, v101, v100
	v_cvt_pk_bf16_f32 v100, v100, s0
	ds_write_b16 v102, v100 offset:3120
	s_waitcnt lgkmcnt(0)
	ds_write_b32 v106, v134
	ds_write_b32 v106, v135 offset:528
	ds_write_b32 v106, v136 offset:1056
	ds_write_b32 v107, v137
	v_mfma_f32_16x16x32_bf16 v[134:137], v[74:77], v[58:61], 0
	s_nop 7
	ds_write_b32 v106, v134 offset:64
	ds_write_b32 v106, v135 offset:592
	ds_write_b32 v106, v136 offset:1120
	ds_write_b32 v107, v137 offset:64
	v_mfma_f32_16x16x32_bf16 v[134:137], v[74:77], v[54:57], 0
	s_nop 7
	ds_write_b32 v106, v134 offset:128
	ds_write_b32 v106, v135 offset:656
	ds_write_b32 v106, v136 offset:1184
	ds_write_b32 v107, v137 offset:128
	v_mfma_f32_16x16x32_bf16 v[134:137], v[74:77], v[50:53], 0
	s_nop 7
	ds_write2_b32 v108, v134, v135 offset1:132
	ds_write_b32 v108, v136 offset:1056
	ds_write_b32 v109, v137
	v_mfma_f32_16x16x32_bf16 v[134:137], v[74:77], v[46:49], 0
	s_nop 7
	ds_write_b32 v106, v134 offset:256
	ds_write_b32 v106, v135 offset:784
	ds_write_b32 v106, v136 offset:1312
	ds_write_b32 v107, v137 offset:256
	v_mfma_f32_16x16x32_bf16 v[134:137], v[74:77], v[42:45], 0
	s_nop 7
	ds_write_b32 v106, v134 offset:320
	ds_write_b32 v106, v135 offset:848
	ds_write_b32 v106, v136 offset:1376
	ds_write_b32 v107, v137 offset:320
	v_mfma_f32_16x16x32_bf16 v[134:137], v[74:77], v[38:41], 0
	v_lshl_add_u64 v[100:101], s[2:3], 0, v[84:85]
	s_nop 6
	ds_write_b32 v106, v134 offset:384
	ds_write_b32 v106, v135 offset:912
	ds_write_b32 v106, v136 offset:1440
	ds_write_b32 v107, v137 offset:384
	v_mfma_f32_16x16x32_bf16 v[74:77], v[74:77], v[34:37], 0
	s_nop 7
	ds_write2_b32 v110, v74, v75 offset1:132
	ds_write_b32 v110, v76 offset:1056
	ds_write_b32 v111, v77
	v_add_co_u32_e32 v74, vcc, s12, v100
	v_lshl_add_u64 v[84:85], v[84:85], 0, 32
	s_nop 0
	v_addc_co_u32_e32 v75, vcc, 0, v101, vcc
	global_load_ushort v103, v[74:75], off
	v_add_co_u32_e32 v74, vcc, s13, v100
	s_waitcnt vmcnt(0)
	v_lshlrev_b32_e32 v103, 16, v103
	v_addc_co_u32_e32 v75, vcc, 0, v101, vcc
	global_load_ushort v129, v[74:75], off offset:512
	v_add_co_u32_e32 v74, vcc, s33, v100
	s_nop 1
	v_addc_co_u32_e32 v75, vcc, 0, v101, vcc
	global_load_ushort v158, v[74:75], off offset:1024
	v_add_co_u32_e32 v74, vcc, s28, v100
	s_nop 1
	v_addc_co_u32_e32 v75, vcc, 0, v101, vcc
	global_load_ushort v159, v[74:75], off offset:1536
	s_waitcnt lgkmcnt(0)
	ds_read2st64_b32 v[74:75], v112 offset1:1
	ds_read2_b32 v[76:77], v112 offset0:132 offset1:196
	ds_read2st64_b32 v[100:101], v115 offset0:4 offset1:5
	ds_read2st64_b32 v[130:131], v116 offset0:6 offset1:7
	ds_read2st64_b32 v[134:135], v117 offset0:8 offset1:9
	ds_read2st64_b32 v[136:137], v118 offset0:10 offset1:11
	ds_read2st64_b32 v[138:139], v119 offset0:12 offset1:13
	ds_read2st64_b32 v[140:141], v120 offset0:14 offset1:15
	ds_read2st64_b32 v[142:143], v121 offset0:16 offset1:17
	ds_read2st64_b32 v[144:145], v122 offset0:18 offset1:19
	ds_read2st64_b32 v[146:147], v123 offset0:20 offset1:21
	ds_read2st64_b32 v[148:149], v124 offset0:22 offset1:23
	ds_read2st64_b32 v[150:151], v125 offset0:24 offset1:25
	ds_read2st64_b32 v[152:153], v126 offset0:26 offset1:27
	ds_read2st64_b32 v[154:155], v127 offset0:28 offset1:29
	ds_read2st64_b32 v[156:157], v128 offset0:30 offset1:31
	s_waitcnt lgkmcnt(14)
	v_add_f32_e32 v160, v160, v74
	v_mul_f32_e32 v74, v32, v133
	v_fmac_f32_e32 v74, v33, v132
	v_add_f32_e32 v132, v74, v75
	v_mul_f32_e32 v74, v33, v132
	v_fma_f32 v74, v32, v160, -v74
	v_add_f32_e32 v76, v76, v74
	v_mul_f32_e32 v74, v32, v132
	v_fmac_f32_e32 v74, v33, v160
	v_add_f32_e32 v77, v77, v74
	v_mul_f32_e32 v74, v33, v77
	v_fma_f32 v74, v32, v76, -v74
	s_waitcnt lgkmcnt(13)
	v_add_f32_e32 v100, v100, v74
	v_mul_f32_e32 v74, v32, v77
	v_fmac_f32_e32 v74, v33, v76
	v_add_f32_e32 v101, v101, v74
	v_mul_f32_e32 v74, v33, v101
	v_fma_f32 v74, v32, v100, -v74
	s_waitcnt lgkmcnt(12)
	v_add_f32_e32 v130, v130, v74
	v_mul_f32_e32 v74, v32, v101
	v_fmac_f32_e32 v74, v33, v100
	v_add_f32_e32 v131, v131, v74
	v_mul_f32_e32 v74, v33, v131
	v_fma_f32 v74, v32, v130, -v74
	s_waitcnt lgkmcnt(11)
	v_add_f32_e32 v133, v134, v74
	v_mul_f32_e32 v74, v32, v131
	v_fmac_f32_e32 v74, v33, v130
	v_add_f32_e32 v134, v135, v74
	v_mul_f32_e32 v74, v33, v134
	v_fma_f32 v74, v32, v133, -v74
	s_waitcnt lgkmcnt(10)
	v_add_f32_e32 v135, v136, v74
	v_mul_f32_e32 v74, v32, v134
	v_fmac_f32_e32 v74, v33, v133
	v_add_f32_e32 v136, v137, v74
	v_mul_f32_e32 v74, v33, v136
	v_fma_f32 v74, v32, v135, -v74
	s_waitcnt lgkmcnt(9)
; __device__ __forceinline__ unsigned cvt_pk(float lo, float hi) { f32x2_t v = {lo, hi}; bf16x2_t b = __builtin_convertvector(v, bf16x2_t); return __builtin_bit_cast(unsigned, b); }
; __device__ __forceinline__ float bflo(unsigned w) { return __uint_as_float(w << 16); }
; __device__ __forceinline__ float bfhi(unsigned w) { return __uint_as_float(w & 0xffff0000u); }
; #define S5_LDS_FENCE() do { __builtin_amdgcn_wave_barrier(); asm volatile("s_waitcnt lgkmcnt(0)" ::: "memory"); } while (0)
; template <bool WRITEH>
; __device__ __forceinline__ void s5_block(const S5Coef& C, const bf16x8 (&bm)[8], u32x4 uw, float* Hs, int lane, float& hr, float& hi) {
;     ...
;     for (int tl = 0; tl < 16; ++tl) { bur[tl] = Hs[tl * 132 + lane]; bui[tl] = Hs[tl * 132 + 64 + lane]; }
; #pragma unroll
;     for (int tl = 0; tl < 16; ++tl) { const float nr = C.ar * hr - C.ai * hi + bur[tl], ni = C.ar * hi + C.ai * hr + bui[tl]; hr = nr; hi = ni; bur[tl] = hr; bui[tl] = hi; }
;     if (WRITEH) {
; #pragma unroll
;         for (int tl = 0; tl < 16; ++tl) { Hs[tl * 132 + lane] = bur[tl]; Hs[tl * 132 + 64 + lane] = bui[tl]; }
;     }
;     S5_LDS_FENCE();
; }
; __device__ __forceinline__ void s5_unit(ArgsP A, int l, int unit, unsigned char* lds, int wave_, int lane_) {
;     ...
;             for (int ks = 0; ks < 4; ++ks) { const float* hp = Hs + (lane & 15) * 132 + 32 * ks + 8 * (lane >> 4); const f32x4 h0 = *(const f32x4*)hp, h1 = *(const f32x4*)(hp + 4);
;                 u32x4 wh; wh.x = cvt_pk(h0[0], h0[1]); wh.y = cvt_pk(h0[2], h0[3]); wh.z = cvt_pk(h1[0], h1[1]); wh.w = cvt_pk(h1[2], h1[3]);
;                 u32x4 wl; wl.x = cvt_pk(h0[0] - bflo(wh.x), h0[1] - bfhi(wh.x)); wl.y = cvt_pk(h0[2] - bflo(wh.y), h0[3] - bfhi(wh.y)); wl.z = cvt_pk(h1[0] - bflo(wh.z), h1[1] - bfhi(wh.z)); wl.w = cvt_pk(h1[2] - bflo(wh.w), h1[3] - bfhi(wh.w));
;                 const bf16x8 hh_ = __builtin_bit_cast(bf16x8, wh), hl_ = __builtin_bit_cast(bf16x8, wl);
;                 y = __builtin_amdgcn_mfma_f32_16x16x32_bf16(hh_, chl[2 * ks], y, 0, 0, 0); y2 = __builtin_amdgcn_mfma_f32_16x16x32_bf16(hh_, chl[2 * ks + 1], y2, 0, 0, 0);
;                 y2 = __builtin_amdgcn_mfma_f32_16x16x32_bf16(hl_, chl[2 * ks], y2, 0, 0, 0); }
	v_add_f32_e32 v137, v138, v74
	v_mul_f32_e32 v74, v32, v136
	v_fmac_f32_e32 v74, v33, v135
	v_add_f32_e32 v138, v139, v74
	v_mul_f32_e32 v74, v33, v138
	v_fma_f32 v74, v32, v137, -v74
	s_waitcnt lgkmcnt(8)
	v_add_f32_e32 v139, v140, v74
	v_mul_f32_e32 v74, v32, v138
	v_fmac_f32_e32 v74, v33, v137
	v_add_f32_e32 v140, v141, v74
	v_mul_f32_e32 v74, v33, v140
	v_fma_f32 v74, v32, v139, -v74
	s_waitcnt lgkmcnt(7)
	v_add_f32_e32 v141, v142, v74
	v_mul_f32_e32 v74, v32, v140
	v_fmac_f32_e32 v74, v33, v139
	v_add_f32_e32 v142, v143, v74
	v_mul_f32_e32 v74, v33, v142
	v_fma_f32 v74, v32, v141, -v74
	s_waitcnt lgkmcnt(6)
	v_add_f32_e32 v143, v144, v74
	v_mul_f32_e32 v74, v32, v142
	v_fmac_f32_e32 v74, v33, v141
	v_add_f32_e32 v144, v145, v74
	v_mul_f32_e32 v74, v33, v144
	v_fma_f32 v74, v32, v143, -v74
	s_waitcnt lgkmcnt(5)
	v_add_f32_e32 v145, v146, v74
	v_mul_f32_e32 v74, v32, v144
	v_fmac_f32_e32 v74, v33, v143
	v_add_f32_e32 v146, v147, v74
	v_mul_f32_e32 v74, v33, v146
	v_fma_f32 v74, v32, v145, -v74
	s_waitcnt lgkmcnt(4)
	v_add_f32_e32 v147, v148, v74
	v_mul_f32_e32 v74, v32, v146
	v_fmac_f32_e32 v74, v33, v145
	v_add_f32_e32 v148, v149, v74
	v_mul_f32_e32 v74, v33, v148
	v_fma_f32 v74, v32, v147, -v74
	s_waitcnt lgkmcnt(3)
	v_add_f32_e32 v149, v150, v74
	v_mul_f32_e32 v74, v32, v148
	v_fmac_f32_e32 v74, v33, v147
	v_add_f32_e32 v150, v151, v74
	v_mul_f32_e32 v74, v33, v150
	v_fma_f32 v74, v32, v149, -v74
	s_waitcnt lgkmcnt(2)
	v_add_f32_e32 v151, v152, v74
	v_mul_f32_e32 v74, v32, v150
	v_fmac_f32_e32 v74, v33, v149
	v_add_f32_e32 v152, v153, v74
	v_mul_f32_e32 v74, v33, v152
	v_fma_f32 v74, v32, v151, -v74
	s_waitcnt lgkmcnt(1)
	v_add_f32_e32 v153, v154, v74
	v_mul_f32_e32 v74, v32, v152
	v_fmac_f32_e32 v74, v33, v151
	v_add_f32_e32 v154, v155, v74
	v_mul_f32_e32 v74, v33, v154
	v_mul_f32_e32 v75, v32, v154
	v_fma_f32 v74, v32, v153, -v74
	v_fmac_f32_e32 v75, v33, v153
	s_waitcnt lgkmcnt(0)
	v_add_f32_e32 v74, v156, v74
	v_add_f32_e32 v75, v157, v75
	ds_write2st64_b32 v112, v160, v132 offset1:1
	ds_write2_b32 v112, v76, v77 offset0:132 offset1:196
	ds_write2st64_b32 v115, v100, v101 offset0:4 offset1:5
	ds_write2st64_b32 v116, v130, v131 offset0:6 offset1:7
	ds_write2st64_b32 v117, v133, v134 offset0:8 offset1:9
	ds_write2st64_b32 v118, v135, v136 offset0:10 offset1:11
	ds_write2st64_b32 v119, v137, v138 offset0:12 offset1:13
	ds_write2st64_b32 v120, v139, v140 offset0:14 offset1:15
	ds_write2st64_b32 v121, v141, v142 offset0:16 offset1:17
	ds_write2st64_b32 v122, v143, v144 offset0:18 offset1:19
	ds_write2st64_b32 v123, v145, v146 offset0:20 offset1:21
	ds_write2st64_b32 v124, v147, v148 offset0:22 offset1:23
	ds_write2st64_b32 v125, v149, v150 offset0:24 offset1:25
	ds_write2st64_b32 v126, v151, v152 offset0:26 offset1:27
	ds_write2st64_b32 v127, v153, v154 offset0:28 offset1:29
	ds_write2st64_b32 v128, v74, v75 offset0:30 offset1:31
	s_waitcnt lgkmcnt(0)
	ds_read_b128 v[130:133], v113
	ds_read_b128 v[134:137], v113 offset:16
	v_mul_f32_e32 v156, v33, v75
	v_fma_f32 v156, v32, v74, -v156
	s_waitcnt lgkmcnt(1)
	v_cvt_pk_bf16_f32 v138, v130, v131
	v_lshlrev_b32_e32 v76, 16, v138
	v_and_b32_e32 v77, 0xffff0000, v138
	v_cvt_pk_bf16_f32 v139, v132, v133
	v_pk_add_f32 v[76:77], v[130:131], v[76:77] neg_lo:[0,1] neg_hi:[0,1]
	s_waitcnt lgkmcnt(0)
	v_cvt_pk_bf16_f32 v140, v134, v135
	v_cvt_pk_bf16_f32 v130, v76, v77
	v_lshlrev_b32_e32 v76, 16, v139
	v_and_b32_e32 v77, 0xffff0000, v139
	v_pk_add_f32 v[76:77], v[132:133], v[76:77] neg_lo:[0,1] neg_hi:[0,1]
	v_cvt_pk_bf16_f32 v141, v136, v137
	v_cvt_pk_bf16_f32 v131, v76, v77
	v_lshlrev_b32_e32 v76, 16, v140
	v_and_b32_e32 v77, 0xffff0000, v140
	v_pk_add_f32 v[76:77], v[134:135], v[76:77] neg_lo:[0,1] neg_hi:[0,1]
	s_nop 0
	v_cvt_pk_bf16_f32 v132, v76, v77
	v_lshlrev_b32_e32 v76, 16, v141
	v_and_b32_e32 v77, 0xffff0000, v141
	v_pk_add_f32 v[76:77], v[136:137], v[76:77] neg_lo:[0,1] neg_hi:[0,1]
	v_mfma_f32_16x16x32_bf16 v[134:137], v[138:141], v[24:27], 0
	v_cvt_pk_bf16_f32 v133, v76, v77
	v_mfma_f32_16x16x32_bf16 v[138:141], v[138:141], v[28:31], 0
	s_nop 0
	v_mfma_f32_16x16x32_bf16 v[130:133], v[130:133], v[24:27], v[138:141]
	s_nop 5
	ds_read_b128 v[138:141], v113 offset:128
	ds_read_b128 v[142:145], v113 offset:144
	s_waitcnt lgkmcnt(1)
	v_cvt_pk_bf16_f32 v146, v138, v139
	v_lshlrev_b32_e32 v76, 16, v146
	v_and_b32_e32 v77, 0xffff0000, v146
	v_cvt_pk_bf16_f32 v147, v140, v141
	v_pk_add_f32 v[76:77], v[138:139], v[76:77] neg_lo:[0,1] neg_hi:[0,1]
	s_waitcnt lgkmcnt(0)
	v_cvt_pk_bf16_f32 v148, v142, v143
	v_cvt_pk_bf16_f32 v138, v76, v77
	v_lshlrev_b32_e32 v76, 16, v147
	v_and_b32_e32 v77, 0xffff0000, v147
	v_pk_add_f32 v[76:77], v[140:141], v[76:77] neg_lo:[0,1] neg_hi:[0,1]
	v_cvt_pk_bf16_f32 v149, v144, v145
	v_cvt_pk_bf16_f32 v139, v76, v77
	v_lshlrev_b32_e32 v76, 16, v148
	v_and_b32_e32 v77, 0xffff0000, v148
	v_pk_add_f32 v[76:77], v[142:143], v[76:77] neg_lo:[0,1] neg_hi:[0,1]
	v_mfma_f32_16x16x32_bf16 v[130:133], v[146:149], v[20:23], v[130:133]
	v_cvt_pk_bf16_f32 v140, v76, v77
	v_lshlrev_b32_e32 v76, 16, v149
	v_and_b32_e32 v77, 0xffff0000, v149
	v_pk_add_f32 v[76:77], v[144:145], v[76:77] neg_lo:[0,1] neg_hi:[0,1]
	v_mfma_f32_16x16x32_bf16 v[134:137], v[146:149], v[16:19], v[134:137]
	v_cvt_pk_bf16_f32 v141, v76, v77
	s_nop 1
	v_mfma_f32_16x16x32_bf16 v[130:133], v[138:141], v[16:19], v[130:133]
	ds_read_b128 v[138:141], v113 offset:256
	ds_read_b128 v[142:145], v113 offset:272
	s_waitcnt lgkmcnt(1)
	v_cvt_pk_bf16_f32 v146, v138, v139
	v_lshlrev_b32_e32 v76, 16, v146
	v_and_b32_e32 v77, 0xffff0000, v146
	v_cvt_pk_bf16_f32 v147, v140, v141
	v_pk_add_f32 v[76:77], v[138:139], v[76:77] neg_lo:[0,1] neg_hi:[0,1]
	s_waitcnt lgkmcnt(0)
; __device__ __forceinline__ unsigned cvt_pk(float lo, float hi) { f32x2_t v = {lo, hi}; bf16x2_t b = __builtin_convertvector(v, bf16x2_t); return __builtin_bit_cast(unsigned, b); }
; __device__ __forceinline__ float bf2f(unsigned short h) { return __uint_as_float(((unsigned)h) << 16); }
; __device__ __forceinline__ float bflo(unsigned w) { return __uint_as_float(w << 16); }
; __device__ __forceinline__ float bfhi(unsigned w) { return __uint_as_float(w & 0xffff0000u); }
; template <bool WRITEH>
; __device__ __forceinline__ void s5_block(const S5Coef& C, const bf16x8 (&bm)[8], u32x4 uw, float* Hs, int lane, float& hr, float& hi) {
;     ...
;     for (int nb = 0; nb < 8; ++nb) { const f32x4 d = __builtin_amdgcn_mfma_f32_16x16x32_bf16(ua, bm[nb], (f32x4){0.f, 0.f, 0.f, 0.f}, 0, 0, 0);
; #pragma unroll
;         for (int i = 0; i < 4; ++i) Hs[(4 * (lane >> 4) + i) * 132 + 16 * nb + (lane & 15)] = d[i]; }
;     S5_LDS_FENCE();
; __device__ __forceinline__ void s5_unit(ArgsP A, int l, int unit, unsigned char* lds, int wave_, int lane_) {
;     ...
;             for (int ks = 0; ks < 4; ++ks) { const float* hp = Hs + (lane & 15) * 132 + 32 * ks + 8 * (lane >> 4); const f32x4 h0 = *(const f32x4*)hp, h1 = *(const f32x4*)(hp + 4);
;                 u32x4 wh; wh.x = cvt_pk(h0[0], h0[1]); wh.y = cvt_pk(h0[2], h0[3]); wh.z = cvt_pk(h1[0], h1[1]); wh.w = cvt_pk(h1[2], h1[3]);
;                 u32x4 wl; wl.x = cvt_pk(h0[0] - bflo(wh.x), h0[1] - bfhi(wh.x)); wl.y = cvt_pk(h0[2] - bflo(wh.y), h0[3] - bfhi(wh.y)); wl.z = cvt_pk(h1[0] - bflo(wh.z), h1[1] - bfhi(wh.z)); wl.w = cvt_pk(h1[2] - bflo(wh.w), h1[3] - bfhi(wh.w));
;                 const bf16x8 hh_ = __builtin_bit_cast(bf16x8, wh), hl_ = __builtin_bit_cast(bf16x8, wl);
;                 y = __builtin_amdgcn_mfma_f32_16x16x32_bf16(hh_, chl[2 * ks], y, 0, 0, 0); y2 = __builtin_amdgcn_mfma_f32_16x16x32_bf16(hh_, chl[2 * ks + 1], y2, 0, 0, 0);
;                 y2 = __builtin_amdgcn_mfma_f32_16x16x32_bf16(hl_, chl[2 * ks], y2, 0, 0, 0); }
;             y = y + y2;
; #pragma unroll
;             for (int i = 0; i < 4; ++i) { const int t = 16 * blk + 4 * (lane >> 4) + i; const int col = 16 * g + (lane & 15);
;                 const float uval = bf2f(uraw[i]); const float v = gelu_tanh(y[i] + dv * uval); ys[t * YS_STRIDE + col] = f2bf(v); }
	v_cvt_pk_bf16_f32 v148, v142, v143
	v_cvt_pk_bf16_f32 v138, v76, v77
	v_lshlrev_b32_e32 v76, 16, v147
	v_and_b32_e32 v77, 0xffff0000, v147
	v_pk_add_f32 v[76:77], v[140:141], v[76:77] neg_lo:[0,1] neg_hi:[0,1]
	v_cvt_pk_bf16_f32 v149, v144, v145
	v_cvt_pk_bf16_f32 v139, v76, v77
	v_lshlrev_b32_e32 v76, 16, v148
	v_and_b32_e32 v77, 0xffff0000, v148
	v_pk_add_f32 v[76:77], v[142:143], v[76:77] neg_lo:[0,1] neg_hi:[0,1]
	v_mfma_f32_16x16x32_bf16 v[130:133], v[146:149], v[12:15], v[130:133]
	v_cvt_pk_bf16_f32 v140, v76, v77
	v_lshlrev_b32_e32 v76, 16, v149
	v_and_b32_e32 v77, 0xffff0000, v149
	v_pk_add_f32 v[76:77], v[144:145], v[76:77] neg_lo:[0,1] neg_hi:[0,1]
	v_mfma_f32_16x16x32_bf16 v[134:137], v[146:149], v[8:11], v[134:137]
	v_cvt_pk_bf16_f32 v141, v76, v77
	s_nop 1
	v_mfma_f32_16x16x32_bf16 v[130:133], v[138:141], v[8:11], v[130:133]
	ds_read_b128 v[138:141], v113 offset:384
	ds_read_b128 v[142:145], v113 offset:400
	s_waitcnt lgkmcnt(1)
	v_cvt_pk_bf16_f32 v146, v138, v139
	v_lshlrev_b32_e32 v76, 16, v146
	v_and_b32_e32 v77, 0xffff0000, v146
	v_cvt_pk_bf16_f32 v147, v140, v141
	v_pk_add_f32 v[76:77], v[138:139], v[76:77] neg_lo:[0,1] neg_hi:[0,1]
	s_waitcnt lgkmcnt(0)
	v_cvt_pk_bf16_f32 v148, v142, v143
	v_cvt_pk_bf16_f32 v138, v76, v77
	v_lshlrev_b32_e32 v76, 16, v147
	v_and_b32_e32 v77, 0xffff0000, v147
	v_pk_add_f32 v[76:77], v[140:141], v[76:77] neg_lo:[0,1] neg_hi:[0,1]
	v_cvt_pk_bf16_f32 v149, v144, v145
	v_cvt_pk_bf16_f32 v139, v76, v77
	v_lshlrev_b32_e32 v76, 16, v148
	v_and_b32_e32 v77, 0xffff0000, v148
	v_pk_add_f32 v[76:77], v[142:143], v[76:77] neg_lo:[0,1] neg_hi:[0,1]
	v_mfma_f32_16x16x32_bf16 v[130:133], v[146:149], v[4:7], v[130:133]
	v_cvt_pk_bf16_f32 v140, v76, v77
	v_lshlrev_b32_e32 v76, 16, v149
	v_and_b32_e32 v77, 0xffff0000, v149
	v_pk_add_f32 v[76:77], v[144:145], v[76:77] neg_lo:[0,1] neg_hi:[0,1]
	v_mfma_f32_16x16x32_bf16 v[134:137], v[146:149], v[0:3], v[134:137]
	v_cvt_pk_bf16_f32 v141, v76, v77
	s_nop 1
	v_mfma_f32_16x16x32_bf16 v[130:133], v[138:141], v[0:3], v[130:133]
	s_nop 7
	v_pk_add_f32 v[100:101], v[134:135], v[130:131]
	v_pk_add_f32 v[76:77], v[136:137], v[132:133]
	v_fma_f32 v100, v79, v103, v100
	v_mul_f32_e32 v103, 0x3d372713, v100
	v_mul_f32_e32 v103, v100, v103
	v_fma_f32 v103, v100, v103, v100
	v_mul_f32_e32 v103, 0x3f4c422a, v103
	v_add_f32_e32 v103, v103, v103
	v_mul_f32_e32 v103, 0x3fb8aa3b, v103
	v_exp_f32_e32 v103, v103
	v_mul_f32_e32 v100, 0.5, v100
	v_mfma_f32_16x16x32_bf16 v[130:133], v[70:73], v[62:65], 0
	v_add_f32_e32 v103, 1.0, v103
	v_rcp_f32_e32 v103, v103
	v_mfma_f32_16x16x32_bf16 v[62:65], v[66:69], v[62:65], 0
	v_fma_f32 v103, v103, -2.0, 1.0
	v_add_f32_e32 v103, 1.0, v103
	v_mul_f32_e32 v100, v100, v103
	v_cvt_pk_bf16_f32 v100, v100, s0
	ds_write_b16 v102, v100 offset:16640
	s_waitcnt vmcnt(2)
	v_lshlrev_b32_e32 v100, 16, v129
	v_fmac_f32_e32 v101, v79, v100
	v_mul_f32_e32 v100, 0x3d372713, v101
	v_mul_f32_e32 v100, v101, v100
	v_fma_f32 v100, v101, v100, v101
	v_mul_f32_e32 v100, 0x3f4c422a, v100
	v_add_f32_e32 v100, v100, v100
	v_mul_f32_e32 v100, 0x3fb8aa3b, v100
	v_exp_f32_e32 v100, v100
	v_mul_f32_e32 v101, 0.5, v101
	v_add_f32_e32 v100, 1.0, v100
	v_rcp_f32_e32 v100, v100
	s_nop 0
	v_fma_f32 v100, v100, -2.0, 1.0
	v_add_f32_e32 v100, 1.0, v100
	v_mul_f32_e32 v100, v101, v100
	v_cvt_pk_bf16_f32 v100, v100, s0
	ds_write_b16 v102, v100 offset:17680
	s_waitcnt vmcnt(1)
	v_lshlrev_b32_e32 v100, 16, v158
	v_fma_f32 v76, v79, v100, v76
	v_mul_f32_e32 v100, 0x3d372713, v76
	v_mul_f32_e32 v100, v76, v100
	v_fma_f32 v100, v76, v100, v76
	v_mul_f32_e32 v100, 0x3f4c422a, v100
	v_add_f32_e32 v100, v100, v100
	v_mul_f32_e32 v100, 0x3fb8aa3b, v100
	v_exp_f32_e32 v100, v100
	v_mul_f32_e32 v76, 0.5, v76
	v_add_f32_e32 v100, 1.0, v100
	v_rcp_f32_e32 v100, v100
	s_nop 0
	v_fma_f32 v100, v100, -2.0, 1.0
	v_add_f32_e32 v100, 1.0, v100
	v_mul_f32_e32 v76, v76, v100
	v_cvt_pk_bf16_f32 v76, v76, s0
	ds_write_b16 v102, v76 offset:18720
	s_waitcnt vmcnt(0)
	v_lshlrev_b32_e32 v76, 16, v159
	v_fmac_f32_e32 v77, v79, v76
	v_mul_f32_e32 v76, 0x3d372713, v77
	v_mul_f32_e32 v76, v77, v76
	v_fma_f32 v76, v77, v76, v77
	v_mul_f32_e32 v76, 0x3f4c422a, v76
	v_add_f32_e32 v76, v76, v76
	v_mul_f32_e32 v76, 0x3fb8aa3b, v76
	v_exp_f32_e32 v76, v76
	v_mul_f32_e32 v77, 0.5, v77
	v_add_f32_e32 v76, 1.0, v76
	v_rcp_f32_e32 v76, v76
	s_nop 0
	v_fma_f32 v76, v76, -2.0, 1.0
	v_add_f32_e32 v76, 1.0, v76
	v_mul_f32_e32 v76, v77, v76
	v_cvt_pk_bf16_f32 v76, v76, s0
	ds_write_b16 v102, v76 offset:19760
	s_waitcnt lgkmcnt(0)
; #define S5_LDS_FENCE() do { __builtin_amdgcn_wave_barrier(); asm volatile("s_waitcnt lgkmcnt(0)" ::: "memory"); } while (0)
; template <bool WRITEH>
; __device__ __forceinline__ void s5_block(const S5Coef& C, const bf16x8 (&bm)[8], u32x4 uw, float* Hs, int lane, float& hr, float& hi) {
;     const bf16x8 ua = __builtin_bit_cast(bf16x8, uw);
; #pragma unroll
;     for (int nb = 0; nb < 8; ++nb) { const f32x4 d = __builtin_amdgcn_mfma_f32_16x16x32_bf16(ua, bm[nb], (f32x4){0.f, 0.f, 0.f, 0.f}, 0, 0, 0);
; #pragma unroll
;         for (int i = 0; i < 4; ++i) Hs[(4 * (lane >> 4) + i) * 132 + 16 * nb + (lane & 15)] = d[i]; }
;     S5_LDS_FENCE();
;     float bur[16], bui[16];
; #pragma unroll
;     for (int tl = 0; tl < 16; ++tl) { bur[tl] = Hs[tl * 132 + lane]; bui[tl] = Hs[tl * 132 + 64 + lane]; }
; #pragma unroll
;     for (int tl = 0; tl < 16; ++tl) { const float nr = C.ar * hr - C.ai * hi + bur[tl], ni = C.ar * hi + C.ai * hr + bui[tl]; hr = nr; hi = ni; bur[tl] = hr; bui[tl] = hi; }
	ds_write_b32 v106, v130
	ds_write_b32 v106, v131 offset:528
	ds_write_b32 v106, v132 offset:1056
	ds_write_b32 v107, v133
	v_mfma_f32_16x16x32_bf16 v[130:133], v[70:73], v[58:61], 0
	s_nop 7
	ds_write_b32 v106, v130 offset:64
	ds_write_b32 v106, v131 offset:592
	ds_write_b32 v106, v132 offset:1120
	ds_write_b32 v107, v133 offset:64
	v_mfma_f32_16x16x32_bf16 v[130:133], v[70:73], v[54:57], 0
	s_nop 7
	ds_write_b32 v106, v130 offset:128
	ds_write_b32 v106, v131 offset:656
	ds_write_b32 v106, v132 offset:1184
	ds_write_b32 v107, v133 offset:128
	v_mfma_f32_16x16x32_bf16 v[130:133], v[70:73], v[50:53], 0
	s_nop 7
	ds_write2_b32 v108, v130, v131 offset1:132
	ds_write_b32 v108, v132 offset:1056
	ds_write_b32 v109, v133
	v_mfma_f32_16x16x32_bf16 v[130:133], v[70:73], v[46:49], 0
	s_nop 7
	ds_write_b32 v106, v130 offset:256
	ds_write_b32 v106, v131 offset:784
	ds_write_b32 v106, v132 offset:1312
	ds_write_b32 v107, v133 offset:256
	v_mfma_f32_16x16x32_bf16 v[130:133], v[70:73], v[42:45], 0
	s_nop 7
	ds_write_b32 v106, v130 offset:320
	ds_write_b32 v106, v131 offset:848
	ds_write_b32 v106, v132 offset:1376
	ds_write_b32 v107, v133 offset:320
	v_mfma_f32_16x16x32_bf16 v[130:133], v[70:73], v[38:41], 0
	v_lshl_add_u64 v[76:77], s[2:3], 0, v[82:83]
	s_nop 6
	ds_write_b32 v106, v130 offset:384
	ds_write_b32 v106, v131 offset:912
	ds_write_b32 v106, v132 offset:1440
	ds_write_b32 v107, v133 offset:384
	v_mfma_f32_16x16x32_bf16 v[70:73], v[70:73], v[34:37], 0
	s_nop 7
	ds_write2_b32 v110, v70, v71 offset1:132
	ds_write_b32 v110, v72 offset:1056
	ds_write_b32 v111, v73
	v_add_co_u32_e32 v70, vcc, s12, v76
	v_mfma_f32_16x16x32_bf16 v[58:61], v[66:69], v[58:61], 0
	s_nop 0
	v_addc_co_u32_e32 v71, vcc, 0, v77, vcc
	global_load_ushort v103, v[70:71], off
	v_add_co_u32_e32 v70, vcc, s13, v76
	v_mfma_f32_16x16x32_bf16 v[54:57], v[66:69], v[54:57], 0
	s_nop 0
	v_addc_co_u32_e32 v71, vcc, 0, v77, vcc
	global_load_ushort v129, v[70:71], off offset:512
	v_add_co_u32_e32 v70, vcc, s33, v76
	v_mfma_f32_16x16x32_bf16 v[50:53], v[66:69], v[50:53], 0
	s_nop 0
	v_addc_co_u32_e32 v71, vcc, 0, v77, vcc
	global_load_ushort v154, v[70:71], off offset:1024
	v_add_co_u32_e32 v70, vcc, s28, v76
	v_mfma_f32_16x16x32_bf16 v[46:49], v[66:69], v[46:49], 0
	s_nop 0
	v_addc_co_u32_e32 v71, vcc, 0, v77, vcc
	global_load_ushort v155, v[70:71], off offset:1536
	s_waitcnt lgkmcnt(0)
	ds_read2st64_b32 v[70:71], v112 offset1:1
	ds_read2_b32 v[72:73], v112 offset0:132 offset1:196
	ds_read2st64_b32 v[76:77], v115 offset0:4 offset1:5
	ds_read2st64_b32 v[100:101], v116 offset0:6 offset1:7
	ds_read2st64_b32 v[130:131], v117 offset0:8 offset1:9
	ds_read2st64_b32 v[132:133], v118 offset0:10 offset1:11
	ds_read2st64_b32 v[134:135], v119 offset0:12 offset1:13
	ds_read2st64_b32 v[136:137], v120 offset0:14 offset1:15
	ds_read2st64_b32 v[138:139], v121 offset0:16 offset1:17
	ds_read2st64_b32 v[140:141], v122 offset0:18 offset1:19
	ds_read2st64_b32 v[142:143], v123 offset0:20 offset1:21
	ds_read2st64_b32 v[144:145], v124 offset0:22 offset1:23
	ds_read2st64_b32 v[146:147], v125 offset0:24 offset1:25
	ds_read2st64_b32 v[148:149], v126 offset0:26 offset1:27
	ds_read2st64_b32 v[150:151], v127 offset0:28 offset1:29
	ds_read2st64_b32 v[152:153], v128 offset0:30 offset1:31
	s_waitcnt lgkmcnt(14)
	v_add_f32_e32 v156, v156, v70
	v_mul_f32_e32 v70, v32, v75
	v_fmac_f32_e32 v70, v33, v74
	v_add_f32_e32 v74, v70, v71
	v_mul_f32_e32 v70, v33, v74
	v_fma_f32 v70, v32, v156, -v70
	v_add_f32_e32 v72, v72, v70
	v_mul_f32_e32 v70, v32, v74
	v_fmac_f32_e32 v70, v33, v156
	v_add_f32_e32 v73, v73, v70
	v_mul_f32_e32 v70, v33, v73
	v_fma_f32 v70, v32, v72, -v70
	s_waitcnt lgkmcnt(13)
	v_add_f32_e32 v75, v76, v70
	v_mul_f32_e32 v70, v32, v73
	v_fmac_f32_e32 v70, v33, v72
	v_add_f32_e32 v76, v77, v70
	v_mul_f32_e32 v70, v33, v76
	v_fma_f32 v70, v32, v75, -v70
	s_waitcnt lgkmcnt(12)
	v_add_f32_e32 v77, v100, v70
	v_mul_f32_e32 v70, v32, v76
	v_fmac_f32_e32 v70, v33, v75
	v_add_f32_e32 v100, v101, v70
	v_mul_f32_e32 v70, v33, v100
	v_fma_f32 v70, v32, v77, -v70
	s_waitcnt lgkmcnt(11)
	v_add_f32_e32 v101, v130, v70
	v_mul_f32_e32 v70, v32, v100
	v_fmac_f32_e32 v70, v33, v77
	v_add_f32_e32 v130, v131, v70
	v_mul_f32_e32 v70, v33, v130
	v_fma_f32 v70, v32, v101, -v70
	s_waitcnt lgkmcnt(10)
	v_add_f32_e32 v131, v132, v70
	v_mul_f32_e32 v70, v32, v130
	v_fmac_f32_e32 v70, v33, v101
	v_add_f32_e32 v132, v133, v70
	v_mul_f32_e32 v70, v33, v132
	v_fma_f32 v70, v32, v131, -v70
	s_waitcnt lgkmcnt(9)
	v_add_f32_e32 v133, v134, v70
	v_mul_f32_e32 v70, v32, v132
	v_fmac_f32_e32 v70, v33, v131
	v_add_f32_e32 v134, v135, v70
	v_mul_f32_e32 v70, v33, v134
	v_fma_f32 v70, v32, v133, -v70
	s_waitcnt lgkmcnt(8)
	v_add_f32_e32 v135, v136, v70
	v_mul_f32_e32 v70, v32, v134
	v_fmac_f32_e32 v70, v33, v133
	v_add_f32_e32 v136, v137, v70
	v_mul_f32_e32 v70, v33, v136
	v_fma_f32 v70, v32, v135, -v70
	s_waitcnt lgkmcnt(7)
	v_add_f32_e32 v137, v138, v70
	v_mul_f32_e32 v70, v32, v136
	v_fmac_f32_e32 v70, v33, v135
	v_add_f32_e32 v138, v139, v70
	v_mul_f32_e32 v70, v33, v138
	v_fma_f32 v70, v32, v137, -v70
	s_waitcnt lgkmcnt(6)
	v_add_f32_e32 v139, v140, v70
	v_mul_f32_e32 v70, v32, v138
	v_fmac_f32_e32 v70, v33, v137
	v_add_f32_e32 v140, v141, v70
	v_mul_f32_e32 v70, v33, v140
	v_fma_f32 v70, v32, v139, -v70
	s_waitcnt lgkmcnt(5)
	v_add_f32_e32 v141, v142, v70
	v_mul_f32_e32 v70, v32, v140
	v_fmac_f32_e32 v70, v33, v139
	v_add_f32_e32 v142, v143, v70
	v_mul_f32_e32 v70, v33, v142
	v_fma_f32 v70, v32, v141, -v70
	s_waitcnt lgkmcnt(4)
	v_add_f32_e32 v143, v144, v70
	v_mul_f32_e32 v70, v32, v142
	v_fmac_f32_e32 v70, v33, v141
	v_add_f32_e32 v144, v145, v70
	v_mul_f32_e32 v70, v33, v144
	v_fma_f32 v70, v32, v143, -v70
	s_waitcnt lgkmcnt(3)
; __device__ __forceinline__ unsigned cvt_pk(float lo, float hi) { f32x2_t v = {lo, hi}; bf16x2_t b = __builtin_convertvector(v, bf16x2_t); return __builtin_bit_cast(unsigned, b); }
; __device__ __forceinline__ float bflo(unsigned w) { return __uint_as_float(w << 16); }
; __device__ __forceinline__ float bfhi(unsigned w) { return __uint_as_float(w & 0xffff0000u); }
; #define S5_LDS_FENCE() do { __builtin_amdgcn_wave_barrier(); asm volatile("s_waitcnt lgkmcnt(0)" ::: "memory"); } while (0)
; template <bool WRITEH>
; __device__ __forceinline__ void s5_block(const S5Coef& C, const bf16x8 (&bm)[8], u32x4 uw, float* Hs, int lane, float& hr, float& hi) {
;     ...
;     for (int tl = 0; tl < 16; ++tl) { bur[tl] = Hs[tl * 132 + lane]; bui[tl] = Hs[tl * 132 + 64 + lane]; }
; #pragma unroll
;     for (int tl = 0; tl < 16; ++tl) { const float nr = C.ar * hr - C.ai * hi + bur[tl], ni = C.ar * hi + C.ai * hr + bui[tl]; hr = nr; hi = ni; bur[tl] = hr; bui[tl] = hi; }
;     if (WRITEH) {
; #pragma unroll
;         for (int tl = 0; tl < 16; ++tl) { Hs[tl * 132 + lane] = bur[tl]; Hs[tl * 132 + 64 + lane] = bui[tl]; }
;     }
;     S5_LDS_FENCE();
; }
; __device__ __forceinline__ void s5_unit(ArgsP A, int l, int unit, unsigned char* lds, int wave_, int lane_) {
;     ...
;             for (int ks = 0; ks < 4; ++ks) { const float* hp = Hs + (lane & 15) * 132 + 32 * ks + 8 * (lane >> 4); const f32x4 h0 = *(const f32x4*)hp, h1 = *(const f32x4*)(hp + 4);
;                 u32x4 wh; wh.x = cvt_pk(h0[0], h0[1]); wh.y = cvt_pk(h0[2], h0[3]); wh.z = cvt_pk(h1[0], h1[1]); wh.w = cvt_pk(h1[2], h1[3]);
;                 u32x4 wl; wl.x = cvt_pk(h0[0] - bflo(wh.x), h0[1] - bfhi(wh.x)); wl.y = cvt_pk(h0[2] - bflo(wh.y), h0[3] - bfhi(wh.y)); wl.z = cvt_pk(h1[0] - bflo(wh.z), h1[1] - bfhi(wh.z)); wl.w = cvt_pk(h1[2] - bflo(wh.w), h1[3] - bfhi(wh.w));
;                 const bf16x8 hh_ = __builtin_bit_cast(bf16x8, wh), hl_ = __builtin_bit_cast(bf16x8, wl);
;                 y = __builtin_amdgcn_mfma_f32_16x16x32_bf16(hh_, chl[2 * ks], y, 0, 0, 0); y2 = __builtin_amdgcn_mfma_f32_16x16x32_bf16(hh_, chl[2 * ks + 1], y2, 0, 0, 0);
;                 y2 = __builtin_amdgcn_mfma_f32_16x16x32_bf16(hl_, chl[2 * ks], y2, 0, 0, 0); }
	v_add_f32_e32 v145, v146, v70
	v_mul_f32_e32 v70, v32, v144
	v_fmac_f32_e32 v70, v33, v143
	v_add_f32_e32 v146, v147, v70
	v_mul_f32_e32 v70, v33, v146
	v_fma_f32 v70, v32, v145, -v70
	s_waitcnt lgkmcnt(2)
	v_add_f32_e32 v147, v148, v70
	v_mul_f32_e32 v70, v32, v146
	v_fmac_f32_e32 v70, v33, v145
	v_add_f32_e32 v148, v149, v70
	v_mul_f32_e32 v70, v33, v148
	v_fma_f32 v70, v32, v147, -v70
	s_waitcnt lgkmcnt(1)
	v_add_f32_e32 v149, v150, v70
	v_mul_f32_e32 v70, v32, v148
	v_fmac_f32_e32 v70, v33, v147
	v_add_f32_e32 v150, v151, v70
	v_mul_f32_e32 v70, v33, v150
	v_mul_f32_e32 v71, v32, v150
	v_fma_f32 v70, v32, v149, -v70
	v_fmac_f32_e32 v71, v33, v149
	s_waitcnt lgkmcnt(0)
	v_add_f32_e32 v70, v152, v70
	v_add_f32_e32 v71, v153, v71
	ds_write2st64_b32 v112, v156, v74 offset1:1
	ds_write2_b32 v112, v72, v73 offset0:132 offset1:196
	ds_write2st64_b32 v115, v75, v76 offset0:4 offset1:5
	ds_write2st64_b32 v116, v77, v100 offset0:6 offset1:7
	ds_write2st64_b32 v117, v101, v130 offset0:8 offset1:9
	ds_write2st64_b32 v118, v131, v132 offset0:10 offset1:11
	ds_write2st64_b32 v119, v133, v134 offset0:12 offset1:13
	ds_write2st64_b32 v120, v135, v136 offset0:14 offset1:15
	ds_write2st64_b32 v121, v137, v138 offset0:16 offset1:17
	ds_write2st64_b32 v122, v139, v140 offset0:18 offset1:19
	ds_write2st64_b32 v123, v141, v142 offset0:20 offset1:21
	ds_write2st64_b32 v124, v143, v144 offset0:22 offset1:23
	ds_write2st64_b32 v125, v145, v146 offset0:24 offset1:25
	ds_write2st64_b32 v126, v147, v148 offset0:26 offset1:27
	ds_write2st64_b32 v127, v149, v150 offset0:28 offset1:29
	ds_write2st64_b32 v128, v70, v71 offset0:30 offset1:31
	s_waitcnt lgkmcnt(0)
	ds_read_b128 v[72:75], v113
	ds_read_b128 v[130:133], v113 offset:16
	v_mfma_f32_16x16x32_bf16 v[42:45], v[66:69], v[42:45], 0
	v_lshl_add_u64 v[82:83], v[82:83], 0, 32
	s_waitcnt lgkmcnt(1)
	v_cvt_pk_bf16_f32 v134, v72, v73
	v_cvt_pk_bf16_f32 v135, v74, v75
	v_lshlrev_b32_e32 v76, 16, v134
	v_and_b32_e32 v77, 0xffff0000, v134
	s_waitcnt lgkmcnt(0)
	v_cvt_pk_bf16_f32 v136, v130, v131
	v_cvt_pk_bf16_f32 v137, v132, v133
	v_pk_add_f32 v[72:73], v[72:73], v[76:77] neg_lo:[0,1] neg_hi:[0,1]
	v_lshlrev_b32_e32 v76, 16, v135
	v_and_b32_e32 v77, 0xffff0000, v135
	v_pk_add_f32 v[74:75], v[74:75], v[76:77] neg_lo:[0,1] neg_hi:[0,1]
	v_cvt_pk_bf16_f32 v72, v72, v73
	v_cvt_pk_bf16_f32 v73, v74, v75
	v_lshlrev_b32_e32 v74, 16, v136
	v_and_b32_e32 v75, 0xffff0000, v136
	v_lshlrev_b32_e32 v76, 16, v137
	v_and_b32_e32 v77, 0xffff0000, v137
	v_pk_add_f32 v[74:75], v[130:131], v[74:75] neg_lo:[0,1] neg_hi:[0,1]
	v_pk_add_f32 v[76:77], v[132:133], v[76:77] neg_lo:[0,1] neg_hi:[0,1]
	v_cvt_pk_bf16_f32 v74, v74, v75
	v_cvt_pk_bf16_f32 v75, v76, v77
	v_mfma_f32_16x16x32_bf16 v[130:133], v[134:137], v[24:27], 0
	v_mfma_f32_16x16x32_bf16 v[134:137], v[134:137], v[28:31], 0
	v_mfma_f32_16x16x32_bf16 v[72:75], v[72:75], v[24:27], v[134:137]
	s_nop 6
	ds_read_b128 v[134:137], v113 offset:128
	ds_read_b128 v[138:141], v113 offset:144
	s_waitcnt lgkmcnt(1)
	v_cvt_pk_bf16_f32 v142, v134, v135
	v_lshlrev_b32_e32 v76, 16, v142
	v_and_b32_e32 v77, 0xffff0000, v142
	v_cvt_pk_bf16_f32 v143, v136, v137
	v_pk_add_f32 v[76:77], v[134:135], v[76:77] neg_lo:[0,1] neg_hi:[0,1]
	s_waitcnt lgkmcnt(0)
	v_cvt_pk_bf16_f32 v144, v138, v139
	v_cvt_pk_bf16_f32 v134, v76, v77
	v_lshlrev_b32_e32 v76, 16, v143
	v_and_b32_e32 v77, 0xffff0000, v143
	v_pk_add_f32 v[76:77], v[136:137], v[76:77] neg_lo:[0,1] neg_hi:[0,1]
	v_cvt_pk_bf16_f32 v145, v140, v141
	v_cvt_pk_bf16_f32 v135, v76, v77
	v_lshlrev_b32_e32 v76, 16, v144
	v_and_b32_e32 v77, 0xffff0000, v144
	v_pk_add_f32 v[76:77], v[138:139], v[76:77] neg_lo:[0,1] neg_hi:[0,1]
	v_mfma_f32_16x16x32_bf16 v[72:75], v[142:145], v[20:23], v[72:75]
	v_cvt_pk_bf16_f32 v136, v76, v77
	v_lshlrev_b32_e32 v76, 16, v145
	v_and_b32_e32 v77, 0xffff0000, v145
	v_pk_add_f32 v[76:77], v[140:141], v[76:77] neg_lo:[0,1] neg_hi:[0,1]
	v_mfma_f32_16x16x32_bf16 v[130:133], v[142:145], v[16:19], v[130:133]
	v_cvt_pk_bf16_f32 v137, v76, v77
	s_nop 1
	v_mfma_f32_16x16x32_bf16 v[72:75], v[134:137], v[16:19], v[72:75]
	ds_read_b128 v[134:137], v113 offset:256
	ds_read_b128 v[138:141], v113 offset:272
	s_waitcnt lgkmcnt(1)
	v_cvt_pk_bf16_f32 v142, v134, v135
	v_lshlrev_b32_e32 v76, 16, v142
	v_and_b32_e32 v77, 0xffff0000, v142
	v_cvt_pk_bf16_f32 v143, v136, v137
	v_pk_add_f32 v[76:77], v[134:135], v[76:77] neg_lo:[0,1] neg_hi:[0,1]
	s_waitcnt lgkmcnt(0)
	v_cvt_pk_bf16_f32 v144, v138, v139
	v_cvt_pk_bf16_f32 v134, v76, v77
	v_lshlrev_b32_e32 v76, 16, v143
	v_and_b32_e32 v77, 0xffff0000, v143
	v_pk_add_f32 v[76:77], v[136:137], v[76:77] neg_lo:[0,1] neg_hi:[0,1]
	v_cvt_pk_bf16_f32 v145, v140, v141
	v_cvt_pk_bf16_f32 v135, v76, v77
	v_lshlrev_b32_e32 v76, 16, v144
	v_and_b32_e32 v77, 0xffff0000, v144
	v_pk_add_f32 v[76:77], v[138:139], v[76:77] neg_lo:[0,1] neg_hi:[0,1]
	v_mfma_f32_16x16x32_bf16 v[72:75], v[142:145], v[12:15], v[72:75]
	v_cvt_pk_bf16_f32 v136, v76, v77
	v_lshlrev_b32_e32 v76, 16, v145
	v_and_b32_e32 v77, 0xffff0000, v145
	v_pk_add_f32 v[76:77], v[140:141], v[76:77] neg_lo:[0,1] neg_hi:[0,1]
	v_mfma_f32_16x16x32_bf16 v[130:133], v[142:145], v[8:11], v[130:133]
	v_cvt_pk_bf16_f32 v137, v76, v77
	s_nop 1
	v_mfma_f32_16x16x32_bf16 v[72:75], v[134:137], v[8:11], v[72:75]
	ds_read_b128 v[134:137], v113 offset:384
	ds_read_b128 v[138:141], v113 offset:400
	s_waitcnt lgkmcnt(1)
	v_cvt_pk_bf16_f32 v142, v134, v135
	v_lshlrev_b32_e32 v76, 16, v142
	v_and_b32_e32 v77, 0xffff0000, v142
	v_cvt_pk_bf16_f32 v143, v136, v137
	v_pk_add_f32 v[76:77], v[134:135], v[76:77] neg_lo:[0,1] neg_hi:[0,1]
	s_waitcnt lgkmcnt(0)
; __device__ __forceinline__ float bf2f(unsigned short h) { return __uint_as_float(((unsigned)h) << 16); }
; template <bool WRITEH>
; __device__ __forceinline__ void s5_block(const S5Coef& C, const bf16x8 (&bm)[8], u32x4 uw, float* Hs, int lane, float& hr, float& hi) {
;     const bf16x8 ua = __builtin_bit_cast(bf16x8, uw);
; #pragma unroll
;     for (int nb = 0; nb < 8; ++nb) { const f32x4 d = __builtin_amdgcn_mfma_f32_16x16x32_bf16(ua, bm[nb], (f32x4){0.f, 0.f, 0.f, 0.f}, 0, 0, 0);
; #pragma unroll
;         for (int i = 0; i < 4; ++i) Hs[(4 * (lane >> 4) + i) * 132 + 16 * nb + (lane & 15)] = d[i]; }
;     S5_LDS_FENCE();
;     float bur[16], bui[16];
; #pragma unroll
;     for (int tl = 0; tl < 16; ++tl) { bur[tl] = Hs[tl * 132 + lane]; bui[tl] = Hs[tl * 132 + 64 + lane]; }
; #pragma unroll
;     for (int tl = 0; tl < 16; ++tl) { const float nr = C.ar * hr - C.ai * hi + bur[tl], ni = C.ar * hi + C.ai * hr + bui[tl]; hr = nr; hi = ni; bur[tl] = hr; bui[tl] = hi; }
; __device__ __forceinline__ void s5_unit(ArgsP A, int l, int unit, unsigned char* lds, int wave_, int lane_) {
;     ...
;             for (int ks = 0; ks < 4; ++ks) { const float* hp = Hs + (lane & 15) * 132 + 32 * ks + 8 * (lane >> 4); const f32x4 h0 = *(const f32x4*)hp, h1 = *(const f32x4*)(hp + 4);
;                 u32x4 wh; wh.x = cvt_pk(h0[0], h0[1]); wh.y = cvt_pk(h0[2], h0[3]); wh.z = cvt_pk(h1[0], h1[1]); wh.w = cvt_pk(h1[2], h1[3]);
;                 u32x4 wl; wl.x = cvt_pk(h0[0] - bflo(wh.x), h0[1] - bfhi(wh.x)); wl.y = cvt_pk(h0[2] - bflo(wh.y), h0[3] - bfhi(wh.y)); wl.z = cvt_pk(h1[0] - bflo(wh.z), h1[1] - bfhi(wh.z)); wl.w = cvt_pk(h1[2] - bflo(wh.w), h1[3] - bfhi(wh.w));
;                 const bf16x8 hh_ = __builtin_bit_cast(bf16x8, wh), hl_ = __builtin_bit_cast(bf16x8, wl);
;                 y = __builtin_amdgcn_mfma_f32_16x16x32_bf16(hh_, chl[2 * ks], y, 0, 0, 0); y2 = __builtin_amdgcn_mfma_f32_16x16x32_bf16(hh_, chl[2 * ks + 1], y2, 0, 0, 0);
;                 y2 = __builtin_amdgcn_mfma_f32_16x16x32_bf16(hl_, chl[2 * ks], y2, 0, 0, 0); }
;             y = y + y2;
; #pragma unroll
;             for (int i = 0; i < 4; ++i) { const int t = 16 * blk + 4 * (lane >> 4) + i; const int col = 16 * g + (lane & 15);
;                 const float uval = bf2f(uraw[i]); const float v = gelu_tanh(y[i] + dv * uval); ys[t * YS_STRIDE + col] = f2bf(v); }
	v_cvt_pk_bf16_f32 v144, v138, v139
	v_cvt_pk_bf16_f32 v134, v76, v77
	v_lshlrev_b32_e32 v76, 16, v143
	v_and_b32_e32 v77, 0xffff0000, v143
	v_pk_add_f32 v[76:77], v[136:137], v[76:77] neg_lo:[0,1] neg_hi:[0,1]
	v_cvt_pk_bf16_f32 v145, v140, v141
	v_cvt_pk_bf16_f32 v135, v76, v77
	v_lshlrev_b32_e32 v76, 16, v144
	v_and_b32_e32 v77, 0xffff0000, v144
	v_pk_add_f32 v[76:77], v[138:139], v[76:77] neg_lo:[0,1] neg_hi:[0,1]
	v_mfma_f32_16x16x32_bf16 v[72:75], v[142:145], v[4:7], v[72:75]
	v_cvt_pk_bf16_f32 v136, v76, v77
	v_lshlrev_b32_e32 v76, 16, v145
	v_and_b32_e32 v77, 0xffff0000, v145
	v_pk_add_f32 v[76:77], v[140:141], v[76:77] neg_lo:[0,1] neg_hi:[0,1]
	v_mfma_f32_16x16x32_bf16 v[130:133], v[142:145], v[0:3], v[130:133]
	v_cvt_pk_bf16_f32 v137, v76, v77
	s_waitcnt vmcnt(3)
	v_lshlrev_b32_e32 v76, 16, v103
	v_mfma_f32_16x16x32_bf16 v[72:75], v[134:137], v[0:3], v[72:75]
	v_mfma_f32_16x16x32_bf16 v[38:41], v[66:69], v[38:41], 0
	s_nop 6
	v_add_f32_e64 v72, v130, v72
	v_add_f32_e64 v73, v131, v73
	v_pk_add_f32 v[74:75], v[132:133], v[74:75]
	v_fma_f32 v72, v79, v76, v72
	v_mul_f32_e32 v76, 0x3d372713, v72
	v_mul_f32_e32 v76, v72, v76
	v_fma_f32 v76, v72, v76, v72
	v_mul_f32_e32 v76, 0x3f4c422a, v76
	v_add_f32_e32 v76, v76, v76
	v_mul_f32_e32 v76, 0x3fb8aa3b, v76
	v_exp_f32_e32 v76, v76
	v_mul_f32_e32 v72, 0.5, v72
	v_mfma_f32_16x16x32_bf16 v[34:37], v[66:69], v[34:37], 0
	v_add_f32_e32 v76, 1.0, v76
	v_rcp_f32_e32 v76, v76
	s_nop 0
	v_fma_f32 v76, v76, -2.0, 1.0
	v_add_f32_e32 v76, 1.0, v76
	v_mul_f32_e32 v72, v72, v76
	v_cvt_pk_bf16_f32 v72, v72, s0
	ds_write_b16 v102, v72 offset:33280
	s_waitcnt vmcnt(2)
	v_lshlrev_b32_e32 v72, 16, v129
	v_fmac_f32_e32 v73, v79, v72
	v_mul_f32_e32 v72, 0x3d372713, v73
	v_mul_f32_e32 v72, v73, v72
	v_fma_f32 v72, v73, v72, v73
	v_mul_f32_e32 v72, 0x3f4c422a, v72
	v_add_f32_e32 v72, v72, v72
	v_mul_f32_e32 v72, 0x3fb8aa3b, v72
	v_exp_f32_e32 v72, v72
	v_mul_f32_e32 v73, 0.5, v73
	v_add_f32_e32 v72, 1.0, v72
	v_rcp_f32_e32 v72, v72
	s_nop 0
	v_fma_f32 v72, v72, -2.0, 1.0
	v_add_f32_e32 v72, 1.0, v72
	v_mul_f32_e32 v72, v73, v72
	v_cvt_pk_bf16_f32 v72, v72, s0
	ds_write_b16 v102, v72 offset:34320
	s_waitcnt vmcnt(1)
	v_lshlrev_b32_e32 v72, 16, v154
	v_fma_f32 v72, v79, v72, v74
	v_mul_f32_e32 v73, 0x3d372713, v72
	v_mul_f32_e32 v73, v72, v73
	v_fma_f32 v73, v72, v73, v72
	v_mul_f32_e32 v73, 0x3f4c422a, v73
	v_add_f32_e32 v73, v73, v73
	v_mul_f32_e32 v73, 0x3fb8aa3b, v73
	v_exp_f32_e32 v73, v73
	v_mul_f32_e32 v72, 0.5, v72
	v_add_f32_e32 v73, 1.0, v73
	v_rcp_f32_e32 v73, v73
	s_nop 0
	v_fma_f32 v73, v73, -2.0, 1.0
	v_add_f32_e32 v73, 1.0, v73
	v_mul_f32_e32 v72, v72, v73
	v_cvt_pk_bf16_f32 v72, v72, s0
	ds_write_b16 v102, v72 offset:35360
	s_waitcnt vmcnt(0)
	v_lshlrev_b32_e32 v72, 16, v155
	v_fmac_f32_e32 v75, v79, v72
	v_mul_f32_e32 v72, 0x3d372713, v75
	v_mul_f32_e32 v72, v75, v72
	v_fma_f32 v72, v75, v72, v75
	v_mul_f32_e32 v72, 0x3f4c422a, v72
	v_add_f32_e32 v72, v72, v72
	v_mul_f32_e32 v72, 0x3fb8aa3b, v72
	v_exp_f32_e32 v72, v72
	v_mul_f32_e32 v73, 0.5, v75
	v_add_f32_e32 v72, 1.0, v72
	v_rcp_f32_e32 v72, v72
	s_nop 0
	v_fma_f32 v72, v72, -2.0, 1.0
	v_add_f32_e32 v72, 1.0, v72
	v_mul_f32_e32 v72, v73, v72
	v_cvt_pk_bf16_f32 v72, v72, s0
	ds_write_b16 v102, v72 offset:36400
	v_lshl_add_u64 v[72:73], s[2:3], 0, v[80:81]
	s_waitcnt lgkmcnt(0)
	ds_write_b32 v106, v62
	ds_write_b32 v106, v63 offset:528
	ds_write_b32 v106, v64 offset:1056
	ds_write_b32 v107, v65
	ds_write_b32 v106, v58 offset:64
	ds_write_b32 v106, v59 offset:592
	ds_write_b32 v106, v60 offset:1120
	ds_write_b32 v107, v61 offset:64
	ds_write_b32 v106, v54 offset:128
	ds_write_b32 v106, v55 offset:656
	ds_write_b32 v106, v56 offset:1184
	ds_write_b32 v107, v57 offset:128
	ds_write2_b32 v108, v50, v51 offset1:132
	ds_write_b32 v108, v52 offset:1056
	ds_write_b32 v109, v53
	ds_write_b32 v106, v46 offset:256
	ds_write_b32 v106, v47 offset:784
	ds_write_b32 v106, v48 offset:1312
	ds_write_b32 v107, v49 offset:256
	ds_write_b32 v106, v42 offset:320
	ds_write_b32 v106, v43 offset:848
	ds_write_b32 v106, v44 offset:1376
	ds_write_b32 v107, v45 offset:320
	ds_write_b32 v106, v38 offset:384
	ds_write_b32 v106, v39 offset:912
	ds_write_b32 v106, v40 offset:1440
	ds_write_b32 v107, v41 offset:384
	ds_write2_b32 v110, v34, v35 offset1:132
	ds_write_b32 v110, v36 offset:1056
	ds_write_b32 v111, v37
	v_add_co_u32_e32 v34, vcc, s12, v72
	v_lshl_add_u64 v[80:81], v[80:81], 0, 32
	s_nop 0
	v_addc_co_u32_e32 v35, vcc, 0, v73, vcc
	global_load_ushort v66, v[34:35], off
	v_add_co_u32_e32 v34, vcc, s13, v72
	s_nop 1
	v_addc_co_u32_e32 v35, vcc, 0, v73, vcc
	global_load_ushort v67, v[34:35], off offset:512
	v_add_co_u32_e32 v34, vcc, s33, v72
	s_nop 1
	v_addc_co_u32_e32 v35, vcc, 0, v73, vcc
	global_load_ushort v68, v[34:35], off offset:1024
	v_add_co_u32_e32 v34, vcc, s28, v72
	v_mul_f32_e32 v72, v33, v71
	s_nop 0
	v_addc_co_u32_e32 v35, vcc, 0, v73, vcc
	global_load_ushort v69, v[34:35], off offset:1536
	s_waitcnt lgkmcnt(0)
	v_mul_f32_e32 v71, v32, v71
	ds_read2st64_b32 v[34:35], v112 offset1:1
	ds_read2_b32 v[36:37], v112 offset0:132 offset1:196
	ds_read2st64_b32 v[38:39], v115 offset0:4 offset1:5
	ds_read2st64_b32 v[40:41], v116 offset0:6 offset1:7
	ds_read2st64_b32 v[42:43], v117 offset0:8 offset1:9
	ds_read2st64_b32 v[44:45], v118 offset0:10 offset1:11
	ds_read2st64_b32 v[46:47], v119 offset0:12 offset1:13
	ds_read2st64_b32 v[48:49], v120 offset0:14 offset1:15
	ds_read2st64_b32 v[50:51], v121 offset0:16 offset1:17
	ds_read2st64_b32 v[52:53], v122 offset0:18 offset1:19
	ds_read2st64_b32 v[54:55], v123 offset0:20 offset1:21
	ds_read2st64_b32 v[56:57], v124 offset0:22 offset1:23
	ds_read2st64_b32 v[58:59], v125 offset0:24 offset1:25
	ds_read2st64_b32 v[60:61], v126 offset0:26 offset1:27
	ds_read2st64_b32 v[62:63], v127 offset0:28 offset1:29
	ds_read2st64_b32 v[64:65], v128 offset0:30 offset1:31
	v_fmac_f32_e32 v71, v33, v70
	v_fma_f32 v72, v32, v70, -v72
	s_waitcnt lgkmcnt(14)
; __device__ __forceinline__ unsigned cvt_pk(float lo, float hi) { f32x2_t v = {lo, hi}; bf16x2_t b = __builtin_convertvector(v, bf16x2_t); return __builtin_bit_cast(unsigned, b); }
; __device__ __forceinline__ float bflo(unsigned w) { return __uint_as_float(w << 16); }
; __device__ __forceinline__ float bfhi(unsigned w) { return __uint_as_float(w & 0xffff0000u); }
; #define S5_LDS_FENCE() do { __builtin_amdgcn_wave_barrier(); asm volatile("s_waitcnt lgkmcnt(0)" ::: "memory"); } while (0)
; template <bool WRITEH>
; __device__ __forceinline__ void s5_block(const S5Coef& C, const bf16x8 (&bm)[8], u32x4 uw, float* Hs, int lane, float& hr, float& hi) {
;     ...
;     for (int tl = 0; tl < 16; ++tl) { bur[tl] = Hs[tl * 132 + lane]; bui[tl] = Hs[tl * 132 + 64 + lane]; }
; #pragma unroll
;     for (int tl = 0; tl < 16; ++tl) { const float nr = C.ar * hr - C.ai * hi + bur[tl], ni = C.ar * hi + C.ai * hr + bui[tl]; hr = nr; hi = ni; bur[tl] = hr; bui[tl] = hi; }
;     if (WRITEH) {
; #pragma unroll
;         for (int tl = 0; tl < 16; ++tl) { Hs[tl * 132 + lane] = bur[tl]; Hs[tl * 132 + 64 + lane] = bui[tl]; }
;     }
;     S5_LDS_FENCE();
; }
; __device__ __forceinline__ void s5_unit(ArgsP A, int l, int unit, unsigned char* lds, int wave_, int lane_) {
;     ...
;             for (int ks = 0; ks < 4; ++ks) { const float* hp = Hs + (lane & 15) * 132 + 32 * ks + 8 * (lane >> 4); const f32x4 h0 = *(const f32x4*)hp, h1 = *(const f32x4*)(hp + 4);
;                 u32x4 wh; wh.x = cvt_pk(h0[0], h0[1]); wh.y = cvt_pk(h0[2], h0[3]); wh.z = cvt_pk(h1[0], h1[1]); wh.w = cvt_pk(h1[2], h1[3]);
;                 u32x4 wl; wl.x = cvt_pk(h0[0] - bflo(wh.x), h0[1] - bfhi(wh.x)); wl.y = cvt_pk(h0[2] - bflo(wh.y), h0[3] - bfhi(wh.y)); wl.z = cvt_pk(h1[0] - bflo(wh.z), h1[1] - bfhi(wh.z)); wl.w = cvt_pk(h1[2] - bflo(wh.w), h1[3] - bfhi(wh.w));
;                 const bf16x8 hh_ = __builtin_bit_cast(bf16x8, wh), hl_ = __builtin_bit_cast(bf16x8, wl);
;                 y = __builtin_amdgcn_mfma_f32_16x16x32_bf16(hh_, chl[2 * ks], y, 0, 0, 0); y2 = __builtin_amdgcn_mfma_f32_16x16x32_bf16(hh_, chl[2 * ks + 1], y2, 0, 0, 0);
;                 y2 = __builtin_amdgcn_mfma_f32_16x16x32_bf16(hl_, chl[2 * ks], y2, 0, 0, 0); }
	v_add_f32_e32 v35, v71, v35
	v_add_f32_e32 v34, v72, v34
	v_mul_f32_e32 v70, v33, v35
	v_fma_f32 v70, v32, v34, -v70
	v_add_f32_e32 v36, v36, v70
	v_mul_f32_e32 v70, v32, v35
	v_fmac_f32_e32 v70, v33, v34
	v_add_f32_e32 v37, v37, v70
	v_mul_f32_e32 v70, v33, v37
	v_fma_f32 v70, v32, v36, -v70
	s_waitcnt lgkmcnt(13)
	v_add_f32_e32 v38, v38, v70
	v_mul_f32_e32 v70, v32, v37
	v_fmac_f32_e32 v70, v33, v36
	v_add_f32_e32 v39, v39, v70
	v_mul_f32_e32 v70, v33, v39
	v_fma_f32 v70, v32, v38, -v70
	s_waitcnt lgkmcnt(12)
	v_add_f32_e32 v40, v40, v70
	v_mul_f32_e32 v70, v32, v39
	v_fmac_f32_e32 v70, v33, v38
	v_add_f32_e32 v41, v41, v70
	v_mul_f32_e32 v70, v33, v41
	v_fma_f32 v70, v32, v40, -v70
	s_waitcnt lgkmcnt(11)
	v_add_f32_e32 v42, v42, v70
	v_mul_f32_e32 v70, v32, v41
	v_fmac_f32_e32 v70, v33, v40
	v_add_f32_e32 v43, v43, v70
	v_mul_f32_e32 v70, v33, v43
	v_fma_f32 v70, v32, v42, -v70
	s_waitcnt lgkmcnt(10)
	v_add_f32_e32 v44, v44, v70
	v_mul_f32_e32 v70, v32, v43
	v_fmac_f32_e32 v70, v33, v42
	v_add_f32_e32 v45, v45, v70
	v_mul_f32_e32 v70, v33, v45
	v_fma_f32 v70, v32, v44, -v70
	s_waitcnt lgkmcnt(9)
	v_add_f32_e32 v46, v46, v70
	v_mul_f32_e32 v70, v32, v45
	v_fmac_f32_e32 v70, v33, v44
	v_add_f32_e32 v47, v47, v70
	v_mul_f32_e32 v70, v33, v47
	v_fma_f32 v70, v32, v46, -v70
	s_waitcnt lgkmcnt(8)
	v_add_f32_e32 v48, v48, v70
	v_mul_f32_e32 v70, v32, v47
	v_fmac_f32_e32 v70, v33, v46
	v_add_f32_e32 v49, v49, v70
	v_mul_f32_e32 v70, v33, v49
	v_fma_f32 v70, v32, v48, -v70
	s_waitcnt lgkmcnt(7)
	v_add_f32_e32 v50, v50, v70
	v_mul_f32_e32 v70, v32, v49
	v_fmac_f32_e32 v70, v33, v48
	v_add_f32_e32 v51, v51, v70
	v_mul_f32_e32 v70, v33, v51
	v_fma_f32 v70, v32, v50, -v70
	s_waitcnt lgkmcnt(6)
	v_add_f32_e32 v52, v52, v70
	v_mul_f32_e32 v70, v32, v51
	v_fmac_f32_e32 v70, v33, v50
	v_add_f32_e32 v53, v53, v70
	v_mul_f32_e32 v70, v33, v53
	v_fma_f32 v70, v32, v52, -v70
	s_waitcnt lgkmcnt(5)
	v_add_f32_e32 v54, v54, v70
	v_mul_f32_e32 v70, v32, v53
	v_fmac_f32_e32 v70, v33, v52
	v_add_f32_e32 v55, v55, v70
	v_mul_f32_e32 v70, v33, v55
	v_fma_f32 v70, v32, v54, -v70
	s_waitcnt lgkmcnt(4)
	v_add_f32_e32 v56, v56, v70
	v_mul_f32_e32 v70, v32, v55
	v_fmac_f32_e32 v70, v33, v54
	v_add_f32_e32 v57, v57, v70
	v_mul_f32_e32 v70, v33, v57
	v_fma_f32 v70, v32, v56, -v70
	s_waitcnt lgkmcnt(3)
	v_add_f32_e32 v58, v58, v70
	v_mul_f32_e32 v70, v32, v57
	v_fmac_f32_e32 v70, v33, v56
	v_add_f32_e32 v59, v59, v70
	v_mul_f32_e32 v70, v33, v59
	v_fma_f32 v70, v32, v58, -v70
	s_waitcnt lgkmcnt(2)
	v_add_f32_e32 v60, v60, v70
	v_mul_f32_e32 v70, v32, v59
	v_fmac_f32_e32 v70, v33, v58
	v_add_f32_e32 v61, v61, v70
	v_mul_f32_e32 v70, v33, v61
	v_fma_f32 v70, v32, v60, -v70
	s_waitcnt lgkmcnt(1)
	v_add_f32_e32 v62, v62, v70
	v_mul_f32_e32 v70, v32, v61
	v_fmac_f32_e32 v70, v33, v60
	v_add_f32_e32 v63, v63, v70
	v_mul_f32_e32 v70, v33, v63
	v_fma_f32 v70, v32, v62, -v70
	v_mul_f32_e32 v32, v32, v63
	v_fmac_f32_e32 v32, v33, v62
	s_waitcnt lgkmcnt(0)
	v_add_f32_e32 v64, v64, v70
	v_add_f32_e32 v32, v65, v32
	ds_write2st64_b32 v112, v34, v35 offset1:1
	ds_write2_b32 v112, v36, v37 offset0:132 offset1:196
	ds_write2st64_b32 v115, v38, v39 offset0:4 offset1:5
	ds_write2st64_b32 v116, v40, v41 offset0:6 offset1:7
	ds_write2st64_b32 v117, v42, v43 offset0:8 offset1:9
	ds_write2st64_b32 v118, v44, v45 offset0:10 offset1:11
	ds_write2st64_b32 v119, v46, v47 offset0:12 offset1:13
	ds_write2st64_b32 v120, v48, v49 offset0:14 offset1:15
	ds_write2st64_b32 v121, v50, v51 offset0:16 offset1:17
	ds_write2st64_b32 v122, v52, v53 offset0:18 offset1:19
	ds_write2st64_b32 v123, v54, v55 offset0:20 offset1:21
	ds_write2st64_b32 v124, v56, v57 offset0:22 offset1:23
	ds_write2st64_b32 v125, v58, v59 offset0:24 offset1:25
	ds_write2st64_b32 v126, v60, v61 offset0:26 offset1:27
	ds_write2st64_b32 v127, v62, v63 offset0:28 offset1:29
	ds_write2st64_b32 v128, v64, v32 offset0:30 offset1:31
	s_waitcnt lgkmcnt(0)
	ds_read_b128 v[32:35], v113
	ds_read_b128 v[36:39], v113 offset:16
	s_waitcnt lgkmcnt(1)
	v_cvt_pk_bf16_f32 v40, v32, v33
	v_cvt_pk_bf16_f32 v41, v34, v35
	v_lshlrev_b32_e32 v44, 16, v40
	v_and_b32_e32 v45, 0xffff0000, v40
	v_pk_add_f32 v[32:33], v[32:33], v[44:45] neg_lo:[0,1] neg_hi:[0,1]
	v_lshlrev_b32_e32 v44, 16, v41
	v_and_b32_e32 v45, 0xffff0000, v41
	s_waitcnt lgkmcnt(0)
	v_cvt_pk_bf16_f32 v42, v36, v37
	v_cvt_pk_bf16_f32 v43, v38, v39
	v_pk_add_f32 v[34:35], v[34:35], v[44:45] neg_lo:[0,1] neg_hi:[0,1]
	v_cvt_pk_bf16_f32 v32, v32, v33
	v_cvt_pk_bf16_f32 v33, v34, v35
	v_lshlrev_b32_e32 v34, 16, v42
	v_and_b32_e32 v35, 0xffff0000, v42
	v_pk_add_f32 v[34:35], v[36:37], v[34:35] neg_lo:[0,1] neg_hi:[0,1]
	v_lshlrev_b32_e32 v36, 16, v43
	v_and_b32_e32 v37, 0xffff0000, v43
	v_pk_add_f32 v[36:37], v[38:39], v[36:37] neg_lo:[0,1] neg_hi:[0,1]
	v_cvt_pk_bf16_f32 v34, v34, v35
	v_cvt_pk_bf16_f32 v35, v36, v37
	v_mfma_f32_16x16x32_bf16 v[28:31], v[40:43], v[28:31], 0
	v_mfma_f32_16x16x32_bf16 v[36:39], v[40:43], v[24:27], 0
	v_mfma_f32_16x16x32_bf16 v[24:27], v[32:35], v[24:27], v[28:31]
	s_nop 5
	ds_read_b128 v[28:31], v113 offset:128
	ds_read_b128 v[32:35], v113 offset:144
	s_waitcnt lgkmcnt(1)
	v_cvt_pk_bf16_f32 v40, v28, v29
	v_cvt_pk_bf16_f32 v41, v30, v31
	v_lshlrev_b32_e32 v44, 16, v40
	v_and_b32_e32 v45, 0xffff0000, v40
	v_pk_add_f32 v[28:29], v[28:29], v[44:45] neg_lo:[0,1] neg_hi:[0,1]
	v_lshlrev_b32_e32 v44, 16, v41
	v_and_b32_e32 v45, 0xffff0000, v41
	s_waitcnt lgkmcnt(0)
; __device__ __forceinline__ unsigned cvt_pk(float lo, float hi) { f32x2_t v = {lo, hi}; bf16x2_t b = __builtin_convertvector(v, bf16x2_t); return __builtin_bit_cast(unsigned, b); }
; __device__ __forceinline__ float bf2f(unsigned short h) { return __uint_as_float(((unsigned)h) << 16); }
; __device__ __forceinline__ float bflo(unsigned w) { return __uint_as_float(w << 16); }
; __device__ __forceinline__ float bfhi(unsigned w) { return __uint_as_float(w & 0xffff0000u); }
; __device__ __forceinline__ unsigned short f2bf(float f) { return (unsigned short)(cvt_pk(f, 0.f) & 0xffffu); }
; __device__ __forceinline__ void s5_unit(ArgsP A, int l, int unit, unsigned char* lds, int wave_, int lane_) {
;     ...
;             for (int ks = 0; ks < 4; ++ks) { const float* hp = Hs + (lane & 15) * 132 + 32 * ks + 8 * (lane >> 4); const f32x4 h0 = *(const f32x4*)hp, h1 = *(const f32x4*)(hp + 4);
;                 u32x4 wh; wh.x = cvt_pk(h0[0], h0[1]); wh.y = cvt_pk(h0[2], h0[3]); wh.z = cvt_pk(h1[0], h1[1]); wh.w = cvt_pk(h1[2], h1[3]);
;                 u32x4 wl; wl.x = cvt_pk(h0[0] - bflo(wh.x), h0[1] - bfhi(wh.x)); wl.y = cvt_pk(h0[2] - bflo(wh.y), h0[3] - bfhi(wh.y)); wl.z = cvt_pk(h1[0] - bflo(wh.z), h1[1] - bfhi(wh.z)); wl.w = cvt_pk(h1[2] - bflo(wh.w), h1[3] - bfhi(wh.w));
;                 const bf16x8 hh_ = __builtin_bit_cast(bf16x8, wh), hl_ = __builtin_bit_cast(bf16x8, wl);
;                 y = __builtin_amdgcn_mfma_f32_16x16x32_bf16(hh_, chl[2 * ks], y, 0, 0, 0); y2 = __builtin_amdgcn_mfma_f32_16x16x32_bf16(hh_, chl[2 * ks + 1], y2, 0, 0, 0);
;                 y2 = __builtin_amdgcn_mfma_f32_16x16x32_bf16(hl_, chl[2 * ks], y2, 0, 0, 0); }
;             y = y + y2;
; #pragma unroll
;             for (int i = 0; i < 4; ++i) { const int t = 16 * blk + 4 * (lane >> 4) + i; const int col = 16 * g + (lane & 15);
;                 const float uval = bf2f(uraw[i]); const float v = gelu_tanh(y[i] + dv * uval); ys[t * YS_STRIDE + col] = f2bf(v); }
;             __builtin_amdgcn_wave_barrier(); asm volatile("s_waitcnt lgkmcnt(0)" ::: "memory");
;         }
	v_cvt_pk_bf16_f32 v42, v32, v33
	v_cvt_pk_bf16_f32 v43, v34, v35
	v_pk_add_f32 v[30:31], v[30:31], v[44:45] neg_lo:[0,1] neg_hi:[0,1]
	v_cvt_pk_bf16_f32 v28, v28, v29
	v_cvt_pk_bf16_f32 v29, v30, v31
	v_lshlrev_b32_e32 v30, 16, v42
	v_and_b32_e32 v31, 0xffff0000, v42
	v_pk_add_f32 v[30:31], v[32:33], v[30:31] neg_lo:[0,1] neg_hi:[0,1]
	v_lshlrev_b32_e32 v32, 16, v43
	v_and_b32_e32 v33, 0xffff0000, v43
	v_pk_add_f32 v[32:33], v[34:35], v[32:33] neg_lo:[0,1] neg_hi:[0,1]
	v_cvt_pk_bf16_f32 v30, v30, v31
	v_cvt_pk_bf16_f32 v31, v32, v33
	v_mfma_f32_16x16x32_bf16 v[20:23], v[40:43], v[20:23], v[24:27]
	v_mfma_f32_16x16x32_bf16 v[32:35], v[40:43], v[16:19], v[36:39]
	v_mfma_f32_16x16x32_bf16 v[16:19], v[28:31], v[16:19], v[20:23]
	s_nop 5
	ds_read_b128 v[20:23], v113 offset:256
	ds_read_b128 v[24:27], v113 offset:272
	s_waitcnt lgkmcnt(1)
	v_cvt_pk_bf16_f32 v28, v20, v21
	v_cvt_pk_bf16_f32 v29, v22, v23
	v_lshlrev_b32_e32 v36, 16, v28
	v_and_b32_e32 v37, 0xffff0000, v28
	v_pk_add_f32 v[20:21], v[20:21], v[36:37] neg_lo:[0,1] neg_hi:[0,1]
	v_lshlrev_b32_e32 v36, 16, v29
	v_and_b32_e32 v37, 0xffff0000, v29
	s_waitcnt lgkmcnt(0)
	v_cvt_pk_bf16_f32 v30, v24, v25
	v_cvt_pk_bf16_f32 v31, v26, v27
	v_pk_add_f32 v[22:23], v[22:23], v[36:37] neg_lo:[0,1] neg_hi:[0,1]
	v_cvt_pk_bf16_f32 v20, v20, v21
	v_cvt_pk_bf16_f32 v21, v22, v23
	v_lshlrev_b32_e32 v22, 16, v30
	v_and_b32_e32 v23, 0xffff0000, v30
	v_pk_add_f32 v[22:23], v[24:25], v[22:23] neg_lo:[0,1] neg_hi:[0,1]
	v_lshlrev_b32_e32 v24, 16, v31
	v_and_b32_e32 v25, 0xffff0000, v31
	v_pk_add_f32 v[24:25], v[26:27], v[24:25] neg_lo:[0,1] neg_hi:[0,1]
	v_cvt_pk_bf16_f32 v22, v22, v23
	v_cvt_pk_bf16_f32 v23, v24, v25
	v_mfma_f32_16x16x32_bf16 v[12:15], v[28:31], v[12:15], v[16:19]
	v_mfma_f32_16x16x32_bf16 v[24:27], v[28:31], v[8:11], v[32:35]
	v_mfma_f32_16x16x32_bf16 v[8:11], v[20:23], v[8:11], v[12:15]
	s_nop 5
	ds_read_b128 v[12:15], v113 offset:384
	ds_read_b128 v[16:19], v113 offset:400
	s_waitcnt lgkmcnt(1)
	v_cvt_pk_bf16_f32 v20, v12, v13
	v_cvt_pk_bf16_f32 v21, v14, v15
	v_lshlrev_b32_e32 v28, 16, v20
	v_and_b32_e32 v29, 0xffff0000, v20
	v_pk_add_f32 v[12:13], v[12:13], v[28:29] neg_lo:[0,1] neg_hi:[0,1]
	v_lshlrev_b32_e32 v28, 16, v21
	v_and_b32_e32 v29, 0xffff0000, v21
	s_waitcnt lgkmcnt(0)
	v_cvt_pk_bf16_f32 v22, v16, v17
	v_cvt_pk_bf16_f32 v23, v18, v19
	v_pk_add_f32 v[14:15], v[14:15], v[28:29] neg_lo:[0,1] neg_hi:[0,1]
	v_cvt_pk_bf16_f32 v12, v12, v13
	v_cvt_pk_bf16_f32 v13, v14, v15
	v_lshlrev_b32_e32 v14, 16, v22
	v_and_b32_e32 v15, 0xffff0000, v22
	v_pk_add_f32 v[14:15], v[16:17], v[14:15] neg_lo:[0,1] neg_hi:[0,1]
	v_lshlrev_b32_e32 v16, 16, v23
	v_and_b32_e32 v17, 0xffff0000, v23
	v_pk_add_f32 v[16:17], v[18:19], v[16:17] neg_lo:[0,1] neg_hi:[0,1]
	v_cvt_pk_bf16_f32 v14, v14, v15
	v_cvt_pk_bf16_f32 v15, v16, v17
	v_mfma_f32_16x16x32_bf16 v[4:7], v[20:23], v[4:7], v[8:11]
	v_mfma_f32_16x16x32_bf16 v[16:19], v[20:23], v[0:3], v[24:27]
	v_mfma_f32_16x16x32_bf16 v[0:3], v[12:15], v[0:3], v[4:7]
	s_waitcnt vmcnt(3)
	s_nop 4
	v_lshlrev_b32_e32 v4, 16, v66
	s_nop 0
	v_pk_add_f32 v[0:1], v[16:17], v[0:1]
	v_pk_add_f32 v[2:3], v[18:19], v[2:3]
	v_fma_f32 v0, v79, v4, v0
	v_mul_f32_e32 v4, 0x3d372713, v0
	v_mul_f32_e32 v4, v0, v4
	v_fma_f32 v4, v0, v4, v0
	v_mul_f32_e32 v4, 0x3f4c422a, v4
	v_add_f32_e32 v4, v4, v4
	v_mul_f32_e32 v4, 0x3fb8aa3b, v4
	v_exp_f32_e32 v4, v4
	v_mul_f32_e32 v0, 0.5, v0
	v_add_f32_e32 v4, 1.0, v4
	v_rcp_f32_e32 v4, v4
	s_nop 0
	v_fma_f32 v4, v4, -2.0, 1.0
	v_add_f32_e32 v4, 1.0, v4
	v_mul_f32_e32 v0, v0, v4
	v_cvt_pk_bf16_f32 v0, v0, s0
	ds_write_b16 v102, v0 offset:49920
	s_waitcnt vmcnt(2)
	v_lshlrev_b32_e32 v0, 16, v67
	v_fmac_f32_e32 v1, v79, v0
	v_mul_f32_e32 v0, 0x3d372713, v1
	v_mul_f32_e32 v0, v1, v0
	v_fma_f32 v0, v1, v0, v1
	v_mul_f32_e32 v0, 0x3f4c422a, v0
	v_add_f32_e32 v0, v0, v0
	v_mul_f32_e32 v0, 0x3fb8aa3b, v0
	v_exp_f32_e32 v0, v0
	v_mul_f32_e32 v1, 0.5, v1
	v_add_f32_e32 v0, 1.0, v0
	v_rcp_f32_e32 v0, v0
	s_nop 0
	v_fma_f32 v0, v0, -2.0, 1.0
	v_add_f32_e32 v0, 1.0, v0
	v_mul_f32_e32 v0, v1, v0
	v_cvt_pk_bf16_f32 v0, v0, s0
	ds_write_b16 v102, v0 offset:50960
	s_waitcnt vmcnt(1)
	v_lshlrev_b32_e32 v0, 16, v68
	v_fma_f32 v0, v79, v0, v2
	v_mul_f32_e32 v1, 0x3d372713, v0
	v_mul_f32_e32 v1, v0, v1
	v_fma_f32 v1, v0, v1, v0
	v_mul_f32_e32 v1, 0x3f4c422a, v1
	v_add_f32_e32 v1, v1, v1
	v_mul_f32_e32 v1, 0x3fb8aa3b, v1
	v_exp_f32_e32 v1, v1
	v_mul_f32_e32 v0, 0.5, v0
	v_add_f32_e32 v1, 1.0, v1
	v_rcp_f32_e32 v1, v1
	s_nop 0
	v_fma_f32 v1, v1, -2.0, 1.0
	v_add_f32_e32 v1, 1.0, v1
	v_mul_f32_e32 v0, v0, v1
	v_cvt_pk_bf16_f32 v0, v0, s0
	ds_write_b16 v102, v0 offset:52000
	s_waitcnt vmcnt(0)
	v_lshlrev_b32_e32 v0, 16, v69
	v_fmac_f32_e32 v3, v79, v0
	v_mul_f32_e32 v0, 0x3d372713, v3
	v_mul_f32_e32 v0, v3, v0
	v_fma_f32 v0, v3, v0, v3
	v_mul_f32_e32 v0, 0x3f4c422a, v0
	v_add_f32_e32 v0, v0, v0
	v_mul_f32_e32 v0, 0x3fb8aa3b, v0
	v_exp_f32_e32 v0, v0
	v_mul_f32_e32 v1, 0.5, v3
	v_add_f32_e32 v0, 1.0, v0
	v_rcp_f32_e32 v0, v0
	s_nop 0
	v_fma_f32 v0, v0, -2.0, 1.0
	v_add_f32_e32 v0, 1.0, v0
	v_mul_f32_e32 v0, v1, v0
	v_cvt_pk_bf16_f32 v0, v0, s0
	ds_write_b16 v102, v0 offset:53040
	s_waitcnt lgkmcnt(0)
	s_cbranch_scc1 .LBB0_792
; __device__ __forceinline__ void s5_unit(ArgsP A, int l, int unit, unsigned char* lds, int wave_, int lane_) {
;     ...
;     const bf16_t* WG = (const bf16_t*)(A->ws + WS_W + (size_t)l * WL_SIZE + WL_WGLU);
;     f32x4 acc[4][4];
; #pragma unroll
;     for (int mb = 0; mb < 4; ++mb)
; #pragma unroll
;         for (int nb = 0; nb < 4; ++nb) acc[mb][nb] = (f32x4){0.f, 0.f, 0.f, 0.f};
;     {
;         const bf16_t* wb = WG + (size_t)(64 * wave + (lane & 15)) * 512 + 8 * (lane >> 4);
;         bf16x8 bq[4][4];
; #pragma unroll
;         for (int p = 0; p < 4; ++p)
; #pragma unroll
;             for (int nb = 0; nb < 4; ++nb) bq[p][nb] = *(const bf16x8*)(wb + (size_t)(16 * nb) * 512 + 32 * p);
; #pragma unroll
;         for (int ks = 0; ks < 16; ++ks) {
;             bf16x8 af[4];
; #pragma unroll
;             for (int mb = 0; mb < 4; ++mb) af[mb] = *(const bf16x8*)(ys + (16 * mb + (lane & 15)) * YS_STRIDE + 32 * ks + 8 * (lane >> 4));
;             asm volatile("" : "+v"(bq[ks & 3][0]), "+v"(bq[ks & 3][1]), "+v"(bq[ks & 3][2]), "+v"(bq[ks & 3][3]) :: "memory");
; #pragma unroll
;             for (int mb = 0; mb < 4; ++mb)
; #pragma unroll
;                 for (int nb = 0; nb < 4; ++nb) acc[mb][nb] = __builtin_amdgcn_mfma_f32_16x16x32_bf16(af[mb], bq[ks & 3][nb], acc[mb][nb], 0, 0, 0);
;             if (ks + 4 < 16) {
; #pragma unroll
;                 for (int nb = 0; nb < 4; ++nb) bq[ks & 3][nb] = *(const bf16x8*)(wb + (size_t)(16 * nb) * 512 + 32 * (ks + 4));
;             }
;         }
	s_mul_i32 s5, s92, 0xa7c0000
	v_or_b32_e32 v64, s4, v104
	s_add_u32 s6, s2, s5
	v_ashrrev_i32_e32 v65, 31, v64
	s_addc_u32 s7, s3, 0
	v_lshlrev_b64 v[0:1], 10, v[64:65]
	v_lshl_add_u64 v[0:1], s[6:7], 0, v[0:1]
	v_and_b32_e32 v176, 48, v105
	v_lshl_add_u64 v[34:35], v[0:1], 0, v[176:177]
	s_mov_b64 s[4:5], 0xa650000
	v_lshl_add_u64 v[48:49], v[34:35], 0, s[4:5]
	s_mov_b32 s4, 0xa65c000
	v_add_co_u32_e32 v16, vcc, s4, v34
	s_mov_b32 s4, 0xa658000
	s_nop 0
	v_addc_co_u32_e32 v17, vcc, 0, v35, vcc
	v_add_co_u32_e32 v18, vcc, s4, v34
	s_mov_b32 s4, 0xa654000
	s_nop 0
	v_addc_co_u32_e32 v19, vcc, 0, v35, vcc
	v_add_co_u32_e32 v32, vcc, s4, v34
	s_mov_b32 s4, 0xa650000
	s_nop 0
	v_addc_co_u32_e32 v33, vcc, 0, v35, vcc
	v_mul_u32_u24_e32 v0, 0x410, v104
	v_add_co_u32_e32 v34, vcc, s4, v34
	v_add3_u32 v67, 16, v176, v0
	s_nop 0
	v_addc_co_u32_e32 v35, vcc, 0, v35, vcc
	s_waitcnt lgkmcnt(0)
	s_barrier
	ds_read_b128 v[0:3], v67
	ds_read_b128 v[4:7], v67 offset:16640
	ds_read_b128 v[8:11], v67 offset:33280
	ds_read_b128 v[12:15], v67 offset:49920
	global_load_dwordx4 v[20:23], v[16:17], off
	global_load_dwordx4 v[24:27], v[18:19], off
	global_load_dwordx4 v[28:31], v[32:33], off
	s_nop 0
	global_load_dwordx4 v[34:37], v[34:35], off
	s_nop 0
	global_load_dwordx4 v[38:41], v[16:17], off offset:64
	global_load_dwordx4 v[42:45], v[18:19], off offset:64
	global_load_dwordx4 v[50:53], v[32:33], off offset:64
	global_load_dwordx4 v[54:57], v[48:49], off offset:64
	global_load_dwordx4 v[58:61], v[16:17], off offset:128
	global_load_dwordx4 v[68:71], v[18:19], off offset:128
	global_load_dwordx4 v[72:75], v[32:33], off offset:128
	global_load_dwordx4 v[76:79], v[48:49], off offset:128
	global_load_dwordx4 v[80:83], v[16:17], off offset:192
	global_load_dwordx4 v[84:87], v[18:19], off offset:192
	global_load_dwordx4 v[88:91], v[32:33], off offset:192
	global_load_dwordx4 v[92:95], v[48:49], off offset:192
	v_lshrrev_b32_e32 v66, 4, v105
	s_add_u32 s2, s2, 0x24f90000
	s_addc_u32 s3, s3, 0
	s_waitcnt vmcnt(12)
	s_waitcnt lgkmcnt(3)
	v_mfma_f32_16x16x32_bf16 v[96:99], v[0:3], v[34:37], 0
	v_mfma_f32_16x16x32_bf16 v[100:103], v[0:3], v[28:31], 0
	v_mfma_f32_16x16x32_bf16 v[106:109], v[0:3], v[24:27], 0
	v_mfma_f32_16x16x32_bf16 v[0:3], v[0:3], v[20:23], 0
	s_waitcnt lgkmcnt(2)
	v_mfma_f32_16x16x32_bf16 v[110:113], v[4:7], v[34:37], 0
	v_mfma_f32_16x16x32_bf16 v[114:117], v[4:7], v[28:31], 0
	v_mfma_f32_16x16x32_bf16 v[118:121], v[4:7], v[24:27], 0
	v_mfma_f32_16x16x32_bf16 v[4:7], v[4:7], v[20:23], 0
	s_waitcnt lgkmcnt(1)
	v_mfma_f32_16x16x32_bf16 v[122:125], v[8:11], v[34:37], 0
	v_mfma_f32_16x16x32_bf16 v[126:129], v[8:11], v[28:31], 0
	v_mfma_f32_16x16x32_bf16 v[130:133], v[8:11], v[24:27], 0
	v_mfma_f32_16x16x32_bf16 v[8:11], v[8:11], v[20:23], 0
	s_waitcnt lgkmcnt(0)
	v_mfma_f32_16x16x32_bf16 v[34:37], v[12:15], v[34:37], 0
	v_mfma_f32_16x16x32_bf16 v[28:31], v[12:15], v[28:31], 0
	v_mfma_f32_16x16x32_bf16 v[24:27], v[12:15], v[24:27], 0
	v_mfma_f32_16x16x32_bf16 v[12:15], v[12:15], v[20:23], 0
	ds_read_b128 v[20:23], v67 offset:64
	ds_read_b128 v[134:137], v67 offset:16704
	ds_read_b128 v[138:141], v67 offset:33344
	ds_read_b128 v[142:145], v67 offset:49984
	global_load_dwordx4 v[146:149], v[16:17], off offset:256
	global_load_dwordx4 v[150:153], v[18:19], off offset:256
	global_load_dwordx4 v[154:157], v[32:33], off offset:256
	global_load_dwordx4 v[158:161], v[48:49], off offset:256
	s_waitcnt vmcnt(12)
	s_waitcnt lgkmcnt(3)
	v_mfma_f32_16x16x32_bf16 v[96:99], v[20:23], v[54:57], v[96:99]
	v_mfma_f32_16x16x32_bf16 v[100:103], v[20:23], v[50:53], v[100:103]
	v_mfma_f32_16x16x32_bf16 v[106:109], v[20:23], v[42:45], v[106:109]
	v_mfma_f32_16x16x32_bf16 v[0:3], v[20:23], v[38:41], v[0:3]
	s_waitcnt lgkmcnt(2)
	v_mfma_f32_16x16x32_bf16 v[20:23], v[134:137], v[54:57], v[110:113]
	v_mfma_f32_16x16x32_bf16 v[110:113], v[134:137], v[50:53], v[114:117]
	v_mfma_f32_16x16x32_bf16 v[114:117], v[134:137], v[42:45], v[118:121]
	v_mfma_f32_16x16x32_bf16 v[4:7], v[134:137], v[38:41], v[4:7]
	s_waitcnt lgkmcnt(1)
	v_mfma_f32_16x16x32_bf16 v[118:121], v[138:141], v[54:57], v[122:125]
	v_mfma_f32_16x16x32_bf16 v[122:125], v[138:141], v[50:53], v[126:129]
	v_mfma_f32_16x16x32_bf16 v[126:129], v[138:141], v[42:45], v[130:133]
	v_mfma_f32_16x16x32_bf16 v[8:11], v[138:141], v[38:41], v[8:11]
	s_waitcnt lgkmcnt(0)
	v_mfma_f32_16x16x32_bf16 v[34:37], v[142:145], v[54:57], v[34:37]
	v_mfma_f32_16x16x32_bf16 v[28:31], v[142:145], v[50:53], v[28:31]
	v_mfma_f32_16x16x32_bf16 v[24:27], v[142:145], v[42:45], v[24:27]
	v_mfma_f32_16x16x32_bf16 v[12:15], v[142:145], v[38:41], v[12:15]
	ds_read_b128 v[38:41], v67 offset:128
	ds_read_b128 v[42:45], v67 offset:16768
	ds_read_b128 v[50:53], v67 offset:33408
	ds_read_b128 v[54:57], v67 offset:50048
	global_load_dwordx4 v[130:133], v[16:17], off offset:320
	global_load_dwordx4 v[134:137], v[18:19], off offset:320
	global_load_dwordx4 v[138:141], v[32:33], off offset:320
	global_load_dwordx4 v[142:145], v[48:49], off offset:320
	s_waitcnt vmcnt(12)
	s_waitcnt lgkmcnt(3)
	v_mfma_f32_16x16x32_bf16 v[96:99], v[38:41], v[76:79], v[96:99]
	v_mfma_f32_16x16x32_bf16 v[100:103], v[38:41], v[72:75], v[100:103]
	v_mfma_f32_16x16x32_bf16 v[106:109], v[38:41], v[68:71], v[106:109]
	v_mfma_f32_16x16x32_bf16 v[0:3], v[38:41], v[58:61], v[0:3]
	s_waitcnt lgkmcnt(2)
	v_mfma_f32_16x16x32_bf16 v[20:23], v[42:45], v[76:79], v[20:23]
	v_mfma_f32_16x16x32_bf16 v[38:41], v[42:45], v[72:75], v[110:113]
	v_mfma_f32_16x16x32_bf16 v[110:113], v[42:45], v[68:71], v[114:117]
	v_mfma_f32_16x16x32_bf16 v[4:7], v[42:45], v[58:61], v[4:7]
	s_waitcnt lgkmcnt(1)
; __device__ __forceinline__ void s5_unit(ArgsP A, int l, int unit, unsigned char* lds, int wave_, int lane_) {
;     ...
; #pragma unroll
;         for (int ks = 0; ks < 16; ++ks) {
;             bf16x8 af[4];
; #pragma unroll
;             for (int mb = 0; mb < 4; ++mb) af[mb] = *(const bf16x8*)(ys + (16 * mb + (lane & 15)) * YS_STRIDE + 32 * ks + 8 * (lane >> 4));
;             asm volatile("" : "+v"(bq[ks & 3][0]), "+v"(bq[ks & 3][1]), "+v"(bq[ks & 3][2]), "+v"(bq[ks & 3][3]) :: "memory");
; #pragma unroll
;             for (int mb = 0; mb < 4; ++mb)
; #pragma unroll
;                 for (int nb = 0; nb < 4; ++nb) acc[mb][nb] = __builtin_amdgcn_mfma_f32_16x16x32_bf16(af[mb], bq[ks & 3][nb], acc[mb][nb], 0, 0, 0);
;             if (ks + 4 < 16) {
; #pragma unroll
;                 for (int nb = 0; nb < 4; ++nb) bq[ks & 3][nb] = *(const bf16x8*)(wb + (size_t)(16 * nb) * 512 + 32 * (ks + 4));
;             }
;         }
	v_mfma_f32_16x16x32_bf16 v[42:45], v[50:53], v[76:79], v[118:121]
	v_mfma_f32_16x16x32_bf16 v[114:117], v[50:53], v[72:75], v[122:125]
	v_mfma_f32_16x16x32_bf16 v[118:121], v[50:53], v[68:71], v[126:129]
	v_mfma_f32_16x16x32_bf16 v[8:11], v[50:53], v[58:61], v[8:11]
	s_waitcnt lgkmcnt(0)
	v_mfma_f32_16x16x32_bf16 v[34:37], v[54:57], v[76:79], v[34:37]
	v_mfma_f32_16x16x32_bf16 v[28:31], v[54:57], v[72:75], v[28:31]
	v_mfma_f32_16x16x32_bf16 v[24:27], v[54:57], v[68:71], v[24:27]
	v_mfma_f32_16x16x32_bf16 v[12:15], v[54:57], v[58:61], v[12:15]
	ds_read_b128 v[50:53], v67 offset:192
	ds_read_b128 v[54:57], v67 offset:16832
	ds_read_b128 v[58:61], v67 offset:33472
	ds_read_b128 v[68:71], v67 offset:50112
	global_load_dwordx4 v[72:75], v[16:17], off offset:384
	global_load_dwordx4 v[76:79], v[18:19], off offset:384
	global_load_dwordx4 v[122:125], v[32:33], off offset:384
	global_load_dwordx4 v[126:129], v[48:49], off offset:384
	s_waitcnt vmcnt(12)
	s_waitcnt lgkmcnt(3)
	v_mfma_f32_16x16x32_bf16 v[96:99], v[50:53], v[92:95], v[96:99]
	v_mfma_f32_16x16x32_bf16 v[100:103], v[50:53], v[88:91], v[100:103]
	v_mfma_f32_16x16x32_bf16 v[106:109], v[50:53], v[84:87], v[106:109]
	v_mfma_f32_16x16x32_bf16 v[0:3], v[50:53], v[80:83], v[0:3]
	s_waitcnt lgkmcnt(2)
	v_mfma_f32_16x16x32_bf16 v[20:23], v[54:57], v[92:95], v[20:23]
	v_mfma_f32_16x16x32_bf16 v[38:41], v[54:57], v[88:91], v[38:41]
	v_mfma_f32_16x16x32_bf16 v[50:53], v[54:57], v[84:87], v[110:113]
	v_mfma_f32_16x16x32_bf16 v[4:7], v[54:57], v[80:83], v[4:7]
	s_waitcnt lgkmcnt(1)
	v_mfma_f32_16x16x32_bf16 v[42:45], v[58:61], v[92:95], v[42:45]
	v_mfma_f32_16x16x32_bf16 v[54:57], v[58:61], v[88:91], v[114:117]
	v_mfma_f32_16x16x32_bf16 v[110:113], v[58:61], v[84:87], v[118:121]
	v_mfma_f32_16x16x32_bf16 v[8:11], v[58:61], v[80:83], v[8:11]
	s_waitcnt lgkmcnt(0)
	v_mfma_f32_16x16x32_bf16 v[34:37], v[68:71], v[92:95], v[34:37]
	v_mfma_f32_16x16x32_bf16 v[28:31], v[68:71], v[88:91], v[28:31]
	v_mfma_f32_16x16x32_bf16 v[24:27], v[68:71], v[84:87], v[24:27]
	v_mfma_f32_16x16x32_bf16 v[12:15], v[68:71], v[80:83], v[12:15]
	ds_read_b128 v[58:61], v67 offset:256
	ds_read_b128 v[68:71], v67 offset:16896
	ds_read_b128 v[80:83], v67 offset:33536
	ds_read_b128 v[84:87], v67 offset:50176
	global_load_dwordx4 v[88:91], v[16:17], off offset:448
	global_load_dwordx4 v[92:95], v[18:19], off offset:448
	global_load_dwordx4 v[114:117], v[32:33], off offset:448
	global_load_dwordx4 v[118:121], v[48:49], off offset:448
	s_waitcnt vmcnt(12)
	s_waitcnt lgkmcnt(3)
	v_mfma_f32_16x16x32_bf16 v[96:99], v[58:61], v[158:161], v[96:99]
	v_mfma_f32_16x16x32_bf16 v[100:103], v[58:61], v[154:157], v[100:103]
	v_mfma_f32_16x16x32_bf16 v[106:109], v[58:61], v[150:153], v[106:109]
	v_mfma_f32_16x16x32_bf16 v[0:3], v[58:61], v[146:149], v[0:3]
	s_waitcnt lgkmcnt(2)
	v_mfma_f32_16x16x32_bf16 v[20:23], v[68:71], v[158:161], v[20:23]
	v_mfma_f32_16x16x32_bf16 v[38:41], v[68:71], v[154:157], v[38:41]
	v_mfma_f32_16x16x32_bf16 v[50:53], v[68:71], v[150:153], v[50:53]
	v_mfma_f32_16x16x32_bf16 v[4:7], v[68:71], v[146:149], v[4:7]
	s_waitcnt lgkmcnt(1)
	v_mfma_f32_16x16x32_bf16 v[42:45], v[80:83], v[158:161], v[42:45]
	v_mfma_f32_16x16x32_bf16 v[54:57], v[80:83], v[154:157], v[54:57]
	v_mfma_f32_16x16x32_bf16 v[58:61], v[80:83], v[150:153], v[110:113]
	v_mfma_f32_16x16x32_bf16 v[8:11], v[80:83], v[146:149], v[8:11]
	s_waitcnt lgkmcnt(0)
	v_mfma_f32_16x16x32_bf16 v[34:37], v[84:87], v[158:161], v[34:37]
	v_mfma_f32_16x16x32_bf16 v[28:31], v[84:87], v[154:157], v[28:31]
	v_mfma_f32_16x16x32_bf16 v[24:27], v[84:87], v[150:153], v[24:27]
	v_mfma_f32_16x16x32_bf16 v[12:15], v[84:87], v[146:149], v[12:15]
	ds_read_b128 v[68:71], v67 offset:320
	ds_read_b128 v[80:83], v67 offset:16960
	ds_read_b128 v[84:87], v67 offset:33600
	ds_read_b128 v[110:113], v67 offset:50240
	global_load_dwordx4 v[146:149], v[16:17], off offset:512
	global_load_dwordx4 v[150:153], v[18:19], off offset:512
	global_load_dwordx4 v[154:157], v[32:33], off offset:512
	global_load_dwordx4 v[158:161], v[48:49], off offset:512
	s_waitcnt vmcnt(12)
	s_waitcnt lgkmcnt(3)
	v_mfma_f32_16x16x32_bf16 v[96:99], v[68:71], v[142:145], v[96:99]
	v_mfma_f32_16x16x32_bf16 v[100:103], v[68:71], v[138:141], v[100:103]
	v_mfma_f32_16x16x32_bf16 v[106:109], v[68:71], v[134:137], v[106:109]
	v_mfma_f32_16x16x32_bf16 v[0:3], v[68:71], v[130:133], v[0:3]
	s_waitcnt lgkmcnt(2)
	v_mfma_f32_16x16x32_bf16 v[20:23], v[80:83], v[142:145], v[20:23]
	v_mfma_f32_16x16x32_bf16 v[38:41], v[80:83], v[138:141], v[38:41]
	v_mfma_f32_16x16x32_bf16 v[50:53], v[80:83], v[134:137], v[50:53]
	v_mfma_f32_16x16x32_bf16 v[4:7], v[80:83], v[130:133], v[4:7]
	s_waitcnt lgkmcnt(1)
	v_mfma_f32_16x16x32_bf16 v[42:45], v[84:87], v[142:145], v[42:45]
	v_mfma_f32_16x16x32_bf16 v[54:57], v[84:87], v[138:141], v[54:57]
	v_mfma_f32_16x16x32_bf16 v[58:61], v[84:87], v[134:137], v[58:61]
	v_mfma_f32_16x16x32_bf16 v[8:11], v[84:87], v[130:133], v[8:11]
	s_waitcnt lgkmcnt(0)
	v_mfma_f32_16x16x32_bf16 v[34:37], v[110:113], v[142:145], v[34:37]
	v_mfma_f32_16x16x32_bf16 v[28:31], v[110:113], v[138:141], v[28:31]
	v_mfma_f32_16x16x32_bf16 v[24:27], v[110:113], v[134:137], v[24:27]
	v_mfma_f32_16x16x32_bf16 v[12:15], v[110:113], v[130:133], v[12:15]
	ds_read_b128 v[68:71], v67 offset:384
	ds_read_b128 v[80:83], v67 offset:17024
	ds_read_b128 v[84:87], v67 offset:33664
	ds_read_b128 v[110:113], v67 offset:50304
	global_load_dwordx4 v[130:133], v[16:17], off offset:576
	global_load_dwordx4 v[134:137], v[18:19], off offset:576
	global_load_dwordx4 v[138:141], v[32:33], off offset:576
	global_load_dwordx4 v[142:145], v[48:49], off offset:576
	s_waitcnt vmcnt(12)
; __device__ __forceinline__ void s5_unit(ArgsP A, int l, int unit, unsigned char* lds, int wave_, int lane_) {
;     ...
; #pragma unroll
;         for (int ks = 0; ks < 16; ++ks) {
;             bf16x8 af[4];
; #pragma unroll
;             for (int mb = 0; mb < 4; ++mb) af[mb] = *(const bf16x8*)(ys + (16 * mb + (lane & 15)) * YS_STRIDE + 32 * ks + 8 * (lane >> 4));
;             asm volatile("" : "+v"(bq[ks & 3][0]), "+v"(bq[ks & 3][1]), "+v"(bq[ks & 3][2]), "+v"(bq[ks & 3][3]) :: "memory");
; #pragma unroll
;             for (int mb = 0; mb < 4; ++mb)
; #pragma unroll
;                 for (int nb = 0; nb < 4; ++nb) acc[mb][nb] = __builtin_amdgcn_mfma_f32_16x16x32_bf16(af[mb], bq[ks & 3][nb], acc[mb][nb], 0, 0, 0);
;             if (ks + 4 < 16) {
; #pragma unroll
;                 for (int nb = 0; nb < 4; ++nb) bq[ks & 3][nb] = *(const bf16x8*)(wb + (size_t)(16 * nb) * 512 + 32 * (ks + 4));
;             }
;         }
	s_waitcnt lgkmcnt(3)
	v_mfma_f32_16x16x32_bf16 v[96:99], v[68:71], v[126:129], v[96:99]
	v_mfma_f32_16x16x32_bf16 v[100:103], v[68:71], v[122:125], v[100:103]
	v_mfma_f32_16x16x32_bf16 v[106:109], v[68:71], v[76:79], v[106:109]
	v_mfma_f32_16x16x32_bf16 v[0:3], v[68:71], v[72:75], v[0:3]
	s_waitcnt lgkmcnt(2)
	v_mfma_f32_16x16x32_bf16 v[20:23], v[80:83], v[126:129], v[20:23]
	v_mfma_f32_16x16x32_bf16 v[38:41], v[80:83], v[122:125], v[38:41]
	v_mfma_f32_16x16x32_bf16 v[50:53], v[80:83], v[76:79], v[50:53]
	v_mfma_f32_16x16x32_bf16 v[4:7], v[80:83], v[72:75], v[4:7]
	s_waitcnt lgkmcnt(1)
	v_mfma_f32_16x16x32_bf16 v[42:45], v[84:87], v[126:129], v[42:45]
	v_mfma_f32_16x16x32_bf16 v[54:57], v[84:87], v[122:125], v[54:57]
	v_mfma_f32_16x16x32_bf16 v[58:61], v[84:87], v[76:79], v[58:61]
	v_mfma_f32_16x16x32_bf16 v[8:11], v[84:87], v[72:75], v[8:11]
	s_waitcnt lgkmcnt(0)
	v_mfma_f32_16x16x32_bf16 v[34:37], v[110:113], v[126:129], v[34:37]
	v_mfma_f32_16x16x32_bf16 v[28:31], v[110:113], v[122:125], v[28:31]
	v_mfma_f32_16x16x32_bf16 v[24:27], v[110:113], v[76:79], v[24:27]
	v_mfma_f32_16x16x32_bf16 v[12:15], v[110:113], v[72:75], v[12:15]
	ds_read_b128 v[68:71], v67 offset:448
	ds_read_b128 v[72:75], v67 offset:17088
	ds_read_b128 v[76:79], v67 offset:33728
	ds_read_b128 v[80:83], v67 offset:50368
	global_load_dwordx4 v[84:87], v[16:17], off offset:640
	global_load_dwordx4 v[110:113], v[18:19], off offset:640
	global_load_dwordx4 v[122:125], v[32:33], off offset:640
	global_load_dwordx4 v[126:129], v[48:49], off offset:640
	s_waitcnt vmcnt(12)
	s_waitcnt lgkmcnt(3)
	v_mfma_f32_16x16x32_bf16 v[96:99], v[68:71], v[118:121], v[96:99]
	v_mfma_f32_16x16x32_bf16 v[100:103], v[68:71], v[114:117], v[100:103]
	v_mfma_f32_16x16x32_bf16 v[106:109], v[68:71], v[92:95], v[106:109]
	v_mfma_f32_16x16x32_bf16 v[0:3], v[68:71], v[88:91], v[0:3]
	s_waitcnt lgkmcnt(2)
	v_mfma_f32_16x16x32_bf16 v[20:23], v[72:75], v[118:121], v[20:23]
	v_mfma_f32_16x16x32_bf16 v[38:41], v[72:75], v[114:117], v[38:41]
	v_mfma_f32_16x16x32_bf16 v[50:53], v[72:75], v[92:95], v[50:53]
	v_mfma_f32_16x16x32_bf16 v[4:7], v[72:75], v[88:91], v[4:7]
	s_waitcnt lgkmcnt(1)
	v_mfma_f32_16x16x32_bf16 v[42:45], v[76:79], v[118:121], v[42:45]
	v_mfma_f32_16x16x32_bf16 v[54:57], v[76:79], v[114:117], v[54:57]
	v_mfma_f32_16x16x32_bf16 v[58:61], v[76:79], v[92:95], v[58:61]
	v_mfma_f32_16x16x32_bf16 v[8:11], v[76:79], v[88:91], v[8:11]
	s_waitcnt lgkmcnt(0)
	v_mfma_f32_16x16x32_bf16 v[34:37], v[80:83], v[118:121], v[34:37]
	v_mfma_f32_16x16x32_bf16 v[28:31], v[80:83], v[114:117], v[28:31]
	v_mfma_f32_16x16x32_bf16 v[24:27], v[80:83], v[92:95], v[24:27]
	v_mfma_f32_16x16x32_bf16 v[12:15], v[80:83], v[88:91], v[12:15]
	ds_read_b128 v[68:71], v67 offset:512
	ds_read_b128 v[72:75], v67 offset:17152
	ds_read_b128 v[76:79], v67 offset:33792
	ds_read_b128 v[80:83], v67 offset:50432
	global_load_dwordx4 v[88:91], v[16:17], off offset:704
	global_load_dwordx4 v[92:95], v[18:19], off offset:704
	global_load_dwordx4 v[114:117], v[32:33], off offset:704
	global_load_dwordx4 v[118:121], v[48:49], off offset:704
	s_waitcnt vmcnt(12)
	s_waitcnt lgkmcnt(3)
	v_mfma_f32_16x16x32_bf16 v[96:99], v[68:71], v[158:161], v[96:99]
	v_mfma_f32_16x16x32_bf16 v[100:103], v[68:71], v[154:157], v[100:103]
	v_mfma_f32_16x16x32_bf16 v[106:109], v[68:71], v[150:153], v[106:109]
	v_mfma_f32_16x16x32_bf16 v[0:3], v[68:71], v[146:149], v[0:3]
	s_waitcnt lgkmcnt(2)
	v_mfma_f32_16x16x32_bf16 v[20:23], v[72:75], v[158:161], v[20:23]
	v_mfma_f32_16x16x32_bf16 v[68:71], v[72:75], v[154:157], v[38:41]
	v_mfma_f32_16x16x32_bf16 v[162:165], v[72:75], v[150:153], v[50:53]
	v_mfma_f32_16x16x32_bf16 v[4:7], v[72:75], v[146:149], v[4:7]
	s_waitcnt lgkmcnt(1)
	v_mfma_f32_16x16x32_bf16 v[72:75], v[76:79], v[158:161], v[42:45]
	v_mfma_f32_16x16x32_bf16 v[166:169], v[76:79], v[154:157], v[54:57]
	v_mfma_f32_16x16x32_bf16 v[56:59], v[76:79], v[150:153], v[58:61]
	v_mfma_f32_16x16x32_bf16 v[8:11], v[76:79], v[146:149], v[8:11]
	s_waitcnt lgkmcnt(0)
	v_mfma_f32_16x16x32_bf16 v[34:37], v[80:83], v[158:161], v[34:37]
	v_mfma_f32_16x16x32_bf16 v[28:31], v[80:83], v[154:157], v[28:31]
	v_mfma_f32_16x16x32_bf16 v[24:27], v[80:83], v[150:153], v[24:27]
	v_mfma_f32_16x16x32_bf16 v[12:15], v[80:83], v[146:149], v[12:15]
	ds_read_b128 v[76:79], v67 offset:576
	ds_read_b128 v[80:83], v67 offset:17216
	ds_read_b128 v[146:149], v67 offset:33856
	ds_read_b128 v[150:153], v67 offset:50496
	global_load_dwordx4 v[40:43], v[16:17], off offset:768
	global_load_dwordx4 v[44:47], v[18:19], off offset:768
	global_load_dwordx4 v[52:55], v[32:33], off offset:768
	global_load_dwordx4 v[60:63], v[48:49], off offset:768
	s_waitcnt vmcnt(12)
	s_waitcnt lgkmcnt(3)
	v_mfma_f32_16x16x32_bf16 v[96:99], v[76:79], v[142:145], v[96:99]
	v_mfma_f32_16x16x32_bf16 v[100:103], v[76:79], v[138:141], v[100:103]
	v_mfma_f32_16x16x32_bf16 v[106:109], v[76:79], v[134:137], v[106:109]
	v_mfma_f32_16x16x32_bf16 v[0:3], v[76:79], v[130:133], v[0:3]
	s_waitcnt lgkmcnt(2)
	v_mfma_f32_16x16x32_bf16 v[20:23], v[80:83], v[142:145], v[20:23]
	v_mfma_f32_16x16x32_bf16 v[68:71], v[80:83], v[138:141], v[68:71]
	v_mfma_f32_16x16x32_bf16 v[76:79], v[80:83], v[134:137], v[162:165]
	v_mfma_f32_16x16x32_bf16 v[4:7], v[80:83], v[130:133], v[4:7]
	s_waitcnt lgkmcnt(1)
	v_mfma_f32_16x16x32_bf16 v[72:75], v[146:149], v[142:145], v[72:75]
	v_mfma_f32_16x16x32_bf16 v[80:83], v[146:149], v[138:141], v[166:169]
	v_mfma_f32_16x16x32_bf16 v[56:59], v[146:149], v[134:137], v[56:59]
	v_mfma_f32_16x16x32_bf16 v[146:149], v[146:149], v[130:133], v[8:11]
	s_waitcnt lgkmcnt(0)
; __device__ __forceinline__ void s5_unit(ArgsP A, int l, int unit, unsigned char* lds, int wave_, int lane_) {
;     ...
; #pragma unroll
;         for (int ks = 0; ks < 16; ++ks) {
;             bf16x8 af[4];
; #pragma unroll
;             for (int mb = 0; mb < 4; ++mb) af[mb] = *(const bf16x8*)(ys + (16 * mb + (lane & 15)) * YS_STRIDE + 32 * ks + 8 * (lane >> 4));
;             asm volatile("" : "+v"(bq[ks & 3][0]), "+v"(bq[ks & 3][1]), "+v"(bq[ks & 3][2]), "+v"(bq[ks & 3][3]) :: "memory");
; #pragma unroll
;             for (int mb = 0; mb < 4; ++mb)
; #pragma unroll
;                 for (int nb = 0; nb < 4; ++nb) acc[mb][nb] = __builtin_amdgcn_mfma_f32_16x16x32_bf16(af[mb], bq[ks & 3][nb], acc[mb][nb], 0, 0, 0);
;             if (ks + 4 < 16) {
; #pragma unroll
;                 for (int nb = 0; nb < 4; ++nb) bq[ks & 3][nb] = *(const bf16x8*)(wb + (size_t)(16 * nb) * 512 + 32 * (ks + 4));
;             }
;         }
	v_mfma_f32_16x16x32_bf16 v[142:145], v[150:153], v[142:145], v[34:37]
	v_mfma_f32_16x16x32_bf16 v[138:141], v[150:153], v[138:141], v[28:31]
	v_mfma_f32_16x16x32_bf16 v[134:137], v[150:153], v[134:137], v[24:27]
	v_mfma_f32_16x16x32_bf16 v[12:15], v[150:153], v[130:133], v[12:15]
	ds_read_b128 v[130:133], v67 offset:640
	ds_read_b128 v[150:153], v67 offset:17280
	ds_read_b128 v[154:157], v67 offset:33920
	ds_read_b128 v[158:161], v67 offset:50560
	global_load_dwordx4 v[8:11], v[16:17], off offset:832
	global_load_dwordx4 v[24:27], v[18:19], off offset:832
	global_load_dwordx4 v[28:31], v[32:33], off offset:832
	global_load_dwordx4 v[36:39], v[48:49], off offset:832
	s_waitcnt vmcnt(12)
	s_waitcnt lgkmcnt(3)
	v_mfma_f32_16x16x32_bf16 v[96:99], v[130:133], v[126:129], v[96:99]
	v_mfma_f32_16x16x32_bf16 v[100:103], v[130:133], v[122:125], v[100:103]
	v_mfma_f32_16x16x32_bf16 v[106:109], v[130:133], v[110:113], v[106:109]
	s_waitcnt lgkmcnt(2)
	v_mfma_f32_16x16x32_bf16 v[162:165], v[150:153], v[126:129], v[20:23]
	v_mfma_f32_16x16x32_bf16 v[68:71], v[150:153], v[122:125], v[68:71]
	v_mfma_f32_16x16x32_bf16 v[76:79], v[150:153], v[110:113], v[76:79]
	s_waitcnt lgkmcnt(1)
	v_mfma_f32_16x16x32_bf16 v[72:75], v[154:157], v[126:129], v[72:75]
	v_mfma_f32_16x16x32_bf16 v[80:83], v[154:157], v[122:125], v[80:83]
	v_mfma_f32_16x16x32_bf16 v[56:59], v[154:157], v[110:113], v[56:59]
	v_mfma_f32_16x16x32_bf16 v[146:149], v[154:157], v[84:87], v[146:149]
	s_waitcnt lgkmcnt(0)
	v_mfma_f32_16x16x32_bf16 v[126:129], v[158:161], v[126:129], v[142:145]
	v_mfma_f32_16x16x32_bf16 v[122:125], v[158:161], v[122:125], v[138:141]
	v_mfma_f32_16x16x32_bf16 v[110:113], v[158:161], v[110:113], v[134:137]
	s_nop 2
	ds_read_b128 v[134:137], v67 offset:704
	ds_read_b128 v[138:141], v67 offset:17344
	ds_read_b128 v[142:145], v67 offset:33984
	ds_read_b128 v[154:157], v67 offset:50624
	v_mfma_f32_16x16x32_bf16 v[130:133], v[130:133], v[84:87], v[0:3]
	v_mfma_f32_16x16x32_bf16 v[150:153], v[150:153], v[84:87], v[4:7]
	v_mfma_f32_16x16x32_bf16 v[84:87], v[158:161], v[84:87], v[12:15]
	s_nop 0
	global_load_dwordx4 v[0:3], v[16:17], off offset:896
	global_load_dwordx4 v[4:7], v[18:19], off offset:896
	global_load_dwordx4 v[12:15], v[32:33], off offset:896
	global_load_dwordx4 v[20:23], v[48:49], off offset:896
	s_waitcnt vmcnt(12)
	s_waitcnt lgkmcnt(3)
	v_mfma_f32_16x16x32_bf16 v[96:99], v[134:137], v[118:121], v[96:99]
	v_mfma_f32_16x16x32_bf16 v[100:103], v[134:137], v[114:117], v[100:103]
	v_mfma_f32_16x16x32_bf16 v[106:109], v[134:137], v[92:95], v[106:109]
	v_mfma_f32_16x16x32_bf16 v[130:133], v[134:137], v[88:91], v[130:133]
	s_waitcnt lgkmcnt(2)
	v_mfma_f32_16x16x32_bf16 v[134:137], v[138:141], v[118:121], v[162:165]
	v_mfma_f32_16x16x32_bf16 v[68:71], v[138:141], v[114:117], v[68:71]
	v_mfma_f32_16x16x32_bf16 v[76:79], v[138:141], v[92:95], v[76:79]
	v_mfma_f32_16x16x32_bf16 v[138:141], v[138:141], v[88:91], v[150:153]
	s_waitcnt lgkmcnt(1)
	v_mfma_f32_16x16x32_bf16 v[72:75], v[142:145], v[118:121], v[72:75]
	v_mfma_f32_16x16x32_bf16 v[80:83], v[142:145], v[114:117], v[80:83]
	v_mfma_f32_16x16x32_bf16 v[150:153], v[142:145], v[92:95], v[56:59]
	v_mfma_f32_16x16x32_bf16 v[142:145], v[142:145], v[88:91], v[146:149]
	s_waitcnt lgkmcnt(0)
	v_mfma_f32_16x16x32_bf16 v[118:121], v[154:157], v[118:121], v[126:129]
	v_mfma_f32_16x16x32_bf16 v[114:117], v[154:157], v[114:117], v[122:125]
	v_mfma_f32_16x16x32_bf16 v[92:95], v[154:157], v[92:95], v[110:113]
	v_mfma_f32_16x16x32_bf16 v[84:87], v[154:157], v[88:91], v[84:87]
	ds_read_b128 v[88:91], v67 offset:768
	s_nop 0
	ds_read_b128 v[110:113], v67 offset:17408
	ds_read_b128 v[122:125], v67 offset:34048
	ds_read_b128 v[126:129], v67 offset:50688
	global_load_dwordx4 v[56:59], v[16:17], off offset:960
	s_nop 0
	global_load_dwordx4 v[16:19], v[18:19], off offset:960
	s_nop 0
	global_load_dwordx4 v[32:35], v[32:33], off offset:960
	s_nop 0
	global_load_dwordx4 v[48:51], v[48:49], off offset:960
	s_waitcnt vmcnt(12)
	s_waitcnt lgkmcnt(3)
	v_mfma_f32_16x16x32_bf16 v[96:99], v[88:91], v[60:63], v[96:99]
	v_mfma_f32_16x16x32_bf16 v[100:103], v[88:91], v[52:55], v[100:103]
	v_mfma_f32_16x16x32_bf16 v[106:109], v[88:91], v[44:47], v[106:109]
	v_mfma_f32_16x16x32_bf16 v[88:91], v[88:91], v[40:43], v[130:133]
	s_waitcnt lgkmcnt(2)
	v_mfma_f32_16x16x32_bf16 v[130:133], v[110:113], v[60:63], v[134:137]
	v_mfma_f32_16x16x32_bf16 v[68:71], v[110:113], v[52:55], v[68:71]
	v_mfma_f32_16x16x32_bf16 v[76:79], v[110:113], v[44:47], v[76:79]
	v_mfma_f32_16x16x32_bf16 v[110:113], v[110:113], v[40:43], v[138:141]
	s_waitcnt lgkmcnt(1)
	v_mfma_f32_16x16x32_bf16 v[72:75], v[122:125], v[60:63], v[72:75]
	v_mfma_f32_16x16x32_bf16 v[80:83], v[122:125], v[52:55], v[80:83]
	v_mfma_f32_16x16x32_bf16 v[134:137], v[122:125], v[44:47], v[150:153]
	v_mfma_f32_16x16x32_bf16 v[122:125], v[122:125], v[40:43], v[142:145]
	s_waitcnt lgkmcnt(0)
	v_mfma_f32_16x16x32_bf16 v[60:63], v[126:129], v[60:63], v[118:121]
	v_mfma_f32_16x16x32_bf16 v[52:55], v[126:129], v[52:55], v[114:117]
	v_mfma_f32_16x16x32_bf16 v[44:47], v[126:129], v[44:47], v[92:95]
	v_mfma_f32_16x16x32_bf16 v[40:43], v[126:129], v[40:43], v[84:87]
	s_nop 2
	ds_read_b128 v[84:87], v67 offset:832
	ds_read_b128 v[92:95], v67 offset:17472
	ds_read_b128 v[114:117], v67 offset:34112
	ds_read_b128 v[118:121], v67 offset:50752
	s_waitcnt vmcnt(8)
	s_waitcnt lgkmcnt(3)
	v_mfma_f32_16x16x32_bf16 v[96:99], v[84:87], v[36:39], v[96:99]
	v_mfma_f32_16x16x32_bf16 v[100:103], v[84:87], v[28:31], v[100:103]
	v_mfma_f32_16x16x32_bf16 v[106:109], v[84:87], v[24:27], v[106:109]
	v_mfma_f32_16x16x32_bf16 v[84:87], v[84:87], v[8:11], v[88:91]
	s_waitcnt lgkmcnt(2)
; __device__ __forceinline__ float bf2f(unsigned short h) { return __uint_as_float(((unsigned)h) << 16); }
; __device__ __forceinline__ unsigned short f2bf(float f) { return (unsigned short)(cvt_pk(f, 0.f) & 0xffffu); }
; __device__ __forceinline__ float sigmoidf_(float x) { return fast_rcp(1.f + fast_exp2(-x * LOG2E)); }
; __device__ __forceinline__ void s5_unit(ArgsP A, int l, int unit, unsigned char* lds, int wave_, int lane_) {
;     ...
;             asm volatile("" : "+v"(bq[ks & 3][0]), "+v"(bq[ks & 3][1]), "+v"(bq[ks & 3][2]), "+v"(bq[ks & 3][3]) :: "memory");
; #pragma unroll
;             for (int mb = 0; mb < 4; ++mb)
; #pragma unroll
;                 for (int nb = 0; nb < 4; ++nb) acc[mb][nb] = __builtin_amdgcn_mfma_f32_16x16x32_bf16(af[mb], bq[ks & 3][nb], acc[mb][nb], 0, 0, 0);
;             if (ks + 4 < 16) {
; #pragma unroll
;                 for (int nb = 0; nb < 4; ++nb) bq[ks & 3][nb] = *(const bf16x8*)(wb + (size_t)(16 * nb) * 512 + 32 * (ks + 4));
;             }
;         }
;     }
;     bf16_t* MIX = (bf16_t*)(A->ws + WS_MIX);
;     float bglv[4];
; #pragma unroll
;     for (int nb = 0; nb < 4; ++nb) bglv[nb] = A->in[22][l * 512 + 64 * wave + 16 * nb + (lane & 15)];
; #pragma unroll
;     for (int nb = 0; nb < 4; ++nb) { const int n = 64 * wave + 16 * nb + (lane & 15); const float bgl = bglv[nb];
; #pragma unroll
;         for (int mb = 0; mb < 4; ++mb)
; #pragma unroll
;             for (int i = 0; i < 4; ++i) { const int t = 16 * mb + 4 * (lane >> 4) + i; const float yv = bf2f(ys[t * YS_STRIDE + n]);
;                 MIX[(size_t)(rowbase + t) * DM + n] = f2bf(yv * sigmoidf_(acc[mb][nb][i] + bgl)); } }
	v_mfma_f32_16x16x32_bf16 v[88:91], v[92:95], v[36:39], v[130:133]
	v_mfma_f32_16x16x32_bf16 v[68:71], v[92:95], v[28:31], v[68:71]
	v_mfma_f32_16x16x32_bf16 v[76:79], v[92:95], v[24:27], v[76:79]
	v_mfma_f32_16x16x32_bf16 v[92:95], v[92:95], v[8:11], v[110:113]
	s_waitcnt lgkmcnt(1)
	v_mfma_f32_16x16x32_bf16 v[72:75], v[114:117], v[36:39], v[72:75]
	v_mfma_f32_16x16x32_bf16 v[80:83], v[114:117], v[28:31], v[80:83]
	v_mfma_f32_16x16x32_bf16 v[110:113], v[114:117], v[24:27], v[134:137]
	v_mfma_f32_16x16x32_bf16 v[114:117], v[114:117], v[8:11], v[122:125]
	s_waitcnt lgkmcnt(0)
	v_mfma_f32_16x16x32_bf16 v[36:39], v[118:121], v[36:39], v[60:63]
	v_mfma_f32_16x16x32_bf16 v[28:31], v[118:121], v[28:31], v[52:55]
	v_mfma_f32_16x16x32_bf16 v[24:27], v[118:121], v[24:27], v[44:47]
	v_mfma_f32_16x16x32_bf16 v[8:11], v[118:121], v[8:11], v[40:43]
	s_nop 2
	ds_read_b128 v[40:43], v67 offset:896
	ds_read_b128 v[44:47], v67 offset:17536
	ds_read_b128 v[52:55], v67 offset:34176
	ds_read_b128 v[60:63], v67 offset:50816
	s_waitcnt vmcnt(4)
	s_waitcnt lgkmcnt(3)
	v_mfma_f32_16x16x32_bf16 v[96:99], v[40:43], v[20:23], v[96:99]
	v_mfma_f32_16x16x32_bf16 v[100:103], v[40:43], v[12:15], v[100:103]
	v_mfma_f32_16x16x32_bf16 v[106:109], v[40:43], v[4:7], v[106:109]
	v_mfma_f32_16x16x32_bf16 v[40:43], v[40:43], v[0:3], v[84:87]
	s_waitcnt lgkmcnt(2)
	v_mfma_f32_16x16x32_bf16 v[84:87], v[44:47], v[20:23], v[88:91]
	v_mfma_f32_16x16x32_bf16 v[76:79], v[44:47], v[4:7], v[76:79]
	v_mfma_f32_16x16x32_bf16 v[88:91], v[44:47], v[0:3], v[92:95]
	s_waitcnt lgkmcnt(1)
	v_mfma_f32_16x16x32_bf16 v[92:95], v[52:55], v[4:7], v[110:113]
	v_mfma_f32_16x16x32_bf16 v[110:113], v[52:55], v[0:3], v[114:117]
	s_waitcnt lgkmcnt(0)
	v_mfma_f32_16x16x32_bf16 v[122:125], v[60:63], v[4:7], v[24:27]
	v_mfma_f32_16x16x32_bf16 v[0:3], v[60:63], v[0:3], v[8:11]
	ds_read_b128 v[4:7], v67 offset:960
	s_nop 1
	ds_read_b128 v[8:11], v67 offset:17600
	ds_read_b128 v[126:129], v67 offset:34240
	ds_read_b128 v[130:133], v67 offset:50880
	s_waitcnt vmcnt(0)
	s_load_dwordx2 s[4:5], s[26:27], 0xb0
	v_mfma_f32_16x16x32_bf16 v[68:71], v[44:47], v[12:15], v[68:71]
	v_lshl_add_u32 v67, v64, 1, 16
	v_mfma_f32_16x16x32_bf16 v[80:83], v[52:55], v[12:15], v[80:83]
	v_mfma_f32_16x16x32_bf16 v[114:117], v[60:63], v[20:23], v[36:39]
	v_mfma_f32_16x16x32_bf16 v[118:121], v[60:63], v[12:15], v[28:31]
	s_waitcnt lgkmcnt(0)
	v_mfma_f32_16x16x32_bf16 v[134:137], v[4:7], v[48:51], v[96:99]
	v_mfma_f32_16x16x32_bf16 v[44:47], v[4:7], v[32:35], v[100:103]
	v_mfma_f32_16x16x32_bf16 v[28:31], v[4:7], v[16:19], v[106:109]
	v_mfma_f32_16x16x32_bf16 v[12:15], v[4:7], v[56:59], v[40:43]
	v_mfma_f32_16x16x32_bf16 v[60:63], v[8:11], v[48:51], v[84:87]
	v_mfma_f32_16x16x32_bf16 v[40:43], v[8:11], v[32:35], v[68:71]
	v_mfma_f32_16x16x32_bf16 v[24:27], v[8:11], v[16:19], v[76:79]
	v_mfma_f32_16x16x32_bf16 v[8:11], v[8:11], v[56:59], v[88:91]
	s_nop 1
	v_lshl_add_u64 v[76:77], v[64:65], 1, s[2:3]
	v_mfma_f32_16x16x32_bf16 v[4:7], v[126:129], v[56:59], v[110:113]
	v_mfma_f32_16x16x32_bf16 v[0:3], v[130:133], v[56:59], v[0:3]
	v_or_b32_e32 v56, s11, v104
	v_ashrrev_i32_e32 v57, 31, v56
	v_lshl_add_u64 v[56:57], v[56:57], 2, s[4:5]
	v_mfma_f32_16x16x32_bf16 v[72:75], v[52:55], v[20:23], v[72:75]
	s_movk_i32 s4, 0x1040
	v_mfma_f32_16x16x32_bf16 v[20:23], v[126:129], v[16:19], v[92:95]
	global_load_dword v97, v[56:57], off
	global_load_dword v96, v[56:57], off offset:64
	s_nop 0
	global_load_dword v94, v[56:57], off offset:128
	global_load_dword v92, v[56:57], off offset:192
	v_mad_u32_u24 v95, v66, s4, v67
	ds_read_u16 v57, v95
	v_lshlrev_b32_e32 v56, 2, v66
	v_mfma_f32_16x16x32_bf16 v[52:55], v[126:129], v[48:51], v[72:75]
	v_or_b32_e32 v70, 48, v56
	s_movk_i32 s4, 0x410
	s_waitcnt lgkmcnt(0)
	v_lshlrev_b32_e32 v57, 16, v57
	v_or_b32_e32 v74, s10, v56
	v_ashrrev_i32_e32 v75, 31, v74
	v_mfma_f32_16x16x32_bf16 v[36:39], v[126:129], v[32:35], v[80:83]
	s_waitcnt vmcnt(3)
	v_add_f32_e32 v58, v134, v97
	v_mul_f32_e32 v58, 0xbfb8aa3b, v58
	v_exp_f32_e32 v58, v58
	v_add_f32_e32 v60, v60, v97
	v_mul_f32_e32 v60, 0xbfb8aa3b, v60
	v_exp_f32_e32 v60, v60
	v_add_f32_e32 v58, 1.0, v58
	v_rcp_f32_e32 v58, v58
	v_add_f32_e32 v61, v61, v97
	v_add_f32_e32 v60, 1.0, v60
	v_rcp_f32_e32 v60, v60
	v_mul_f32_e32 v57, v58, v57
	v_cvt_pk_bf16_f32 v65, v57, s0
	v_lshlrev_b64 v[56:57], 12, v[74:75]
	v_lshl_add_u64 v[58:59], v[76:77], 0, v[56:57]
	global_store_short v[58:59], v65, off
	v_add_f32_e32 v59, v135, v97
	v_mul_f32_e32 v59, 0xbfb8aa3b, v59
	v_exp_f32_e32 v59, v59
	v_mad_u32_u24 v65, v70, s4, v67
	v_add_u32_e32 v93, 0xffff4110, v65
	ds_read_u16 v58, v93
	v_add_f32_e32 v59, 1.0, v59
	v_rcp_f32_e32 v59, v59
	v_mul_f32_e32 v61, 0xbfb8aa3b, v61
	v_exp_f32_e32 v61, v61
	s_waitcnt lgkmcnt(0)
	v_lshlrev_b32_e32 v58, 16, v58
	v_mul_f32_e32 v58, v59, v58
	v_cvt_pk_bf16_f32 v68, v58, s0
	v_or_b32_e32 v58, 1, v74
	v_ashrrev_i32_e32 v59, 31, v58
	v_lshlrev_b64 v[58:59], 12, v[58:59]
	v_lshl_add_u64 v[66:67], v[76:77], 0, v[58:59]
	global_store_short v[66:67], v68, off
	v_add_f32_e32 v67, v136, v97
	v_mul_f32_e32 v67, 0xbfb8aa3b, v67
	v_exp_f32_e32 v67, v67
	ds_read_u16 v66, v93 offset:1040
	v_add_f32_e32 v61, 1.0, v61
	v_rcp_f32_e32 v61, v61
	v_add_f32_e32 v67, 1.0, v67
	v_rcp_f32_e32 v67, v67
	s_waitcnt lgkmcnt(0)
	v_lshlrev_b32_e32 v66, 16, v66
	v_add_f32_e32 v62, v62, v97
	v_mul_f32_e32 v62, 0xbfb8aa3b, v62
	v_mul_f32_e32 v66, v67, v66
	v_cvt_pk_bf16_f32 v71, v66, s0
	v_or_b32_e32 v66, 2, v74
	v_ashrrev_i32_e32 v67, 31, v66
	v_lshlrev_b64 v[66:67], 12, v[66:67]
	v_lshl_add_u64 v[68:69], v[76:77], 0, v[66:67]
	global_store_short v[68:69], v71, off
	v_add_f32_e32 v69, v137, v97
	v_mul_f32_e32 v69, 0xbfb8aa3b, v69
	v_exp_f32_e32 v69, v69
	ds_read_u16 v68, v93 offset:2080
	v_exp_f32_e32 v62, v62
	v_add_f32_e32 v63, v63, v97
	v_add_f32_e32 v69, 1.0, v69
	v_rcp_f32_e32 v69, v69
	s_waitcnt lgkmcnt(0)
; __device__ __forceinline__ float bf2f(unsigned short h) { return __uint_as_float(((unsigned)h) << 16); }
; __device__ __forceinline__ unsigned short f2bf(float f) { return (unsigned short)(cvt_pk(f, 0.f) & 0xffffu); }
; __device__ __forceinline__ float sigmoidf_(float x) { return fast_rcp(1.f + fast_exp2(-x * LOG2E)); }
; __device__ __forceinline__ void s5_unit(ArgsP A, int l, int unit, unsigned char* lds, int wave_, int lane_) {
;     ...
;     for (int nb = 0; nb < 4; ++nb) { const int n = 64 * wave + 16 * nb + (lane & 15); const float bgl = bglv[nb];
; #pragma unroll
;         for (int mb = 0; mb < 4; ++mb)
; #pragma unroll
;             for (int i = 0; i < 4; ++i) { const int t = 16 * mb + 4 * (lane >> 4) + i; const float yv = bf2f(ys[t * YS_STRIDE + n]);
;                 MIX[(size_t)(rowbase + t) * DM + n] = f2bf(yv * sigmoidf_(acc[mb][nb][i] + bgl)); } }
	v_lshlrev_b32_e32 v68, 16, v68
	v_add_f32_e32 v62, 1.0, v62
	v_rcp_f32_e32 v62, v62
	v_mul_f32_e32 v68, v69, v68
	v_cvt_pk_bf16_f32 v71, v68, s0
	v_or_b32_e32 v68, 3, v74
	v_ashrrev_i32_e32 v69, 31, v68
	v_lshlrev_b64 v[78:79], 12, v[68:69]
	v_lshl_add_u64 v[68:69], v[76:77], 0, v[78:79]
	global_store_short v[68:69], v71, off
	ds_read_u16 v68, v93 offset:15600
	v_mul_f32_e32 v63, 0xbfb8aa3b, v63
	v_exp_f32_e32 v63, v63
	v_add_f32_e32 v52, v52, v97
	v_mul_f32_e32 v52, 0xbfb8aa3b, v52
	s_waitcnt lgkmcnt(0)
	v_lshlrev_b32_e32 v68, 16, v68
	v_mul_f32_e32 v60, v60, v68
	v_or_b32_e32 v68, 16, v74
	v_ashrrev_i32_e32 v69, 31, v68
	v_lshlrev_b64 v[80:81], 12, v[68:69]
	v_cvt_pk_bf16_f32 v60, v60, s0
	v_lshl_add_u64 v[68:69], v[76:77], 0, v[80:81]
	global_store_short v[68:69], v60, off
	ds_read_u16 v60, v93 offset:16640
	v_add_f32_e32 v63, 1.0, v63
	v_rcp_f32_e32 v63, v63
	v_exp_f32_e32 v52, v52
	v_add_f32_e32 v53, v53, v97
	s_waitcnt lgkmcnt(0)
	v_lshlrev_b32_e32 v60, 16, v60
	v_mul_f32_e32 v60, v61, v60
	v_cvt_pk_bf16_f32 v71, v60, s0
	v_or_b32_e32 v60, 17, v74
	v_ashrrev_i32_e32 v61, 31, v60
	v_lshlrev_b64 v[60:61], 12, v[60:61]
	v_lshl_add_u64 v[68:69], v[76:77], 0, v[60:61]
	global_store_short v[68:69], v71, off
	ds_read_u16 v68, v93 offset:17680
	v_add_f32_e32 v52, 1.0, v52
	v_rcp_f32_e32 v52, v52
	v_mul_f32_e32 v53, 0xbfb8aa3b, v53
	v_exp_f32_e32 v53, v53
	s_waitcnt lgkmcnt(0)
	v_lshlrev_b32_e32 v68, 16, v68
	v_mul_f32_e32 v62, v62, v68
	v_or_b32_e32 v68, 18, v74
	v_ashrrev_i32_e32 v69, 31, v68
	v_lshlrev_b64 v[82:83], 12, v[68:69]
	v_cvt_pk_bf16_f32 v62, v62, s0
	v_lshl_add_u64 v[68:69], v[76:77], 0, v[82:83]
	global_store_short v[68:69], v62, off
	ds_read_u16 v62, v93 offset:18720
	v_add_f32_e32 v53, 1.0, v53
	v_rcp_f32_e32 v53, v53
	v_mfma_f32_16x16x32_bf16 v[48:51], v[130:133], v[48:51], v[114:117]
	s_waitcnt vmcnt(9)
	v_add_f32_e32 v44, v44, v96
	s_waitcnt lgkmcnt(0)
	v_lshlrev_b32_e32 v62, 16, v62
	v_mul_f32_e32 v62, v63, v62
	v_cvt_pk_bf16_f32 v71, v62, s0
	v_or_b32_e32 v62, 19, v74
	v_ashrrev_i32_e32 v63, 31, v62
	v_lshlrev_b64 v[62:63], 12, v[62:63]
	v_lshl_add_u64 v[68:69], v[76:77], 0, v[62:63]
	global_store_short v[68:69], v71, off
	ds_read_u16 v68, v93 offset:32240
	v_add_f32_e32 v48, v48, v97
	v_mul_f32_e32 v48, 0xbfb8aa3b, v48
	v_exp_f32_e32 v48, v48
	v_add_f32_e32 v49, v49, v97
	s_waitcnt lgkmcnt(0)
	v_lshlrev_b32_e32 v68, 16, v68
	v_mul_f32_e32 v52, v52, v68
	v_or_b32_e32 v68, 32, v74
	v_ashrrev_i32_e32 v69, 31, v68
	v_lshlrev_b64 v[84:85], 12, v[68:69]
	v_cvt_pk_bf16_f32 v52, v52, s0
	v_lshl_add_u64 v[68:69], v[76:77], 0, v[84:85]
	global_store_short v[68:69], v52, off
	ds_read_u16 v52, v93 offset:33280
	v_add_f32_e32 v48, 1.0, v48
	v_rcp_f32_e32 v48, v48
	v_mul_f32_e32 v49, 0xbfb8aa3b, v49
	v_exp_f32_e32 v49, v49
	s_waitcnt lgkmcnt(0)
	v_lshlrev_b32_e32 v52, 16, v52
	v_mul_f32_e32 v52, v53, v52
	v_cvt_pk_bf16_f32 v68, v52, s0
	v_or_b32_e32 v52, 33, v74
	v_ashrrev_i32_e32 v53, 31, v52
	v_lshlrev_b64 v[86:87], 12, v[52:53]
	v_lshl_add_u64 v[52:53], v[76:77], 0, v[86:87]
	global_store_short v[52:53], v68, off
	v_add_f32_e32 v53, v54, v97
	v_mul_f32_e32 v53, 0xbfb8aa3b, v53
	v_exp_f32_e32 v53, v53
	ds_read_u16 v52, v93 offset:34320
	v_add_f32_e32 v49, 1.0, v49
	v_rcp_f32_e32 v49, v49
	v_add_f32_e32 v53, 1.0, v53
	v_rcp_f32_e32 v53, v53
	s_waitcnt lgkmcnt(0)
	v_lshlrev_b32_e32 v52, 16, v52
	v_mul_f32_e32 v44, 0xbfb8aa3b, v44
	v_exp_f32_e32 v44, v44
	v_mul_f32_e32 v52, v53, v52
	v_cvt_pk_bf16_f32 v54, v52, s0
	v_or_b32_e32 v52, 34, v74
	v_ashrrev_i32_e32 v53, 31, v52
	v_lshlrev_b64 v[88:89], 12, v[52:53]
	v_lshl_add_u64 v[52:53], v[76:77], 0, v[88:89]
	global_store_short v[52:53], v54, off
	v_add_f32_e32 v53, v55, v97
	v_mul_f32_e32 v53, 0xbfb8aa3b, v53
	v_exp_f32_e32 v53, v53
	ds_read_u16 v52, v93 offset:35360
	v_add_f32_e32 v44, 1.0, v44
	v_rcp_f32_e32 v44, v44
	v_add_f32_e32 v53, 1.0, v53
	v_rcp_f32_e32 v53, v53
	s_waitcnt lgkmcnt(0)
	v_lshlrev_b32_e32 v52, 16, v52
	v_add_f32_e32 v45, v45, v96
	v_mul_f32_e32 v45, 0xbfb8aa3b, v45
	v_mul_f32_e32 v52, v53, v52
	v_cvt_pk_bf16_f32 v54, v52, s0
	v_or_b32_e32 v52, 35, v74
	v_ashrrev_i32_e32 v53, 31, v52
	v_lshlrev_b64 v[90:91], 12, v[52:53]
	v_lshl_add_u64 v[52:53], v[76:77], 0, v[90:91]
	global_store_short v[52:53], v54, off
	ds_read_u16 v52, v65
	v_exp_f32_e32 v45, v45
	v_add_f32_e32 v46, v46, v96
	v_mul_f32_e32 v46, 0xbfb8aa3b, v46
	v_exp_f32_e32 v46, v46
	s_waitcnt lgkmcnt(0)
	v_lshlrev_b32_e32 v52, 16, v52
	v_mul_f32_e32 v48, v48, v52
	v_or_b32_e32 v52, s10, v70
	v_ashrrev_i32_e32 v53, 31, v52
	v_lshlrev_b64 v[68:69], 12, v[52:53]
	v_cvt_pk_bf16_f32 v48, v48, s0
	v_lshl_add_u64 v[52:53], v[76:77], 0, v[68:69]
	global_store_short v[52:53], v48, off
	ds_read_u16 v48, v65 offset:1040
	v_add_f32_e32 v45, 1.0, v45
	v_rcp_f32_e32 v45, v45
	v_add_f32_e32 v46, 1.0, v46
	v_rcp_f32_e32 v46, v46
	s_waitcnt lgkmcnt(0)
	v_lshlrev_b32_e32 v48, 16, v48
	v_mul_f32_e32 v48, v49, v48
	v_cvt_pk_bf16_f32 v52, v48, s0
	v_or_b32_e32 v48, 49, v74
	v_ashrrev_i32_e32 v49, 31, v48
	v_lshlrev_b64 v[70:71], 12, v[48:49]
	v_lshl_add_u64 v[48:49], v[76:77], 0, v[70:71]
	global_store_short v[48:49], v52, off
	v_add_f32_e32 v49, v50, v97
	v_mul_f32_e32 v49, 0xbfb8aa3b, v49
	v_exp_f32_e32 v49, v49
	ds_read_u16 v48, v65 offset:2080
	v_add_f32_e32 v47, v47, v96
	v_mul_f32_e32 v47, 0xbfb8aa3b, v47
	v_add_f32_e32 v49, 1.0, v49
	v_rcp_f32_e32 v49, v49
	s_waitcnt lgkmcnt(0)
; __device__ __forceinline__ float bf2f(unsigned short h) { return __uint_as_float(((unsigned)h) << 16); }
; __device__ __forceinline__ unsigned short f2bf(float f) { return (unsigned short)(cvt_pk(f, 0.f) & 0xffffu); }
; __device__ __forceinline__ float sigmoidf_(float x) { return fast_rcp(1.f + fast_exp2(-x * LOG2E)); }
; __device__ __forceinline__ void s5_unit(ArgsP A, int l, int unit, unsigned char* lds, int wave_, int lane_) {
;     ...
;     for (int nb = 0; nb < 4; ++nb) { const int n = 64 * wave + 16 * nb + (lane & 15); const float bgl = bglv[nb];
; #pragma unroll
;         for (int mb = 0; mb < 4; ++mb)
; #pragma unroll
;             for (int i = 0; i < 4; ++i) { const int t = 16 * mb + 4 * (lane >> 4) + i; const float yv = bf2f(ys[t * YS_STRIDE + n]);
;                 MIX[(size_t)(rowbase + t) * DM + n] = f2bf(yv * sigmoidf_(acc[mb][nb][i] + bgl)); } }
	v_lshlrev_b32_e32 v48, 16, v48
	v_exp_f32_e32 v47, v47
	v_add_f32_e32 v40, v40, v96
	v_mul_f32_e32 v48, v49, v48
	v_cvt_pk_bf16_f32 v50, v48, s0
	v_or_b32_e32 v48, 50, v74
	v_ashrrev_i32_e32 v49, 31, v48
	v_lshlrev_b64 v[72:73], 12, v[48:49]
	v_lshl_add_u64 v[48:49], v[76:77], 0, v[72:73]
	global_store_short v[48:49], v50, off
	v_add_f32_e32 v49, v51, v97
	v_mul_f32_e32 v49, 0xbfb8aa3b, v49
	v_exp_f32_e32 v49, v49
	ds_read_u16 v48, v65 offset:3120
	v_add_f32_e32 v47, 1.0, v47
	v_rcp_f32_e32 v47, v47
	v_add_f32_e32 v49, 1.0, v49
	v_rcp_f32_e32 v49, v49
	s_waitcnt lgkmcnt(0)
	v_lshlrev_b32_e32 v48, 16, v48
	v_mul_f32_e32 v40, 0xbfb8aa3b, v40
	v_exp_f32_e32 v40, v40
	v_mul_f32_e32 v48, v49, v48
	v_cvt_pk_bf16_f32 v50, v48, s0
	v_or_b32_e32 v48, 51, v74
	v_ashrrev_i32_e32 v49, 31, v48
	v_lshlrev_b64 v[74:75], 12, v[48:49]
	v_lshl_add_u64 v[48:49], v[76:77], 0, v[74:75]
	global_store_short v[48:49], v50, off
	ds_read_u16 v48, v95 offset:32
	v_or_b32_e32 v50, 16, v64
	v_ashrrev_i32_e32 v51, 31, v50
	v_lshlrev_b64 v[76:77], 1, v[50:51]
	v_add_f32_e32 v40, 1.0, v40
	s_waitcnt lgkmcnt(0)
	v_lshlrev_b32_e32 v48, 16, v48
	v_mul_f32_e32 v44, v44, v48
	v_lshl_add_u64 v[48:49], s[2:3], 0, v[56:57]
	v_cvt_pk_bf16_f32 v44, v44, s0
	v_lshl_add_u64 v[50:51], v[48:49], 0, v[76:77]
	global_store_short v[50:51], v44, off
	ds_read_u16 v44, v93 offset:32
	v_rcp_f32_e32 v40, v40
	v_add_f32_e32 v41, v41, v96
	v_mul_f32_e32 v41, 0xbfb8aa3b, v41
	v_exp_f32_e32 v41, v41
	s_waitcnt lgkmcnt(0)
	v_lshlrev_b32_e32 v44, 16, v44
	v_mul_f32_e32 v44, v45, v44
	v_cvt_pk_bf16_f32 v52, v44, s0
	v_lshl_add_u64 v[44:45], s[2:3], 0, v[58:59]
	v_lshl_add_u64 v[50:51], v[44:45], 0, v[76:77]
	global_store_short v[50:51], v52, off
	ds_read_u16 v50, v93 offset:1072
	v_add_f32_e32 v41, 1.0, v41
	v_rcp_f32_e32 v41, v41
	v_add_f32_e32 v36, v36, v96
	v_mul_f32_e32 v36, 0xbfb8aa3b, v36
	s_waitcnt lgkmcnt(0)
	v_lshlrev_b32_e32 v50, 16, v50
	v_mul_f32_e32 v46, v46, v50
	v_lshl_add_u64 v[50:51], s[2:3], 0, v[66:67]
	v_cvt_pk_bf16_f32 v46, v46, s0
	v_lshl_add_u64 v[52:53], v[50:51], 0, v[76:77]
	global_store_short v[52:53], v46, off
	ds_read_u16 v46, v93 offset:2112
	v_exp_f32_e32 v36, v36
	v_add_f32_e32 v37, v37, v96
	v_mul_f32_e32 v37, 0xbfb8aa3b, v37
	v_exp_f32_e32 v37, v37
	s_waitcnt lgkmcnt(0)
	v_lshlrev_b32_e32 v46, 16, v46
	v_mul_f32_e32 v46, v47, v46
	v_cvt_pk_bf16_f32 v54, v46, s0
	v_lshl_add_u64 v[46:47], s[2:3], 0, v[78:79]
	v_lshl_add_u64 v[52:53], v[46:47], 0, v[76:77]
	global_store_short v[52:53], v54, off
	ds_read_u16 v52, v93 offset:15632
	v_add_f32_e32 v36, 1.0, v36
	v_rcp_f32_e32 v36, v36
	v_add_f32_e32 v37, 1.0, v37
	v_rcp_f32_e32 v37, v37
	s_waitcnt lgkmcnt(0)
	v_lshlrev_b32_e32 v52, 16, v52
	v_mul_f32_e32 v40, v40, v52
	v_lshl_add_u64 v[52:53], s[2:3], 0, v[80:81]
	v_cvt_pk_bf16_f32 v40, v40, s0
	v_lshl_add_u64 v[54:55], v[52:53], 0, v[76:77]
	global_store_short v[54:55], v40, off
	ds_read_u16 v40, v93 offset:16672
	v_lshl_add_u64 v[54:55], s[2:3], 0, v[60:61]
	v_lshl_add_u64 v[60:61], s[2:3], 0, v[86:87]
	v_mfma_f32_16x16x32_bf16 v[32:35], v[130:133], v[32:35], v[118:121]
	v_lshl_add_u64 v[66:67], s[2:3], 0, v[90:91]
	s_waitcnt lgkmcnt(0)
	v_lshlrev_b32_e32 v40, 16, v40
	v_mul_f32_e32 v40, v41, v40
	v_cvt_pk_bf16_f32 v56, v40, s0
	v_lshl_add_u64 v[40:41], v[54:55], 0, v[76:77]
	global_store_short v[40:41], v56, off
	v_add_f32_e32 v41, v42, v96
	v_mul_f32_e32 v41, 0xbfb8aa3b, v41
	v_exp_f32_e32 v41, v41
	ds_read_u16 v40, v93 offset:17712
	v_lshl_add_u64 v[56:57], s[2:3], 0, v[82:83]
	v_add_f32_e32 v32, v32, v96
	v_add_f32_e32 v41, 1.0, v41
	v_rcp_f32_e32 v41, v41
	s_waitcnt lgkmcnt(0)
	v_lshlrev_b32_e32 v40, 16, v40
	v_mul_f32_e32 v32, 0xbfb8aa3b, v32
	v_exp_f32_e32 v32, v32
	v_mul_f32_e32 v40, v41, v40
	v_cvt_pk_bf16_f32 v42, v40, s0
	v_lshl_add_u64 v[40:41], v[56:57], 0, v[76:77]
	global_store_short v[40:41], v42, off
	v_add_f32_e32 v41, v43, v96
	v_mul_f32_e32 v41, 0xbfb8aa3b, v41
	v_exp_f32_e32 v41, v41
	ds_read_u16 v40, v93 offset:18752
	v_lshl_add_u64 v[42:43], s[2:3], 0, v[62:63]
	v_lshl_add_u64 v[62:63], s[2:3], 0, v[88:89]
	v_add_f32_e32 v41, 1.0, v41
	v_rcp_f32_e32 v41, v41
	s_waitcnt lgkmcnt(0)
	v_lshlrev_b32_e32 v40, 16, v40
	v_add_f32_e32 v32, 1.0, v32
	v_rcp_f32_e32 v32, v32
	v_mul_f32_e32 v40, v41, v40
	v_cvt_pk_bf16_f32 v58, v40, s0
	v_lshl_add_u64 v[40:41], v[42:43], 0, v[76:77]
	global_store_short v[40:41], v58, off
	ds_read_u16 v40, v93 offset:32272
	v_lshl_add_u64 v[58:59], s[2:3], 0, v[84:85]
	v_add_f32_e32 v33, v33, v96
	v_mul_f32_e32 v33, 0xbfb8aa3b, v33
	v_exp_f32_e32 v33, v33
	s_waitcnt lgkmcnt(0)
	v_lshlrev_b32_e32 v40, 16, v40
	v_mul_f32_e32 v36, v36, v40
	v_cvt_pk_bf16_f32 v36, v36, s0
	v_lshl_add_u64 v[40:41], v[58:59], 0, v[76:77]
	global_store_short v[40:41], v36, off
	ds_read_u16 v36, v93 offset:33312
	v_add_f32_e32 v33, 1.0, v33
	v_rcp_f32_e32 v33, v33
	s_waitcnt vmcnt(26)
	v_add_f32_e32 v28, v28, v94
	v_mul_f32_e32 v28, 0xbfb8aa3b, v28
	s_waitcnt lgkmcnt(0)
	v_lshlrev_b32_e32 v36, 16, v36
	v_mul_f32_e32 v36, v37, v36
	v_cvt_pk_bf16_f32 v40, v36, s0
	v_lshl_add_u64 v[36:37], v[60:61], 0, v[76:77]
	global_store_short v[36:37], v40, off
	v_add_f32_e32 v37, v38, v96
	v_mul_f32_e32 v37, 0xbfb8aa3b, v37
	v_exp_f32_e32 v37, v37
	ds_read_u16 v36, v93 offset:34352
	v_exp_f32_e32 v28, v28
	v_add_f32_e32 v29, v29, v94
	v_add_f32_e32 v37, 1.0, v37
	v_rcp_f32_e32 v37, v37
	s_waitcnt lgkmcnt(0)
	v_lshlrev_b32_e32 v36, 16, v36
	v_add_f32_e32 v28, 1.0, v28
	v_rcp_f32_e32 v28, v28
	v_mul_f32_e32 v36, v37, v36
	v_cvt_pk_bf16_f32 v38, v36, s0
	v_lshl_add_u64 v[36:37], v[62:63], 0, v[76:77]
	global_store_short v[36:37], v38, off
	v_add_f32_e32 v37, v39, v96
	v_mul_f32_e32 v37, 0xbfb8aa3b, v37
	v_exp_f32_e32 v37, v37
	ds_read_u16 v36, v93 offset:35392
	v_mul_f32_e32 v29, 0xbfb8aa3b, v29
	v_exp_f32_e32 v29, v29
	v_add_f32_e32 v37, 1.0, v37
	v_rcp_f32_e32 v37, v37
	s_waitcnt lgkmcnt(0)
; __device__ __forceinline__ float bf2f(unsigned short h) { return __uint_as_float(((unsigned)h) << 16); }
; __device__ __forceinline__ unsigned short f2bf(float f) { return (unsigned short)(cvt_pk(f, 0.f) & 0xffffu); }
; __device__ __forceinline__ float sigmoidf_(float x) { return fast_rcp(1.f + fast_exp2(-x * LOG2E)); }
; __device__ __forceinline__ void s5_unit(ArgsP A, int l, int unit, unsigned char* lds, int wave_, int lane_) {
;     ...
;     for (int nb = 0; nb < 4; ++nb) { const int n = 64 * wave + 16 * nb + (lane & 15); const float bgl = bglv[nb];
; #pragma unroll
;         for (int mb = 0; mb < 4; ++mb)
; #pragma unroll
;             for (int i = 0; i < 4; ++i) { const int t = 16 * mb + 4 * (lane >> 4) + i; const float yv = bf2f(ys[t * YS_STRIDE + n]);
;                 MIX[(size_t)(rowbase + t) * DM + n] = f2bf(yv * sigmoidf_(acc[mb][nb][i] + bgl)); } }
	v_lshlrev_b32_e32 v36, 16, v36
	v_add_f32_e32 v29, 1.0, v29
	v_rcp_f32_e32 v29, v29
	v_mul_f32_e32 v36, v37, v36
	v_cvt_pk_bf16_f32 v38, v36, s0
	v_lshl_add_u64 v[36:37], v[66:67], 0, v[76:77]
	global_store_short v[36:37], v38, off
	ds_read_u16 v36, v65 offset:32
	v_add_f32_e32 v24, v24, v94
	v_mul_f32_e32 v24, 0xbfb8aa3b, v24
	v_exp_f32_e32 v24, v24
	v_add_f32_e32 v25, v25, v94
	s_waitcnt lgkmcnt(0)
	v_lshlrev_b32_e32 v36, 16, v36
	v_mul_f32_e32 v32, v32, v36
	v_lshl_add_u64 v[36:37], s[2:3], 0, v[68:69]
	v_cvt_pk_bf16_f32 v32, v32, s0
	v_lshl_add_u64 v[38:39], v[36:37], 0, v[76:77]
	global_store_short v[38:39], v32, off
	ds_read_u16 v32, v65 offset:1072
	v_lshl_add_u64 v[38:39], s[2:3], 0, v[70:71]
	v_add_f32_e32 v24, 1.0, v24
	v_rcp_f32_e32 v24, v24
	v_mul_f32_e32 v25, 0xbfb8aa3b, v25
	s_waitcnt lgkmcnt(0)
	v_lshlrev_b32_e32 v32, 16, v32
	v_mul_f32_e32 v32, v33, v32
	v_cvt_pk_bf16_f32 v40, v32, s0
	v_lshl_add_u64 v[32:33], v[38:39], 0, v[76:77]
	global_store_short v[32:33], v40, off
	v_add_f32_e32 v33, v34, v96
	v_mul_f32_e32 v33, 0xbfb8aa3b, v33
	v_exp_f32_e32 v33, v33
	ds_read_u16 v32, v65 offset:2112
	v_lshl_add_u64 v[40:41], s[2:3], 0, v[72:73]
	v_exp_f32_e32 v25, v25
	v_add_f32_e32 v33, 1.0, v33
	v_rcp_f32_e32 v33, v33
	s_waitcnt lgkmcnt(0)
	v_lshlrev_b32_e32 v32, 16, v32
	v_add_f32_e32 v25, 1.0, v25
	v_rcp_f32_e32 v25, v25
	v_mul_f32_e32 v32, v33, v32
	v_cvt_pk_bf16_f32 v34, v32, s0
	v_lshl_add_u64 v[32:33], v[40:41], 0, v[76:77]
	global_store_short v[32:33], v34, off
	v_add_f32_e32 v33, v35, v96
	v_mul_f32_e32 v33, 0xbfb8aa3b, v33
	v_exp_f32_e32 v33, v33
	ds_read_u16 v32, v65 offset:3152
	v_add_f32_e32 v20, v20, v94
	v_mul_f32_e32 v20, 0xbfb8aa3b, v20
	v_add_f32_e32 v33, 1.0, v33
	v_rcp_f32_e32 v33, v33
	s_waitcnt lgkmcnt(0)
	v_lshlrev_b32_e32 v32, 16, v32
	v_exp_f32_e32 v20, v20
	v_add_f32_e32 v21, v21, v94
	v_mul_f32_e32 v32, v33, v32
	v_cvt_pk_bf16_f32 v68, v32, s0
	v_lshl_add_u64 v[32:33], s[2:3], 0, v[74:75]
	v_lshl_add_u64 v[34:35], v[32:33], 0, v[76:77]
	global_store_short v[34:35], v68, off
	ds_read_u16 v68, v95 offset:64
	v_or_b32_e32 v34, 32, v64
	v_ashrrev_i32_e32 v35, 31, v34
	v_lshlrev_b64 v[34:35], 1, v[34:35]
	v_add_f32_e32 v20, 1.0, v20
	s_waitcnt lgkmcnt(0)
	v_lshlrev_b32_e32 v68, 16, v68
	v_mul_f32_e32 v28, v28, v68
	v_cvt_pk_bf16_f32 v28, v28, s0
	v_lshl_add_u64 v[68:69], v[48:49], 0, v[34:35]
	global_store_short v[68:69], v28, off
	ds_read_u16 v28, v93 offset:64
	v_rcp_f32_e32 v20, v20
	v_mul_f32_e32 v21, 0xbfb8aa3b, v21
	v_exp_f32_e32 v21, v21
	v_mfma_f32_16x16x32_bf16 v[16:19], v[130:133], v[16:19], v[122:125]
	s_waitcnt lgkmcnt(0)
	v_lshlrev_b32_e32 v28, 16, v28
	v_mul_f32_e32 v28, v29, v28
	v_cvt_pk_bf16_f32 v68, v28, s0
	v_lshl_add_u64 v[28:29], v[44:45], 0, v[34:35]
	global_store_short v[28:29], v68, off
	v_add_f32_e32 v29, v30, v94
	v_mul_f32_e32 v29, 0xbfb8aa3b, v29
	v_exp_f32_e32 v29, v29
	ds_read_u16 v28, v93 offset:1104
	v_add_f32_e32 v21, 1.0, v21
	v_rcp_f32_e32 v21, v21
	v_add_f32_e32 v29, 1.0, v29
	v_rcp_f32_e32 v29, v29
	s_waitcnt lgkmcnt(0)
	v_lshlrev_b32_e32 v28, 16, v28
	v_add_f32_e32 v16, v16, v94
	v_mul_f32_e32 v16, 0xbfb8aa3b, v16
	v_mul_f32_e32 v28, v29, v28
	v_cvt_pk_bf16_f32 v30, v28, s0
	v_lshl_add_u64 v[28:29], v[50:51], 0, v[34:35]
	global_store_short v[28:29], v30, off
	v_add_f32_e32 v29, v31, v94
	v_mul_f32_e32 v29, 0xbfb8aa3b, v29
	v_exp_f32_e32 v29, v29
	ds_read_u16 v28, v93 offset:2144
	v_exp_f32_e32 v16, v16
	v_add_f32_e32 v17, v17, v94
	v_add_f32_e32 v29, 1.0, v29
	v_rcp_f32_e32 v29, v29
	s_waitcnt lgkmcnt(0)
	v_lshlrev_b32_e32 v28, 16, v28
	v_add_f32_e32 v16, 1.0, v16
	v_rcp_f32_e32 v16, v16
	v_mul_f32_e32 v28, v29, v28
	v_cvt_pk_bf16_f32 v30, v28, s0
	v_lshl_add_u64 v[28:29], v[46:47], 0, v[34:35]
	global_store_short v[28:29], v30, off
	ds_read_u16 v28, v93 offset:15664
	v_mul_f32_e32 v17, 0xbfb8aa3b, v17
	v_exp_f32_e32 v17, v17
	s_waitcnt vmcnt(36)
	v_add_f32_e32 v12, v12, v92
	v_mul_f32_e32 v12, 0xbfb8aa3b, v12
	s_waitcnt lgkmcnt(0)
	v_lshlrev_b32_e32 v28, 16, v28
	v_mul_f32_e32 v24, v24, v28
	v_cvt_pk_bf16_f32 v24, v24, s0
	v_lshl_add_u64 v[28:29], v[52:53], 0, v[34:35]
	global_store_short v[28:29], v24, off
	ds_read_u16 v24, v93 offset:16704
	v_add_f32_e32 v17, 1.0, v17
	v_rcp_f32_e32 v17, v17
	v_exp_f32_e32 v12, v12
	v_add_f32_e32 v13, v13, v92
	s_waitcnt lgkmcnt(0)
	v_lshlrev_b32_e32 v24, 16, v24
	v_mul_f32_e32 v24, v25, v24
	v_cvt_pk_bf16_f32 v28, v24, s0
	v_lshl_add_u64 v[24:25], v[54:55], 0, v[34:35]
	global_store_short v[24:25], v28, off
	v_add_f32_e32 v25, v26, v94
	v_mul_f32_e32 v25, 0xbfb8aa3b, v25
	v_exp_f32_e32 v25, v25
	ds_read_u16 v24, v93 offset:17744
	v_add_f32_e32 v12, 1.0, v12
	v_rcp_f32_e32 v12, v12
	v_add_f32_e32 v25, 1.0, v25
	v_rcp_f32_e32 v25, v25
	s_waitcnt lgkmcnt(0)
	v_lshlrev_b32_e32 v24, 16, v24
	v_mul_f32_e32 v13, 0xbfb8aa3b, v13
	v_exp_f32_e32 v13, v13
	v_mul_f32_e32 v24, v25, v24
	v_cvt_pk_bf16_f32 v26, v24, s0
	v_lshl_add_u64 v[24:25], v[56:57], 0, v[34:35]
	global_store_short v[24:25], v26, off
	v_add_f32_e32 v25, v27, v94
	v_mul_f32_e32 v25, 0xbfb8aa3b, v25
	v_exp_f32_e32 v25, v25
	ds_read_u16 v24, v93 offset:18784
	v_add_f32_e32 v13, 1.0, v13
	v_rcp_f32_e32 v13, v13
	v_add_f32_e32 v25, 1.0, v25
	v_rcp_f32_e32 v25, v25
	s_waitcnt lgkmcnt(0)
	v_lshlrev_b32_e32 v24, 16, v24
	v_add_f32_e32 v8, v8, v92
	v_mul_f32_e32 v8, 0xbfb8aa3b, v8
	v_mul_f32_e32 v24, v25, v24
	v_cvt_pk_bf16_f32 v26, v24, s0
	v_lshl_add_u64 v[24:25], v[42:43], 0, v[34:35]
	global_store_short v[24:25], v26, off
	ds_read_u16 v24, v93 offset:32304
	v_exp_f32_e32 v8, v8
	v_add_f32_e32 v9, v9, v92
	v_mul_f32_e32 v9, 0xbfb8aa3b, v9
	v_exp_f32_e32 v9, v9
	s_waitcnt lgkmcnt(0)
; __device__ __forceinline__ float bf2f(unsigned short h) { return __uint_as_float(((unsigned)h) << 16); }
; __device__ __forceinline__ unsigned short f2bf(float f) { return (unsigned short)(cvt_pk(f, 0.f) & 0xffffu); }
; __device__ __forceinline__ float sigmoidf_(float x) { return fast_rcp(1.f + fast_exp2(-x * LOG2E)); }
; __device__ __forceinline__ void s5_unit(ArgsP A, int l, int unit, unsigned char* lds, int wave_, int lane_) {
;     ...
;     for (int nb = 0; nb < 4; ++nb) { const int n = 64 * wave + 16 * nb + (lane & 15); const float bgl = bglv[nb];
; #pragma unroll
;         for (int mb = 0; mb < 4; ++mb)
; #pragma unroll
;             for (int i = 0; i < 4; ++i) { const int t = 16 * mb + 4 * (lane >> 4) + i; const float yv = bf2f(ys[t * YS_STRIDE + n]);
;                 MIX[(size_t)(rowbase + t) * DM + n] = f2bf(yv * sigmoidf_(acc[mb][nb][i] + bgl)); } }
	v_lshlrev_b32_e32 v24, 16, v24
	v_mul_f32_e32 v20, v20, v24
	v_cvt_pk_bf16_f32 v20, v20, s0
	v_lshl_add_u64 v[24:25], v[58:59], 0, v[34:35]
	global_store_short v[24:25], v20, off
	ds_read_u16 v20, v93 offset:33344
	v_add_f32_e32 v8, 1.0, v8
	v_rcp_f32_e32 v8, v8
	v_add_f32_e32 v9, 1.0, v9
	v_rcp_f32_e32 v9, v9
	s_waitcnt lgkmcnt(0)
	v_lshlrev_b32_e32 v20, 16, v20
	v_mul_f32_e32 v20, v21, v20
	v_cvt_pk_bf16_f32 v24, v20, s0
	v_lshl_add_u64 v[20:21], v[60:61], 0, v[34:35]
	global_store_short v[20:21], v24, off
	v_add_f32_e32 v21, v22, v94
	v_mul_f32_e32 v21, 0xbfb8aa3b, v21
	v_exp_f32_e32 v21, v21
	ds_read_u16 v20, v93 offset:34384
	v_add_f32_e32 v4, v4, v92
	v_mul_f32_e32 v4, 0xbfb8aa3b, v4
	v_add_f32_e32 v21, 1.0, v21
	v_rcp_f32_e32 v21, v21
	s_waitcnt lgkmcnt(0)
	v_lshlrev_b32_e32 v20, 16, v20
	v_exp_f32_e32 v4, v4
	v_add_f32_e32 v5, v5, v92
	v_mul_f32_e32 v20, v21, v20
	v_cvt_pk_bf16_f32 v22, v20, s0
	v_lshl_add_u64 v[20:21], v[62:63], 0, v[34:35]
	global_store_short v[20:21], v22, off
	v_add_f32_e32 v21, v23, v94
	v_mul_f32_e32 v21, 0xbfb8aa3b, v21
	v_exp_f32_e32 v21, v21
	ds_read_u16 v20, v93 offset:35424
	v_add_f32_e32 v4, 1.0, v4
	v_rcp_f32_e32 v4, v4
	v_add_f32_e32 v21, 1.0, v21
	v_rcp_f32_e32 v21, v21
	s_waitcnt lgkmcnt(0)
	v_lshlrev_b32_e32 v20, 16, v20
	v_mul_f32_e32 v5, 0xbfb8aa3b, v5
	v_exp_f32_e32 v5, v5
	v_mul_f32_e32 v20, v21, v20
	v_cvt_pk_bf16_f32 v22, v20, s0
	v_lshl_add_u64 v[20:21], v[66:67], 0, v[34:35]
	global_store_short v[20:21], v22, off
	ds_read_u16 v20, v65 offset:64
	v_add_f32_e32 v5, 1.0, v5
	v_rcp_f32_e32 v5, v5
	v_add_f32_e32 v0, v0, v92
	v_mul_f32_e32 v0, 0xbfb8aa3b, v0
	s_waitcnt lgkmcnt(0)
	v_lshlrev_b32_e32 v20, 16, v20
	v_mul_f32_e32 v16, v16, v20
	v_cvt_pk_bf16_f32 v16, v16, s0
	v_lshl_add_u64 v[20:21], v[36:37], 0, v[34:35]
	global_store_short v[20:21], v16, off
	ds_read_u16 v16, v65 offset:1104
	v_exp_f32_e32 v0, v0
	v_add_f32_e32 v1, v1, v92
	v_mul_f32_e32 v1, 0xbfb8aa3b, v1
	v_exp_f32_e32 v1, v1
	s_waitcnt lgkmcnt(0)
	v_lshlrev_b32_e32 v16, 16, v16
	v_mul_f32_e32 v16, v17, v16
	v_cvt_pk_bf16_f32 v20, v16, s0
	v_lshl_add_u64 v[16:17], v[38:39], 0, v[34:35]
	global_store_short v[16:17], v20, off
	v_add_f32_e32 v17, v18, v94
	v_mul_f32_e32 v17, 0xbfb8aa3b, v17
	v_exp_f32_e32 v17, v17
	ds_read_u16 v16, v65 offset:2144
	v_add_f32_e32 v0, 1.0, v0
	v_rcp_f32_e32 v0, v0
	v_add_f32_e32 v17, 1.0, v17
	v_rcp_f32_e32 v17, v17
	s_waitcnt lgkmcnt(0)
	v_lshlrev_b32_e32 v16, 16, v16
	v_add_f32_e32 v1, 1.0, v1
	v_rcp_f32_e32 v1, v1
	v_mul_f32_e32 v16, v17, v16
	v_cvt_pk_bf16_f32 v18, v16, s0
	v_lshl_add_u64 v[16:17], v[40:41], 0, v[34:35]
	global_store_short v[16:17], v18, off
	v_add_f32_e32 v17, v19, v94
	v_mul_f32_e32 v17, 0xbfb8aa3b, v17
	v_exp_f32_e32 v17, v17
	ds_read_u16 v16, v65 offset:3184
	s_mov_b64 s[2:3], 0
	v_add_f32_e32 v17, 1.0, v17
	v_rcp_f32_e32 v17, v17
	s_waitcnt lgkmcnt(0)
	v_lshlrev_b32_e32 v16, 16, v16
	v_mul_f32_e32 v16, v17, v16
	v_cvt_pk_bf16_f32 v18, v16, s0
	v_lshl_add_u64 v[16:17], v[32:33], 0, v[34:35]
	global_store_short v[16:17], v18, off
	ds_read_u16 v18, v95 offset:96
	v_or_b32_e32 v16, 48, v64
	v_ashrrev_i32_e32 v17, 31, v16
	v_lshlrev_b64 v[16:17], 1, v[16:17]
	s_waitcnt lgkmcnt(0)
	v_lshlrev_b32_e32 v18, 16, v18
	v_mul_f32_e32 v12, v12, v18
	v_cvt_pk_bf16_f32 v12, v12, s0
	v_lshl_add_u64 v[18:19], v[48:49], 0, v[16:17]
	global_store_short v[18:19], v12, off
	ds_read_u16 v12, v93 offset:96
	s_waitcnt lgkmcnt(0)
	v_lshlrev_b32_e32 v12, 16, v12
	v_mul_f32_e32 v12, v13, v12
	v_cvt_pk_bf16_f32 v18, v12, s0
	v_lshl_add_u64 v[12:13], v[44:45], 0, v[16:17]
	global_store_short v[12:13], v18, off
	v_add_f32_e32 v13, v14, v92
	v_mul_f32_e32 v13, 0xbfb8aa3b, v13
	v_exp_f32_e32 v13, v13
	ds_read_u16 v12, v93 offset:1136
	v_add_f32_e32 v13, 1.0, v13
	v_rcp_f32_e32 v13, v13
	s_waitcnt lgkmcnt(0)
; __device__ __forceinline__ float bf2f(unsigned short h) { return __uint_as_float(((unsigned)h) << 16); }
; __device__ __forceinline__ unsigned short f2bf(float f) { return (unsigned short)(cvt_pk(f, 0.f) & 0xffffu); }
; __device__ __forceinline__ float sigmoidf_(float x) { return fast_rcp(1.f + fast_exp2(-x * LOG2E)); }
; __device__ __forceinline__ void s5_unit(ArgsP A, int l, int unit, unsigned char* lds, int wave_, int lane_) {
;     ...
;     for (int nb = 0; nb < 4; ++nb) { const int n = 64 * wave + 16 * nb + (lane & 15); const float bgl = bglv[nb];
; #pragma unroll
;         for (int mb = 0; mb < 4; ++mb)
; #pragma unroll
;             for (int i = 0; i < 4; ++i) { const int t = 16 * mb + 4 * (lane >> 4) + i; const float yv = bf2f(ys[t * YS_STRIDE + n]);
;                 MIX[(size_t)(rowbase + t) * DM + n] = f2bf(yv * sigmoidf_(acc[mb][nb][i] + bgl)); } }
;     __syncthreads();
	v_lshlrev_b32_e32 v12, 16, v12
	v_mul_f32_e32 v12, v13, v12
	v_cvt_pk_bf16_f32 v14, v12, s0
	v_lshl_add_u64 v[12:13], v[50:51], 0, v[16:17]
	global_store_short v[12:13], v14, off
	v_add_f32_e32 v13, v15, v92
	v_mul_f32_e32 v13, 0xbfb8aa3b, v13
	v_exp_f32_e32 v13, v13
	ds_read_u16 v12, v93 offset:2176
	v_add_f32_e32 v13, 1.0, v13
	v_rcp_f32_e32 v13, v13
	s_waitcnt lgkmcnt(0)
	v_lshlrev_b32_e32 v12, 16, v12
	v_mul_f32_e32 v12, v13, v12
	v_cvt_pk_bf16_f32 v14, v12, s0
	v_lshl_add_u64 v[12:13], v[46:47], 0, v[16:17]
	global_store_short v[12:13], v14, off
	ds_read_u16 v12, v93 offset:15696
	s_waitcnt lgkmcnt(0)
	v_lshlrev_b32_e32 v12, 16, v12
	v_mul_f32_e32 v8, v8, v12
	v_cvt_pk_bf16_f32 v8, v8, s0
	v_lshl_add_u64 v[12:13], v[52:53], 0, v[16:17]
	global_store_short v[12:13], v8, off
	ds_read_u16 v8, v93 offset:16736
	s_waitcnt lgkmcnt(0)
	v_lshlrev_b32_e32 v8, 16, v8
	v_mul_f32_e32 v8, v9, v8
	v_cvt_pk_bf16_f32 v12, v8, s0
	v_lshl_add_u64 v[8:9], v[54:55], 0, v[16:17]
	global_store_short v[8:9], v12, off
	v_add_f32_e32 v9, v10, v92
	v_mul_f32_e32 v9, 0xbfb8aa3b, v9
	v_exp_f32_e32 v9, v9
	ds_read_u16 v8, v93 offset:17776
	v_add_f32_e32 v9, 1.0, v9
	v_rcp_f32_e32 v9, v9
	s_waitcnt lgkmcnt(0)
	v_lshlrev_b32_e32 v8, 16, v8
	v_mul_f32_e32 v8, v9, v8
	v_cvt_pk_bf16_f32 v10, v8, s0
	v_lshl_add_u64 v[8:9], v[56:57], 0, v[16:17]
	global_store_short v[8:9], v10, off
	v_add_f32_e32 v9, v11, v92
	v_mul_f32_e32 v9, 0xbfb8aa3b, v9
	v_exp_f32_e32 v9, v9
	ds_read_u16 v8, v93 offset:18816
	v_add_f32_e32 v9, 1.0, v9
	v_rcp_f32_e32 v9, v9
	s_waitcnt lgkmcnt(0)
	v_lshlrev_b32_e32 v8, 16, v8
	v_mul_f32_e32 v8, v9, v8
	v_cvt_pk_bf16_f32 v10, v8, s0
	v_lshl_add_u64 v[8:9], v[42:43], 0, v[16:17]
	global_store_short v[8:9], v10, off
	ds_read_u16 v8, v93 offset:32336
	s_waitcnt lgkmcnt(0)
	v_lshlrev_b32_e32 v8, 16, v8
	v_mul_f32_e32 v4, v4, v8
	v_cvt_pk_bf16_f32 v4, v4, s0
	v_lshl_add_u64 v[8:9], v[58:59], 0, v[16:17]
	global_store_short v[8:9], v4, off
	ds_read_u16 v4, v93 offset:33376
	s_waitcnt lgkmcnt(0)
	v_lshlrev_b32_e32 v4, 16, v4
	v_mul_f32_e32 v4, v5, v4
	v_cvt_pk_bf16_f32 v8, v4, s0
	v_lshl_add_u64 v[4:5], v[60:61], 0, v[16:17]
	global_store_short v[4:5], v8, off
	v_add_f32_e32 v5, v6, v92
	v_mul_f32_e32 v5, 0xbfb8aa3b, v5
	v_exp_f32_e32 v5, v5
	ds_read_u16 v4, v93 offset:34416
	v_add_f32_e32 v5, 1.0, v5
	v_rcp_f32_e32 v5, v5
	s_waitcnt lgkmcnt(0)
	v_lshlrev_b32_e32 v4, 16, v4
	v_mul_f32_e32 v4, v5, v4
	v_cvt_pk_bf16_f32 v6, v4, s0
	v_lshl_add_u64 v[4:5], v[62:63], 0, v[16:17]
	global_store_short v[4:5], v6, off
	v_add_f32_e32 v5, v7, v92
	v_mul_f32_e32 v5, 0xbfb8aa3b, v5
	v_exp_f32_e32 v5, v5
	ds_read_u16 v4, v93 offset:35456
	v_add_f32_e32 v5, 1.0, v5
	v_rcp_f32_e32 v5, v5
	s_waitcnt lgkmcnt(0)
	v_lshlrev_b32_e32 v4, 16, v4
	v_mul_f32_e32 v4, v5, v4
	v_cvt_pk_bf16_f32 v6, v4, s0
	v_lshl_add_u64 v[4:5], v[66:67], 0, v[16:17]
	global_store_short v[4:5], v6, off
	ds_read_u16 v4, v65 offset:96
	s_waitcnt lgkmcnt(0)
	v_lshlrev_b32_e32 v4, 16, v4
	v_mul_f32_e32 v0, v0, v4
	v_cvt_pk_bf16_f32 v0, v0, s0
	v_lshl_add_u64 v[4:5], v[36:37], 0, v[16:17]
	global_store_short v[4:5], v0, off
	ds_read_u16 v0, v65 offset:1136
	s_waitcnt lgkmcnt(0)
	v_lshlrev_b32_e32 v0, 16, v0
	v_mul_f32_e32 v0, v1, v0
	v_cvt_pk_bf16_f32 v4, v0, s0
	v_lshl_add_u64 v[0:1], v[38:39], 0, v[16:17]
	global_store_short v[0:1], v4, off
	v_add_f32_e32 v1, v2, v92
	v_mul_f32_e32 v1, 0xbfb8aa3b, v1
	v_exp_f32_e32 v1, v1
	ds_read_u16 v0, v65 offset:2176
	v_add_f32_e32 v1, 1.0, v1
	v_rcp_f32_e32 v1, v1
	s_waitcnt lgkmcnt(0)
	v_lshlrev_b32_e32 v0, 16, v0
	v_mul_f32_e32 v0, v1, v0
	v_cvt_pk_bf16_f32 v2, v0, s0
	v_lshl_add_u64 v[0:1], v[40:41], 0, v[16:17]
	global_store_short v[0:1], v2, off
	v_add_f32_e32 v1, v3, v92
	v_mul_f32_e32 v1, 0xbfb8aa3b, v1
	v_exp_f32_e32 v1, v1
	ds_read_u16 v0, v65 offset:3216
	v_add_f32_e32 v1, 1.0, v1
	v_rcp_f32_e32 v1, v1
	s_waitcnt lgkmcnt(0)
	v_lshlrev_b32_e32 v0, 16, v0
	v_mul_f32_e32 v0, v1, v0
	v_cvt_pk_bf16_f32 v2, v0, s0
	v_lshl_add_u64 v[0:1], v[32:33], 0, v[16:17]
	global_store_short v[0:1], v2, off
	s_waitcnt vmcnt(63) expcnt(7) lgkmcnt(15)
	s_barrier
	s_branch .LBB0_785
